# k-loops unrolled by two with two LDS read-address sets (no per-k-tile address XORs)
# speedup vs baseline: 1.0144x; 1.0105x over previous
.LBB0_114:
	v_mov_b32_e32 v6, v181
	s_ashr_i32 s93, s92, 6
	v_lshrrev_b32_e32 v7, 4, v6
	v_lshlrev_b32_e32 v1, 6, v6
	v_xor_b32_e32 v0, v7, v6
	v_and_b32_e32 v8, 0x3c0, v1
	v_lshlrev_b32_e32 v1, 7, v6
	s_bfe_u32 s94, s92, 0x20006
	s_and_b32 s86, s91, 63
	s_and_b32 s95, s92, 63
	s_and_b32 s21, s93, -4
	v_lshlrev_b32_e32 v0, 3, v0
	v_and_b32_e32 v1, 0xfffffc00, v1
	s_lshl_b32 s20, s86, 19
	s_or_b32 s58, s21, s94
	s_lshl_b32 s21, s95, 19
	v_and_or_b32 v0, v0, 56, v1
	s_waitcnt lgkmcnt(0)
	s_add_u32 s60, s3, s21
	v_ashrrev_i32_e32 v1, 31, v0
	v_lshl_add_u32 v129, v6, 4, 0
	s_addc_u32 s61, s90, 0
	v_lshlrev_b64 v[0:1], 1, v[0:1]
	v_readfirstlane_b32 s21, v129
	v_add_u32_e32 v9, 0x2000, v129
	v_lshl_add_u64 v[2:3], s[60:61], 0, v[0:1]
	s_mov_b32 m0, s21
	v_readfirstlane_b32 s21, v9
	v_add_u32_e32 v9, 0x4000, v129
	s_barrier
	global_load_lds_dwordx4 v[2:3], off
	v_lshl_add_u64 v[4:5], v[2:3], 0, s[10:11]
	s_mov_b32 m0, s21
	v_readfirstlane_b32 s21, v9
	global_load_lds_dwordx4 v[4:5], off
	v_lshl_add_u64 v[4:5], v[2:3], 0, s[12:13]
	s_mov_b32 m0, s21
	s_ashr_i32 s59, s58, 31
	global_load_lds_dwordx4 v[4:5], off
	v_add_u32_e32 v4, 0x6000, v129
	s_lshl_b64 s[88:89], s[58:59], 19
	v_readfirstlane_b32 s21, v4
	v_lshl_add_u64 v[2:3], v[2:3], 0, s[14:15]
	s_mov_b32 m0, s21
	s_add_u32 s88, s34, s88
	global_load_lds_dwordx4 v[2:3], off
	v_add_u32_e32 v2, 0x8000, v129
	s_addc_u32 s89, s35, s89
	v_readfirstlane_b32 s21, v2
	v_add_u32_e32 v4, 0xa000, v129
	v_lshl_add_u64 v[134:135], s[88:89], 0, v[0:1]
	s_mov_b32 m0, s21
	v_readfirstlane_b32 s21, v4
	v_add_u32_e32 v4, 0xc000, v129
	global_load_lds_dwordx4 v[134:135], off
	v_lshl_add_u64 v[2:3], v[134:135], 0, s[10:11]
	s_mov_b32 m0, s21
	v_readfirstlane_b32 s21, v4
	v_add_u32_e32 v4, 0xe000, v129
	global_load_lds_dwordx4 v[2:3], off
	v_lshl_add_u64 v[2:3], v[134:135], 0, s[12:13]
	s_mov_b32 m0, s21
	v_readfirstlane_b32 s21, v4
	global_load_lds_dwordx4 v[2:3], off
	v_lshl_add_u64 v[2:3], v[134:135], 0, s[14:15]
	s_mov_b32 m0, s21
	v_ashrrev_i32_e32 v4, 6, v6
	global_load_lds_dwordx4 v[2:3], off
	v_lshrrev_b32_e32 v5, 30, v4
	v_add_u32_e32 v5, v4, v5
	v_bfe_u32 v2, v6, 4, 2
	v_bfe_u32 v3, v6, 1, 3
	v_and_b32_e32 v6, 0x7fffc, v5
	v_sub_u32_e32 v4, v4, v6
	v_lshlrev_b32_e32 v139, 13, v4
	v_bitop3_b32 v4, v7, v3, 3 bitop3:0x6c
	v_bitop3_b32 v2, v2, v3, 4 bitop3:0x36
	s_add_u32 s60, s34, s20
	v_lshlrev_b32_e32 v5, 12, v5
	v_lshlrev_b32_e32 v4, 3, v4
	v_lshlrev_b32_e32 v2, 3, v2
	s_addc_u32 s61, s35, 0
	v_and_b32_e32 v138, 0xffffc000, v5
	v_lshl_add_u64 v[136:137], s[60:61], 0, v[0:1]
	s_mov_b64 s[60:61], 0
	v_lshlrev_b32_e32 v140, 1, v8
	v_lshlrev_b32_e32 v141, 1, v4
	v_lshlrev_b32_e32 v142, 1, v2
	s_mov_b32 s87, 0
	s_mov_b32 s59, 0
	v_mov_b32_e32 v8, v128
	v_mov_b32_e32 v9, v128
	v_mov_b32_e32 v10, v128
	v_mov_b32_e32 v11, v128
	v_mov_b32_e32 v20, v128
	v_mov_b32_e32 v21, v128
	v_mov_b32_e32 v22, v128
	v_mov_b32_e32 v23, v128
	v_mov_b32_e32 v0, v128
	v_mov_b32_e32 v1, v128
	v_mov_b32_e32 v2, v128
	v_mov_b32_e32 v3, v128
	v_mov_b32_e32 v4, v128
	v_mov_b32_e32 v5, v128
	v_mov_b32_e32 v6, v128
	v_mov_b32_e32 v7, v128
	v_mov_b32_e32 v12, v128
	v_mov_b32_e32 v13, v128
	v_mov_b32_e32 v14, v128
	v_mov_b32_e32 v15, v128
	v_mov_b32_e32 v24, v128
	v_mov_b32_e32 v25, v128
	v_mov_b32_e32 v26, v128
	v_mov_b32_e32 v27, v128
	v_mov_b32_e32 v16, v128
	v_mov_b32_e32 v17, v128
	v_mov_b32_e32 v18, v128
	v_mov_b32_e32 v19, v128
	v_mov_b32_e32 v28, v128
	v_mov_b32_e32 v29, v128
	v_mov_b32_e32 v30, v128
	v_mov_b32_e32 v31, v128
	v_mov_b32_e32 v32, v128
	v_mov_b32_e32 v33, v128
	v_mov_b32_e32 v34, v128
	v_mov_b32_e32 v35, v128
	v_mov_b32_e32 v40, v128
	v_mov_b32_e32 v41, v128
	v_mov_b32_e32 v42, v128
	v_mov_b32_e32 v43, v128
	v_mov_b32_e32 v36, v128
	v_mov_b32_e32 v37, v128
	v_mov_b32_e32 v38, v128
	v_mov_b32_e32 v39, v128
	v_mov_b32_e32 v44, v128
	v_mov_b32_e32 v45, v128
	v_mov_b32_e32 v46, v128
	v_mov_b32_e32 v47, v128
	v_mov_b32_e32 v48, v128
	v_mov_b32_e32 v49, v128
	v_mov_b32_e32 v50, v128
	v_mov_b32_e32 v51, v128
	v_mov_b32_e32 v56, v128
	v_mov_b32_e32 v57, v128
	v_mov_b32_e32 v58, v128
	v_mov_b32_e32 v59, v128
	v_mov_b32_e32 v52, v128
	v_mov_b32_e32 v53, v128
	v_mov_b32_e32 v54, v128
	v_mov_b32_e32 v55, v128
	v_mov_b32_e32 v60, v128
	v_mov_b32_e32 v61, v128
	v_mov_b32_e32 v62, v128
	v_mov_b32_e32 v63, v128
	v_mov_b32_e32 v64, v128
	v_mov_b32_e32 v65, v128
	v_mov_b32_e32 v66, v128
	v_mov_b32_e32 v67, v128
	v_mov_b32_e32 v72, v128
	v_mov_b32_e32 v73, v128
	v_mov_b32_e32 v74, v128
	v_mov_b32_e32 v75, v128
	v_mov_b32_e32 v68, v128
	v_mov_b32_e32 v69, v128
	v_mov_b32_e32 v70, v128
	v_mov_b32_e32 v71, v128
	v_mov_b32_e32 v76, v128
	v_mov_b32_e32 v77, v128
	v_mov_b32_e32 v78, v128
	v_mov_b32_e32 v79, v128
	v_mov_b32_e32 v80, v128
	v_mov_b32_e32 v81, v128
	v_mov_b32_e32 v82, v128
	v_mov_b32_e32 v83, v128
	v_mov_b32_e32 v88, v128
	v_mov_b32_e32 v89, v128
	v_mov_b32_e32 v90, v128
	v_mov_b32_e32 v91, v128
	v_mov_b32_e32 v84, v128
	v_mov_b32_e32 v85, v128
	v_mov_b32_e32 v86, v128
	v_mov_b32_e32 v87, v128
	v_mov_b32_e32 v92, v128
	v_mov_b32_e32 v93, v128
	v_mov_b32_e32 v94, v128
	v_mov_b32_e32 v95, v128
	v_mov_b32_e32 v96, v128
	v_mov_b32_e32 v97, v128
	v_mov_b32_e32 v98, v128
	v_mov_b32_e32 v99, v128
	v_mov_b32_e32 v104, v128
	v_mov_b32_e32 v105, v128
	v_mov_b32_e32 v106, v128
	v_mov_b32_e32 v107, v128
	v_mov_b32_e32 v100, v128
	v_mov_b32_e32 v101, v128
	v_mov_b32_e32 v102, v128
	v_mov_b32_e32 v103, v128
	v_mov_b32_e32 v108, v128
	v_mov_b32_e32 v109, v128
	v_mov_b32_e32 v110, v128
	v_mov_b32_e32 v111, v128
	v_mov_b32_e32 v112, v128
	v_mov_b32_e32 v113, v128
	v_mov_b32_e32 v114, v128
	v_mov_b32_e32 v115, v128
	v_mov_b32_e32 v120, v128
	v_mov_b32_e32 v121, v128
	v_mov_b32_e32 v122, v128
	v_mov_b32_e32 v123, v128
	v_mov_b32_e32 v116, v128
	v_mov_b32_e32 v117, v128
	v_mov_b32_e32 v118, v128
	v_mov_b32_e32 v119, v128
	v_mov_b32_e32 v124, v128
	v_mov_b32_e32 v125, v128
	v_mov_b32_e32 v126, v128
	v_mov_b32_e32 v127, v128
	s_waitcnt vmcnt(0) lgkmcnt(0)
	s_barrier
	v_add3_u32 v143, v138, v140, v141
	v_add3_u32 v180, v139, v140, v141
	v_add3_u32 v155, v138, v140, v142
	v_add3_u32 v222, v139, v140, v142
	v_xor_b32_e32 v223, 0x10000, v143
	v_xor_b32_e32 v224, 0x10000, v155
	v_xor_b32_e32 v225, 0x10000, v180
	v_xor_b32_e32 v226, 0x10000, v222
	v_readfirstlane_b32 s87, v129
	ds_read_b128 v[156:159], v143
	ds_read_b128 v[160:163], v143 offset:2048
	ds_read_b128 v[164:167], v143 offset:4096
	ds_read_b128 v[168:171], v143 offset:6144
	ds_read_b128 v[190:193], v180 offset:32768
	ds_read_b128 v[194:197], v180 offset:34816
	ds_read_b128 v[198:201], v180 offset:36864
	ds_read_b128 v[202:205], v180 offset:38912
	s_mov_b32 s59, 0
	s_mov_b64 s[60:61], s[34:35]
	v_subrev_u32_e32 v144, s34, v136
	v_subrev_u32_e32 v145, s34, v134
	s_add_u32 s87, s87, 0x10000
	s_mov_b32 m0, s87
	s_add_u32 s88, s60, s16
	s_addc_u32 s89, s61, s17
	global_load_lds_dwordx4 v144, s[88:89]
	s_add_u32 m0, s87, 0x2000
	s_add_u32 s88, s60, s18
	s_addc_u32 s89, s61, s19
	global_load_lds_dwordx4 v144, s[88:89]
	s_add_u32 m0, s87, 0x4000
	s_add_u32 s88, s60, s22
	s_addc_u32 s89, s61, s23
	global_load_lds_dwordx4 v144, s[88:89]
	s_add_u32 m0, s87, 0x6000
	s_add_u32 s88, s60, s40
	s_addc_u32 s89, s61, s41
	global_load_lds_dwordx4 v144, s[88:89]
	s_add_u32 m0, s87, 0x8000
	s_add_u32 s88, s60, s42
	s_addc_u32 s89, s61, s43
	global_load_lds_dwordx4 v145, s[88:89]
	s_add_u32 m0, s87, 0xa000
	s_add_u32 s88, s60, s52
	s_addc_u32 s89, s61, s53
	global_load_lds_dwordx4 v145, s[88:89]
	s_add_u32 m0, s87, 0xc000
	s_add_u32 s88, s60, s54
	s_addc_u32 s89, s61, s55
	global_load_lds_dwordx4 v145, s[88:89]
	s_add_u32 m0, s87, 0xe000
	s_add_u32 s88, s60, s56
	s_addc_u32 s89, s61, s57
	global_load_lds_dwordx4 v145, s[88:89]
	s_branch .Lg0_entry
.Lg0_top:
	s_waitcnt lgkmcnt(0)
	s_waitcnt vmcnt(0)
	s_barrier
	s_xor_b32 s87, s87, 0x10000
	ds_read_b128 v[156:159], v143
	ds_read_b128 v[160:163], v143 offset:2048
	ds_read_b128 v[164:167], v143 offset:4096
	ds_read_b128 v[168:171], v143 offset:6144
	ds_read_b128 v[190:193], v180 offset:32768
	ds_read_b128 v[194:197], v180 offset:34816
	ds_read_b128 v[198:201], v180 offset:36864
	ds_read_b128 v[202:205], v180 offset:38912
	v_mfma_f32_16x16x32_bf16 v[60:63], v[172:175], v[206:209], v[60:63]
	v_mfma_f32_16x16x32_bf16 v[52:55], v[172:175], v[210:213], v[52:55]
	s_mov_b32 m0, s87
	s_add_u32 s88, s60, s16
	s_addc_u32 s89, s61, s17
	global_load_lds_dwordx4 v144, s[88:89]
	v_mfma_f32_16x16x32_bf16 v[56:59], v[172:175], v[214:217], v[56:59]
	v_mfma_f32_16x16x32_bf16 v[48:51], v[172:175], v[218:221], v[48:51]
	s_add_u32 m0, s87, 0x2000
	s_add_u32 s88, s60, s18
	s_addc_u32 s89, s61, s19
	global_load_lds_dwordx4 v144, s[88:89]
	v_mfma_f32_16x16x32_bf16 v[44:47], v[176:179], v[206:209], v[44:47]
	v_mfma_f32_16x16x32_bf16 v[36:39], v[176:179], v[210:213], v[36:39]
	s_add_u32 m0, s87, 0x4000
	s_add_u32 s88, s60, s22
	s_addc_u32 s89, s61, s23
	global_load_lds_dwordx4 v144, s[88:89]
	v_mfma_f32_16x16x32_bf16 v[40:43], v[176:179], v[214:217], v[40:43]
	v_mfma_f32_16x16x32_bf16 v[32:35], v[176:179], v[218:221], v[32:35]
	s_add_u32 m0, s87, 0x6000
	s_add_u32 s88, s60, s40
	s_addc_u32 s89, s61, s41
	global_load_lds_dwordx4 v144, s[88:89]
	v_mfma_f32_16x16x32_bf16 v[28:31], v[182:185], v[206:209], v[28:31]
	v_mfma_f32_16x16x32_bf16 v[16:19], v[182:185], v[210:213], v[16:19]
	s_add_u32 m0, s87, 0x8000
	s_add_u32 s88, s60, s42
	s_addc_u32 s89, s61, s43
	global_load_lds_dwordx4 v145, s[88:89]
	v_mfma_f32_16x16x32_bf16 v[24:27], v[182:185], v[214:217], v[24:27]
	v_mfma_f32_16x16x32_bf16 v[12:15], v[182:185], v[218:221], v[12:15]
	s_add_u32 m0, s87, 0xa000
	s_add_u32 s88, s60, s52
	s_addc_u32 s89, s61, s53
	global_load_lds_dwordx4 v145, s[88:89]
	v_mfma_f32_16x16x32_bf16 v[4:7], v[186:189], v[206:209], v[4:7]
	v_mfma_f32_16x16x32_bf16 v[0:3], v[186:189], v[210:213], v[0:3]
	s_add_u32 m0, s87, 0xc000
	s_add_u32 s88, s60, s54
	s_addc_u32 s89, s61, s55
	global_load_lds_dwordx4 v145, s[88:89]
	v_mfma_f32_16x16x32_bf16 v[20:23], v[186:189], v[214:217], v[20:23]
	v_mfma_f32_16x16x32_bf16 v[8:11], v[186:189], v[218:221], v[8:11]
	s_add_u32 m0, s87, 0xe000
	s_add_u32 s88, s60, s56
	s_addc_u32 s89, s61, s57
	global_load_lds_dwordx4 v145, s[88:89]
.Lg0_entry:
	ds_read_b128 v[172:175], v143 offset:8192
	ds_read_b128 v[176:179], v143 offset:10240
	ds_read_b128 v[182:185], v143 offset:12288
	ds_read_b128 v[186:189], v143 offset:14336
	s_waitcnt lgkmcnt(4)
	v_mfma_f32_16x16x32_bf16 v[124:127], v[156:159], v[190:193], v[124:127]
	v_mfma_f32_16x16x32_bf16 v[116:119], v[156:159], v[194:197], v[116:119]
	v_mfma_f32_16x16x32_bf16 v[120:123], v[156:159], v[198:201], v[120:123]
	v_mfma_f32_16x16x32_bf16 v[112:115], v[156:159], v[202:205], v[112:115]
	v_mfma_f32_16x16x32_bf16 v[108:111], v[160:163], v[190:193], v[108:111]
	v_mfma_f32_16x16x32_bf16 v[100:103], v[160:163], v[194:197], v[100:103]
	v_mfma_f32_16x16x32_bf16 v[104:107], v[160:163], v[198:201], v[104:107]
	v_mfma_f32_16x16x32_bf16 v[96:99], v[160:163], v[202:205], v[96:99]
	v_mfma_f32_16x16x32_bf16 v[92:95], v[164:167], v[190:193], v[92:95]
	v_mfma_f32_16x16x32_bf16 v[84:87], v[164:167], v[194:197], v[84:87]
	v_mfma_f32_16x16x32_bf16 v[88:91], v[164:167], v[198:201], v[88:91]
	v_mfma_f32_16x16x32_bf16 v[80:83], v[164:167], v[202:205], v[80:83]
	v_mfma_f32_16x16x32_bf16 v[76:79], v[168:171], v[190:193], v[76:79]
	v_mfma_f32_16x16x32_bf16 v[68:71], v[168:171], v[194:197], v[68:71]
	v_mfma_f32_16x16x32_bf16 v[72:75], v[168:171], v[198:201], v[72:75]
	v_mfma_f32_16x16x32_bf16 v[64:67], v[168:171], v[202:205], v[64:67]
	ds_read_b128 v[156:159], v155
	ds_read_b128 v[160:163], v155 offset:2048
	ds_read_b128 v[164:167], v155 offset:4096
	ds_read_b128 v[168:171], v155 offset:6144
	ds_read_b128 v[206:209], v222 offset:32768
	ds_read_b128 v[210:213], v222 offset:34816
	ds_read_b128 v[214:217], v222 offset:36864
	ds_read_b128 v[218:221], v222 offset:38912
	s_waitcnt lgkmcnt(8)
	v_mfma_f32_16x16x32_bf16 v[60:63], v[172:175], v[190:193], v[60:63]
	v_mfma_f32_16x16x32_bf16 v[52:55], v[172:175], v[194:197], v[52:55]
	v_mfma_f32_16x16x32_bf16 v[56:59], v[172:175], v[198:201], v[56:59]
	v_mfma_f32_16x16x32_bf16 v[48:51], v[172:175], v[202:205], v[48:51]
	v_mfma_f32_16x16x32_bf16 v[44:47], v[176:179], v[190:193], v[44:47]
	v_mfma_f32_16x16x32_bf16 v[36:39], v[176:179], v[194:197], v[36:39]
	v_mfma_f32_16x16x32_bf16 v[40:43], v[176:179], v[198:201], v[40:43]
	v_mfma_f32_16x16x32_bf16 v[32:35], v[176:179], v[202:205], v[32:35]
	v_mfma_f32_16x16x32_bf16 v[28:31], v[182:185], v[190:193], v[28:31]
	v_mfma_f32_16x16x32_bf16 v[16:19], v[182:185], v[194:197], v[16:19]
	v_mfma_f32_16x16x32_bf16 v[24:27], v[182:185], v[198:201], v[24:27]
	v_mfma_f32_16x16x32_bf16 v[12:15], v[182:185], v[202:205], v[12:15]
	v_mfma_f32_16x16x32_bf16 v[4:7], v[186:189], v[190:193], v[4:7]
	v_mfma_f32_16x16x32_bf16 v[0:3], v[186:189], v[194:197], v[0:3]
	v_mfma_f32_16x16x32_bf16 v[20:23], v[186:189], v[198:201], v[20:23]
	v_mfma_f32_16x16x32_bf16 v[8:11], v[186:189], v[202:205], v[8:11]
	ds_read_b128 v[172:175], v155 offset:8192
	ds_read_b128 v[176:179], v155 offset:10240
	ds_read_b128 v[182:185], v155 offset:12288
	ds_read_b128 v[186:189], v155 offset:14336
	s_waitcnt lgkmcnt(4)
	v_mfma_f32_16x16x32_bf16 v[124:127], v[156:159], v[206:209], v[124:127]
	v_mfma_f32_16x16x32_bf16 v[116:119], v[156:159], v[210:213], v[116:119]
	v_mfma_f32_16x16x32_bf16 v[120:123], v[156:159], v[214:217], v[120:123]
	v_mfma_f32_16x16x32_bf16 v[112:115], v[156:159], v[218:221], v[112:115]
	v_mfma_f32_16x16x32_bf16 v[108:111], v[160:163], v[206:209], v[108:111]
	v_mfma_f32_16x16x32_bf16 v[100:103], v[160:163], v[210:213], v[100:103]
	v_mfma_f32_16x16x32_bf16 v[104:107], v[160:163], v[214:217], v[104:107]
	v_mfma_f32_16x16x32_bf16 v[96:99], v[160:163], v[218:221], v[96:99]
	v_mfma_f32_16x16x32_bf16 v[92:95], v[164:167], v[206:209], v[92:95]
	v_mfma_f32_16x16x32_bf16 v[84:87], v[164:167], v[210:213], v[84:87]
	v_mfma_f32_16x16x32_bf16 v[88:91], v[164:167], v[214:217], v[88:91]
	v_mfma_f32_16x16x32_bf16 v[80:83], v[164:167], v[218:221], v[80:83]
	v_mfma_f32_16x16x32_bf16 v[76:79], v[168:171], v[206:209], v[76:79]
	v_mfma_f32_16x16x32_bf16 v[68:71], v[168:171], v[210:213], v[68:71]
	v_mfma_f32_16x16x32_bf16 v[72:75], v[168:171], v[214:217], v[72:75]
	v_mfma_f32_16x16x32_bf16 v[64:67], v[168:171], v[218:221], v[64:67]
	s_add_u32 s60, s60, 0x80
	s_addc_u32 s61, s61, 0
	s_add_i32 s59, s59, 1
	s_cmp_lt_u32 s59, 15
	s_cbranch_scc0 .Lg0_last
	s_waitcnt lgkmcnt(0)
	s_waitcnt vmcnt(0)
	s_barrier
	s_xor_b32 s87, s87, 0x10000
	ds_read_b128 v[156:159], v223
	ds_read_b128 v[160:163], v223 offset:2048
	ds_read_b128 v[164:167], v223 offset:4096
	ds_read_b128 v[168:171], v223 offset:6144
	ds_read_b128 v[190:193], v225 offset:32768
	ds_read_b128 v[194:197], v225 offset:34816
	ds_read_b128 v[198:201], v225 offset:36864
	ds_read_b128 v[202:205], v225 offset:38912
	v_mfma_f32_16x16x32_bf16 v[60:63], v[172:175], v[206:209], v[60:63]
	v_mfma_f32_16x16x32_bf16 v[52:55], v[172:175], v[210:213], v[52:55]
	s_mov_b32 m0, s87
	s_add_u32 s88, s60, s16
	s_addc_u32 s89, s61, s17
	global_load_lds_dwordx4 v144, s[88:89]
	v_mfma_f32_16x16x32_bf16 v[56:59], v[172:175], v[214:217], v[56:59]
	v_mfma_f32_16x16x32_bf16 v[48:51], v[172:175], v[218:221], v[48:51]
	s_add_u32 m0, s87, 0x2000
	s_add_u32 s88, s60, s18
	s_addc_u32 s89, s61, s19
	global_load_lds_dwordx4 v144, s[88:89]
	v_mfma_f32_16x16x32_bf16 v[44:47], v[176:179], v[206:209], v[44:47]
	v_mfma_f32_16x16x32_bf16 v[36:39], v[176:179], v[210:213], v[36:39]
	s_add_u32 m0, s87, 0x4000
	s_add_u32 s88, s60, s22
	s_addc_u32 s89, s61, s23
	global_load_lds_dwordx4 v144, s[88:89]
	v_mfma_f32_16x16x32_bf16 v[40:43], v[176:179], v[214:217], v[40:43]
	v_mfma_f32_16x16x32_bf16 v[32:35], v[176:179], v[218:221], v[32:35]
	s_add_u32 m0, s87, 0x6000
	s_add_u32 s88, s60, s40
	s_addc_u32 s89, s61, s41
	global_load_lds_dwordx4 v144, s[88:89]
	v_mfma_f32_16x16x32_bf16 v[28:31], v[182:185], v[206:209], v[28:31]
	v_mfma_f32_16x16x32_bf16 v[16:19], v[182:185], v[210:213], v[16:19]
	s_add_u32 m0, s87, 0x8000
	s_add_u32 s88, s60, s42
	s_addc_u32 s89, s61, s43
	global_load_lds_dwordx4 v145, s[88:89]
	v_mfma_f32_16x16x32_bf16 v[24:27], v[182:185], v[214:217], v[24:27]
	v_mfma_f32_16x16x32_bf16 v[12:15], v[182:185], v[218:221], v[12:15]
	s_add_u32 m0, s87, 0xa000
	s_add_u32 s88, s60, s52
	s_addc_u32 s89, s61, s53
	global_load_lds_dwordx4 v145, s[88:89]
	v_mfma_f32_16x16x32_bf16 v[4:7], v[186:189], v[206:209], v[4:7]
	v_mfma_f32_16x16x32_bf16 v[0:3], v[186:189], v[210:213], v[0:3]
	s_add_u32 m0, s87, 0xc000
	s_add_u32 s88, s60, s54
	s_addc_u32 s89, s61, s55
	global_load_lds_dwordx4 v145, s[88:89]
	v_mfma_f32_16x16x32_bf16 v[20:23], v[186:189], v[214:217], v[20:23]
	v_mfma_f32_16x16x32_bf16 v[8:11], v[186:189], v[218:221], v[8:11]
	s_add_u32 m0, s87, 0xe000
	s_add_u32 s88, s60, s56
	s_addc_u32 s89, s61, s57
	global_load_lds_dwordx4 v145, s[88:89]
	ds_read_b128 v[172:175], v223 offset:8192
	ds_read_b128 v[176:179], v223 offset:10240
	ds_read_b128 v[182:185], v223 offset:12288
	ds_read_b128 v[186:189], v223 offset:14336
	s_waitcnt lgkmcnt(4)
	v_mfma_f32_16x16x32_bf16 v[124:127], v[156:159], v[190:193], v[124:127]
	v_mfma_f32_16x16x32_bf16 v[116:119], v[156:159], v[194:197], v[116:119]
	v_mfma_f32_16x16x32_bf16 v[120:123], v[156:159], v[198:201], v[120:123]
	v_mfma_f32_16x16x32_bf16 v[112:115], v[156:159], v[202:205], v[112:115]
	v_mfma_f32_16x16x32_bf16 v[108:111], v[160:163], v[190:193], v[108:111]
	v_mfma_f32_16x16x32_bf16 v[100:103], v[160:163], v[194:197], v[100:103]
	v_mfma_f32_16x16x32_bf16 v[104:107], v[160:163], v[198:201], v[104:107]
	v_mfma_f32_16x16x32_bf16 v[96:99], v[160:163], v[202:205], v[96:99]
	v_mfma_f32_16x16x32_bf16 v[92:95], v[164:167], v[190:193], v[92:95]
	v_mfma_f32_16x16x32_bf16 v[84:87], v[164:167], v[194:197], v[84:87]
	v_mfma_f32_16x16x32_bf16 v[88:91], v[164:167], v[198:201], v[88:91]
	v_mfma_f32_16x16x32_bf16 v[80:83], v[164:167], v[202:205], v[80:83]
	v_mfma_f32_16x16x32_bf16 v[76:79], v[168:171], v[190:193], v[76:79]
	v_mfma_f32_16x16x32_bf16 v[68:71], v[168:171], v[194:197], v[68:71]
	v_mfma_f32_16x16x32_bf16 v[72:75], v[168:171], v[198:201], v[72:75]
	v_mfma_f32_16x16x32_bf16 v[64:67], v[168:171], v[202:205], v[64:67]
	ds_read_b128 v[156:159], v224
	ds_read_b128 v[160:163], v224 offset:2048
	ds_read_b128 v[164:167], v224 offset:4096
	ds_read_b128 v[168:171], v224 offset:6144
	ds_read_b128 v[206:209], v226 offset:32768
	ds_read_b128 v[210:213], v226 offset:34816
	ds_read_b128 v[214:217], v226 offset:36864
	ds_read_b128 v[218:221], v226 offset:38912
	s_waitcnt lgkmcnt(8)
	v_mfma_f32_16x16x32_bf16 v[60:63], v[172:175], v[190:193], v[60:63]
	v_mfma_f32_16x16x32_bf16 v[52:55], v[172:175], v[194:197], v[52:55]
	v_mfma_f32_16x16x32_bf16 v[56:59], v[172:175], v[198:201], v[56:59]
	v_mfma_f32_16x16x32_bf16 v[48:51], v[172:175], v[202:205], v[48:51]
	v_mfma_f32_16x16x32_bf16 v[44:47], v[176:179], v[190:193], v[44:47]
	v_mfma_f32_16x16x32_bf16 v[36:39], v[176:179], v[194:197], v[36:39]
	v_mfma_f32_16x16x32_bf16 v[40:43], v[176:179], v[198:201], v[40:43]
	v_mfma_f32_16x16x32_bf16 v[32:35], v[176:179], v[202:205], v[32:35]
	v_mfma_f32_16x16x32_bf16 v[28:31], v[182:185], v[190:193], v[28:31]
	v_mfma_f32_16x16x32_bf16 v[16:19], v[182:185], v[194:197], v[16:19]
	v_mfma_f32_16x16x32_bf16 v[24:27], v[182:185], v[198:201], v[24:27]
	v_mfma_f32_16x16x32_bf16 v[12:15], v[182:185], v[202:205], v[12:15]
	v_mfma_f32_16x16x32_bf16 v[4:7], v[186:189], v[190:193], v[4:7]
	v_mfma_f32_16x16x32_bf16 v[0:3], v[186:189], v[194:197], v[0:3]
	v_mfma_f32_16x16x32_bf16 v[20:23], v[186:189], v[198:201], v[20:23]
	v_mfma_f32_16x16x32_bf16 v[8:11], v[186:189], v[202:205], v[8:11]
	ds_read_b128 v[172:175], v224 offset:8192
	ds_read_b128 v[176:179], v224 offset:10240
	ds_read_b128 v[182:185], v224 offset:12288
	ds_read_b128 v[186:189], v224 offset:14336
	s_waitcnt lgkmcnt(4)
	v_mfma_f32_16x16x32_bf16 v[124:127], v[156:159], v[206:209], v[124:127]
	v_mfma_f32_16x16x32_bf16 v[116:119], v[156:159], v[210:213], v[116:119]
	v_mfma_f32_16x16x32_bf16 v[120:123], v[156:159], v[214:217], v[120:123]
	v_mfma_f32_16x16x32_bf16 v[112:115], v[156:159], v[218:221], v[112:115]
	v_mfma_f32_16x16x32_bf16 v[108:111], v[160:163], v[206:209], v[108:111]
	v_mfma_f32_16x16x32_bf16 v[100:103], v[160:163], v[210:213], v[100:103]
	v_mfma_f32_16x16x32_bf16 v[104:107], v[160:163], v[214:217], v[104:107]
	v_mfma_f32_16x16x32_bf16 v[96:99], v[160:163], v[218:221], v[96:99]
	v_mfma_f32_16x16x32_bf16 v[92:95], v[164:167], v[206:209], v[92:95]
	v_mfma_f32_16x16x32_bf16 v[84:87], v[164:167], v[210:213], v[84:87]
	v_mfma_f32_16x16x32_bf16 v[88:91], v[164:167], v[214:217], v[88:91]
	v_mfma_f32_16x16x32_bf16 v[80:83], v[164:167], v[218:221], v[80:83]
	v_mfma_f32_16x16x32_bf16 v[76:79], v[168:171], v[206:209], v[76:79]
	v_mfma_f32_16x16x32_bf16 v[68:71], v[168:171], v[210:213], v[68:71]
	v_mfma_f32_16x16x32_bf16 v[72:75], v[168:171], v[214:217], v[72:75]
	v_mfma_f32_16x16x32_bf16 v[64:67], v[168:171], v[218:221], v[64:67]
	s_add_u32 s60, s60, 0x80
	s_addc_u32 s61, s61, 0
	s_add_i32 s59, s59, 1
	s_branch .Lg0_top
.Lg0_last:
	s_waitcnt lgkmcnt(0)
	s_waitcnt vmcnt(0)
	s_barrier
	s_xor_b32 s87, s87, 0x10000
	ds_read_b128 v[156:159], v223
	ds_read_b128 v[160:163], v223 offset:2048
	ds_read_b128 v[164:167], v223 offset:4096
	ds_read_b128 v[168:171], v223 offset:6144
	ds_read_b128 v[190:193], v225 offset:32768
	ds_read_b128 v[194:197], v225 offset:34816
	ds_read_b128 v[198:201], v225 offset:36864
	ds_read_b128 v[202:205], v225 offset:38912
	v_mfma_f32_16x16x32_bf16 v[60:63], v[172:175], v[206:209], v[60:63]
	v_mfma_f32_16x16x32_bf16 v[52:55], v[172:175], v[210:213], v[52:55]
	v_mfma_f32_16x16x32_bf16 v[56:59], v[172:175], v[214:217], v[56:59]
	v_mfma_f32_16x16x32_bf16 v[48:51], v[172:175], v[218:221], v[48:51]
	v_mfma_f32_16x16x32_bf16 v[44:47], v[176:179], v[206:209], v[44:47]
	v_mfma_f32_16x16x32_bf16 v[36:39], v[176:179], v[210:213], v[36:39]
	v_mfma_f32_16x16x32_bf16 v[40:43], v[176:179], v[214:217], v[40:43]
	v_mfma_f32_16x16x32_bf16 v[32:35], v[176:179], v[218:221], v[32:35]
	v_mfma_f32_16x16x32_bf16 v[28:31], v[182:185], v[206:209], v[28:31]
	v_mfma_f32_16x16x32_bf16 v[16:19], v[182:185], v[210:213], v[16:19]
	v_mfma_f32_16x16x32_bf16 v[24:27], v[182:185], v[214:217], v[24:27]
	v_mfma_f32_16x16x32_bf16 v[12:15], v[182:185], v[218:221], v[12:15]
	v_mfma_f32_16x16x32_bf16 v[4:7], v[186:189], v[206:209], v[4:7]
	v_mfma_f32_16x16x32_bf16 v[0:3], v[186:189], v[210:213], v[0:3]
	v_mfma_f32_16x16x32_bf16 v[20:23], v[186:189], v[214:217], v[20:23]
	v_mfma_f32_16x16x32_bf16 v[8:11], v[186:189], v[218:221], v[8:11]
	ds_read_b128 v[172:175], v223 offset:8192
	ds_read_b128 v[176:179], v223 offset:10240
	ds_read_b128 v[182:185], v223 offset:12288
	ds_read_b128 v[186:189], v223 offset:14336
	s_waitcnt lgkmcnt(4)
	v_mfma_f32_16x16x32_bf16 v[124:127], v[156:159], v[190:193], v[124:127]
	v_mfma_f32_16x16x32_bf16 v[116:119], v[156:159], v[194:197], v[116:119]
	v_mfma_f32_16x16x32_bf16 v[120:123], v[156:159], v[198:201], v[120:123]
	v_mfma_f32_16x16x32_bf16 v[112:115], v[156:159], v[202:205], v[112:115]
	v_mfma_f32_16x16x32_bf16 v[108:111], v[160:163], v[190:193], v[108:111]
	v_mfma_f32_16x16x32_bf16 v[100:103], v[160:163], v[194:197], v[100:103]
	v_mfma_f32_16x16x32_bf16 v[104:107], v[160:163], v[198:201], v[104:107]
	v_mfma_f32_16x16x32_bf16 v[96:99], v[160:163], v[202:205], v[96:99]
	v_mfma_f32_16x16x32_bf16 v[92:95], v[164:167], v[190:193], v[92:95]
	v_mfma_f32_16x16x32_bf16 v[84:87], v[164:167], v[194:197], v[84:87]
	v_mfma_f32_16x16x32_bf16 v[88:91], v[164:167], v[198:201], v[88:91]
	v_mfma_f32_16x16x32_bf16 v[80:83], v[164:167], v[202:205], v[80:83]
	v_mfma_f32_16x16x32_bf16 v[76:79], v[168:171], v[190:193], v[76:79]
	v_mfma_f32_16x16x32_bf16 v[68:71], v[168:171], v[194:197], v[68:71]
	v_mfma_f32_16x16x32_bf16 v[72:75], v[168:171], v[198:201], v[72:75]
	v_mfma_f32_16x16x32_bf16 v[64:67], v[168:171], v[202:205], v[64:67]
	ds_read_b128 v[156:159], v224
	ds_read_b128 v[160:163], v224 offset:2048
	ds_read_b128 v[164:167], v224 offset:4096
	ds_read_b128 v[168:171], v224 offset:6144
	ds_read_b128 v[206:209], v226 offset:32768
	ds_read_b128 v[210:213], v226 offset:34816
	ds_read_b128 v[214:217], v226 offset:36864
	ds_read_b128 v[218:221], v226 offset:38912
	s_waitcnt lgkmcnt(8)
	v_mfma_f32_16x16x32_bf16 v[60:63], v[172:175], v[190:193], v[60:63]
	v_mfma_f32_16x16x32_bf16 v[52:55], v[172:175], v[194:197], v[52:55]
	v_mfma_f32_16x16x32_bf16 v[56:59], v[172:175], v[198:201], v[56:59]
	v_mfma_f32_16x16x32_bf16 v[48:51], v[172:175], v[202:205], v[48:51]
	v_mfma_f32_16x16x32_bf16 v[44:47], v[176:179], v[190:193], v[44:47]
	v_mfma_f32_16x16x32_bf16 v[36:39], v[176:179], v[194:197], v[36:39]
	v_mfma_f32_16x16x32_bf16 v[40:43], v[176:179], v[198:201], v[40:43]
	v_mfma_f32_16x16x32_bf16 v[32:35], v[176:179], v[202:205], v[32:35]
	v_mfma_f32_16x16x32_bf16 v[28:31], v[182:185], v[190:193], v[28:31]
	v_mfma_f32_16x16x32_bf16 v[16:19], v[182:185], v[194:197], v[16:19]
	v_mfma_f32_16x16x32_bf16 v[24:27], v[182:185], v[198:201], v[24:27]
	v_mfma_f32_16x16x32_bf16 v[12:15], v[182:185], v[202:205], v[12:15]
	v_mfma_f32_16x16x32_bf16 v[4:7], v[186:189], v[190:193], v[4:7]
	v_mfma_f32_16x16x32_bf16 v[0:3], v[186:189], v[194:197], v[0:3]
	v_mfma_f32_16x16x32_bf16 v[20:23], v[186:189], v[198:201], v[20:23]
	v_mfma_f32_16x16x32_bf16 v[8:11], v[186:189], v[202:205], v[8:11]
	ds_read_b128 v[172:175], v224 offset:8192
	ds_read_b128 v[176:179], v224 offset:10240
	ds_read_b128 v[182:185], v224 offset:12288
	ds_read_b128 v[186:189], v224 offset:14336
	s_waitcnt lgkmcnt(4)
	v_mfma_f32_16x16x32_bf16 v[124:127], v[156:159], v[206:209], v[124:127]
	v_mfma_f32_16x16x32_bf16 v[116:119], v[156:159], v[210:213], v[116:119]
	v_mfma_f32_16x16x32_bf16 v[120:123], v[156:159], v[214:217], v[120:123]
	v_mfma_f32_16x16x32_bf16 v[112:115], v[156:159], v[218:221], v[112:115]
	v_mfma_f32_16x16x32_bf16 v[108:111], v[160:163], v[206:209], v[108:111]
	v_mfma_f32_16x16x32_bf16 v[100:103], v[160:163], v[210:213], v[100:103]
	v_mfma_f32_16x16x32_bf16 v[104:107], v[160:163], v[214:217], v[104:107]
	v_mfma_f32_16x16x32_bf16 v[96:99], v[160:163], v[218:221], v[96:99]
	v_mfma_f32_16x16x32_bf16 v[92:95], v[164:167], v[206:209], v[92:95]
	v_mfma_f32_16x16x32_bf16 v[84:87], v[164:167], v[210:213], v[84:87]
	v_mfma_f32_16x16x32_bf16 v[88:91], v[164:167], v[214:217], v[88:91]
	v_mfma_f32_16x16x32_bf16 v[80:83], v[164:167], v[218:221], v[80:83]
	v_mfma_f32_16x16x32_bf16 v[76:79], v[168:171], v[206:209], v[76:79]
	v_mfma_f32_16x16x32_bf16 v[68:71], v[168:171], v[210:213], v[68:71]
	v_mfma_f32_16x16x32_bf16 v[72:75], v[168:171], v[214:217], v[72:75]
	v_mfma_f32_16x16x32_bf16 v[64:67], v[168:171], v[218:221], v[64:67]
	s_add_u32 s60, s60, 0x80
	s_addc_u32 s61, s61, 0
	s_add_i32 s59, s59, 1
	s_waitcnt lgkmcnt(0)
	s_waitcnt vmcnt(0)
	s_barrier
	v_mfma_f32_16x16x32_bf16 v[60:63], v[172:175], v[206:209], v[60:63]
	v_mfma_f32_16x16x32_bf16 v[52:55], v[172:175], v[210:213], v[52:55]
	v_mfma_f32_16x16x32_bf16 v[56:59], v[172:175], v[214:217], v[56:59]
	v_mfma_f32_16x16x32_bf16 v[48:51], v[172:175], v[218:221], v[48:51]
	v_mfma_f32_16x16x32_bf16 v[44:47], v[176:179], v[206:209], v[44:47]
	v_mfma_f32_16x16x32_bf16 v[36:39], v[176:179], v[210:213], v[36:39]
	v_mfma_f32_16x16x32_bf16 v[40:43], v[176:179], v[214:217], v[40:43]
	v_mfma_f32_16x16x32_bf16 v[32:35], v[176:179], v[218:221], v[32:35]
	v_mfma_f32_16x16x32_bf16 v[28:31], v[182:185], v[206:209], v[28:31]
	v_mfma_f32_16x16x32_bf16 v[16:19], v[182:185], v[210:213], v[16:19]
	v_mfma_f32_16x16x32_bf16 v[24:27], v[182:185], v[214:217], v[24:27]
	v_mfma_f32_16x16x32_bf16 v[12:15], v[182:185], v[218:221], v[12:15]
	v_mfma_f32_16x16x32_bf16 v[4:7], v[186:189], v[206:209], v[4:7]
	v_mfma_f32_16x16x32_bf16 v[0:3], v[186:189], v[210:213], v[0:3]
	v_mfma_f32_16x16x32_bf16 v[20:23], v[186:189], v[214:217], v[20:23]
	v_mfma_f32_16x16x32_bf16 v[8:11], v[186:189], v[218:221], v[8:11]
	s_nop 7
	s_nop 7
	s_sub_u32 s60, s60, s34
	s_subb_u32 s61, s61, s35
	s_mov_b32 s87, 0x80000
	s_mov_b32 s96, 0x80000
	s_mov_b64 s[88:89], 0
	s_mov_b64 vcc, exec
	s_branch .LBB0_120

.LBB0_263:
	s_ashr_i32 s21, s58, 2
	v_mov_b32_e32 v6, v181
	s_and_b32 s6, s58, 7
	s_and_b32 s21, s21, -8
	s_or_b32 s48, s21, s6
	v_lshrrev_b32_e32 v7, 4, v6
	v_lshlrev_b32_e32 v1, 6, v6
	v_xor_b32_e32 v0, v7, v6
	v_and_b32_e32 v8, 0x3c0, v1
	v_lshlrev_b32_e32 v1, 8, v6
	s_ashr_i32 s49, s48, 31
	v_lshlrev_b32_e32 v0, 3, v0
	v_and_b32_e32 v1, 0xfffff800, v1
	s_and_b32 s20, s57, 7
	s_bfe_u32 s6, s58, 0x20003
	s_lshl_b64 s[50:51], s[48:49], 20
	v_and_or_b32 v0, v0, 56, v1
	s_add_u32 s50, s3, s50
	v_ashrrev_i32_e32 v1, 31, v0
	s_addc_u32 s51, s54, s51
	v_lshlrev_b64 v[0:1], 1, v[0:1]
	v_lshl_add_u32 v135, v6, 4, 0
	v_lshl_add_u64 v[2:3], s[50:51], 0, v[0:1]
	v_readfirstlane_b32 s50, v135
	v_add_u32_e32 v9, 0x2000, v135
	s_mov_b32 m0, s50
	v_readfirstlane_b32 s50, v9
	v_add_u32_e32 v9, 0x4000, v135
	s_waitcnt lgkmcnt(0)
	s_barrier
	global_load_lds_dwordx4 v[2:3], off
	v_lshl_add_u64 v[4:5], v[2:3], 0, s[8:9]
	s_mov_b32 m0, s50
	v_readfirstlane_b32 s50, v9
	global_load_lds_dwordx4 v[4:5], off
	v_lshl_add_u64 v[4:5], v[2:3], 0, s[10:11]
	s_mov_b32 m0, s50
	s_lshl_b32 s49, s6, 20
	global_load_lds_dwordx4 v[4:5], off
	v_add_u32_e32 v4, 0x6000, v135
	s_add_u32 s52, s55, s49
	v_readfirstlane_b32 s50, v4
	v_add_u32_e32 v4, 0x8000, v135
	s_addc_u32 s53, s56, 0
	v_lshl_add_u64 v[2:3], v[2:3], 0, s[12:13]
	s_mov_b32 m0, s50
	v_readfirstlane_b32 s50, v4
	v_add_u32_e32 v9, 0xa000, v135
	global_load_lds_dwordx4 v[2:3], off
	v_lshl_add_u64 v[2:3], s[52:53], 0, v[0:1]
	s_mov_b32 m0, s50
	v_readfirstlane_b32 s50, v9
	v_add_u32_e32 v9, 0xc000, v135
	global_load_lds_dwordx4 v[2:3], off
	v_lshl_add_u64 v[4:5], v[2:3], 0, s[8:9]
	s_mov_b32 m0, s50
	v_readfirstlane_b32 s50, v9
	global_load_lds_dwordx4 v[4:5], off
	v_lshl_add_u64 v[4:5], v[2:3], 0, s[10:11]
	s_mov_b32 m0, s50
	v_lshl_add_u64 v[2:3], v[2:3], 0, s[12:13]
	global_load_lds_dwordx4 v[4:5], off
	v_add_u32_e32 v4, 0xe000, v135
	v_mov_b32_e32 v12, 0
	v_readfirstlane_b32 s50, v4
	s_mov_b32 m0, s50
	v_ashrrev_i32_e32 v4, 6, v6
	global_load_lds_dwordx4 v[2:3], off
	s_or_b32 s50, s21, s20
	v_lshrrev_b32_e32 v5, 30, v4
	s_ashr_i32 s51, s50, 31
	v_add_u32_e32 v5, v4, v5
	s_lshl_b64 s[50:51], s[50:51], 20
	v_bfe_u32 v2, v6, 4, 2
	v_bfe_u32 v3, v6, 1, 3
	v_and_b32_e32 v6, 0x7fffc, v5
	s_add_u32 s50, s34, s50
	v_sub_u32_e32 v4, v4, v6
	s_addc_u32 s51, s35, s51
	v_lshlrev_b32_e32 v137, 13, v4
	v_bitop3_b32 v4, v7, v3, 3 bitop3:0x6c
	v_bitop3_b32 v2, v2, v3, 4 bitop3:0x36
	v_lshl_add_u64 v[130:131], s[50:51], 0, v[0:1]
	s_add_u32 s50, s34, s49
	v_lshlrev_b32_e32 v5, 12, v5
	v_lshlrev_b32_e32 v4, 3, v4
	v_lshlrev_b32_e32 v2, 3, v2
	s_addc_u32 s51, s35, 0
	v_and_b32_e32 v136, 0xffffc000, v5
	v_lshl_add_u64 v[132:133], s[50:51], 0, v[0:1]
	s_mov_b64 s[50:51], 0
	v_lshlrev_b32_e32 v138, 1, v8
	v_lshlrev_b32_e32 v139, 1, v4
	v_lshlrev_b32_e32 v140, 1, v2
	s_mov_b32 s59, 0
	s_mov_b32 s49, 0
	v_mov_b32_e32 v13, v12
	v_mov_b32_e32 v14, v12
	v_mov_b32_e32 v15, v12
	v_mov_b32_e32 v24, v12
	v_mov_b32_e32 v25, v12
	v_mov_b32_e32 v26, v12
	v_mov_b32_e32 v27, v12
	v_mov_b32_e32 v0, v12
	v_mov_b32_e32 v1, v12
	v_mov_b32_e32 v2, v12
	v_mov_b32_e32 v3, v12
	v_mov_b32_e32 v4, v12
	v_mov_b32_e32 v5, v12
	v_mov_b32_e32 v6, v12
	v_mov_b32_e32 v7, v12
	v_mov_b32_e32 v8, v12
	v_mov_b32_e32 v9, v12
	v_mov_b32_e32 v10, v12
	v_mov_b32_e32 v11, v12
	v_mov_b32_e32 v16, v12
	v_mov_b32_e32 v17, v12
	v_mov_b32_e32 v18, v12
	v_mov_b32_e32 v19, v12
	v_mov_b32_e32 v20, v12
	v_mov_b32_e32 v21, v12
	v_mov_b32_e32 v22, v12
	v_mov_b32_e32 v23, v12
	v_mov_b32_e32 v28, v12
	v_mov_b32_e32 v29, v12
	v_mov_b32_e32 v30, v12
	v_mov_b32_e32 v31, v12
	v_mov_b32_e32 v32, v12
	v_mov_b32_e32 v33, v12
	v_mov_b32_e32 v34, v12
	v_mov_b32_e32 v35, v12
	v_mov_b32_e32 v36, v12
	v_mov_b32_e32 v37, v12
	v_mov_b32_e32 v38, v12
	v_mov_b32_e32 v39, v12
	v_mov_b32_e32 v40, v12
	v_mov_b32_e32 v41, v12
	v_mov_b32_e32 v42, v12
	v_mov_b32_e32 v43, v12
	v_mov_b32_e32 v44, v12
	v_mov_b32_e32 v45, v12
	v_mov_b32_e32 v46, v12
	v_mov_b32_e32 v47, v12
	v_mov_b32_e32 v48, v12
	v_mov_b32_e32 v49, v12
	v_mov_b32_e32 v50, v12
	v_mov_b32_e32 v51, v12
	v_mov_b32_e32 v52, v12
	v_mov_b32_e32 v53, v12
	v_mov_b32_e32 v54, v12
	v_mov_b32_e32 v55, v12
	v_mov_b32_e32 v56, v12
	v_mov_b32_e32 v57, v12
	v_mov_b32_e32 v58, v12
	v_mov_b32_e32 v59, v12
	v_mov_b32_e32 v60, v12
	v_mov_b32_e32 v61, v12
	v_mov_b32_e32 v62, v12
	v_mov_b32_e32 v63, v12
	v_mov_b32_e32 v64, v12
	v_mov_b32_e32 v65, v12
	v_mov_b32_e32 v66, v12
	v_mov_b32_e32 v67, v12
	v_mov_b32_e32 v68, v12
	v_mov_b32_e32 v69, v12
	v_mov_b32_e32 v70, v12
	v_mov_b32_e32 v71, v12
	v_mov_b32_e32 v72, v12
	v_mov_b32_e32 v73, v12
	v_mov_b32_e32 v74, v12
	v_mov_b32_e32 v75, v12
	v_mov_b32_e32 v76, v12
	v_mov_b32_e32 v77, v12
	v_mov_b32_e32 v78, v12
	v_mov_b32_e32 v79, v12
	v_mov_b32_e32 v80, v12
	v_mov_b32_e32 v81, v12
	v_mov_b32_e32 v82, v12
	v_mov_b32_e32 v83, v12
	v_mov_b32_e32 v84, v12
	v_mov_b32_e32 v85, v12
	v_mov_b32_e32 v86, v12
	v_mov_b32_e32 v87, v12
	v_mov_b32_e32 v88, v12
	v_mov_b32_e32 v89, v12
	v_mov_b32_e32 v90, v12
	v_mov_b32_e32 v91, v12
	v_mov_b32_e32 v92, v12
	v_mov_b32_e32 v93, v12
	v_mov_b32_e32 v94, v12
	v_mov_b32_e32 v95, v12
	v_mov_b32_e32 v96, v12
	v_mov_b32_e32 v97, v12
	v_mov_b32_e32 v98, v12
	v_mov_b32_e32 v99, v12
	v_mov_b32_e32 v100, v12
	v_mov_b32_e32 v101, v12
	v_mov_b32_e32 v102, v12
	v_mov_b32_e32 v103, v12
	v_mov_b32_e32 v104, v12
	v_mov_b32_e32 v105, v12
	v_mov_b32_e32 v106, v12
	v_mov_b32_e32 v107, v12
	v_mov_b32_e32 v108, v12
	v_mov_b32_e32 v109, v12
	v_mov_b32_e32 v110, v12
	v_mov_b32_e32 v111, v12
	v_mov_b32_e32 v112, v12
	v_mov_b32_e32 v113, v12
	v_mov_b32_e32 v114, v12
	v_mov_b32_e32 v115, v12
	v_mov_b32_e32 v116, v12
	v_mov_b32_e32 v117, v12
	v_mov_b32_e32 v118, v12
	v_mov_b32_e32 v119, v12
	v_mov_b32_e32 v120, v12
	v_mov_b32_e32 v121, v12
	v_mov_b32_e32 v122, v12
	v_mov_b32_e32 v123, v12
	v_mov_b32_e32 v124, v12
	v_mov_b32_e32 v125, v12
	v_mov_b32_e32 v126, v12
	v_mov_b32_e32 v127, v12
	s_waitcnt vmcnt(0) lgkmcnt(0)
	s_barrier
	v_add3_u32 v141, v136, v138, v139
	v_add3_u32 v210, v137, v138, v139
	v_add3_u32 v180, v136, v138, v140
	v_add3_u32 v211, v137, v138, v140
	v_xor_b32_e32 v212, 0x10000, v141
	v_xor_b32_e32 v213, 0x10000, v180
	v_xor_b32_e32 v214, 0x10000, v210
	v_xor_b32_e32 v215, 0x10000, v211
	v_readfirstlane_b32 s59, v135
	ds_read_b128 v[142:145], v141
	ds_read_b128 v[146:149], v141 offset:2048
	ds_read_b128 v[150:153], v141 offset:4096
	ds_read_b128 v[154:157], v141 offset:6144
	ds_read_b128 v[174:177], v210 offset:32768
	ds_read_b128 v[182:185], v210 offset:34816
	ds_read_b128 v[186:189], v210 offset:36864
	ds_read_b128 v[190:193], v210 offset:38912
	s_mov_b32 s49, 0
	s_mov_b64 s[50:51], s[34:35]
	v_subrev_u32_e32 v178, s34, v130
	v_subrev_u32_e32 v179, s34, v132
	s_add_u32 s59, s59, 0x10000
	s_mov_b32 m0, s59
	s_add_u32 s52, s50, s14
	s_addc_u32 s53, s51, s15
	global_load_lds_dwordx4 v178, s[52:53]
	s_add_u32 m0, s59, 0x2000
	s_add_u32 s52, s50, s16
	s_addc_u32 s53, s51, s17
	global_load_lds_dwordx4 v178, s[52:53]
	s_add_u32 m0, s59, 0x4000
	s_add_u32 s52, s50, s18
	s_addc_u32 s53, s51, s19
	global_load_lds_dwordx4 v178, s[52:53]
	s_add_u32 m0, s59, 0x6000
	s_add_u32 s52, s50, s22
	s_addc_u32 s53, s51, s23
	global_load_lds_dwordx4 v178, s[52:53]
	s_add_u32 m0, s59, 0x8000
	s_add_u32 s52, s50, s40
	s_addc_u32 s53, s51, s41
	global_load_lds_dwordx4 v179, s[52:53]
	s_add_u32 m0, s59, 0xa000
	s_add_u32 s52, s50, s42
	s_addc_u32 s53, s51, s43
	global_load_lds_dwordx4 v179, s[52:53]
	s_add_u32 m0, s59, 0xc000
	s_add_u32 s52, s50, s44
	s_addc_u32 s53, s51, s45
	global_load_lds_dwordx4 v179, s[52:53]
	s_add_u32 m0, s59, 0xe000
	s_add_u32 s52, s50, s46
	s_addc_u32 s53, s51, s47
	global_load_lds_dwordx4 v179, s[52:53]
	s_branch .Lg1_entry
.Lg1_top:
	s_waitcnt lgkmcnt(0)
	s_waitcnt vmcnt(0)
	s_barrier
	s_xor_b32 s59, s59, 0x10000
	ds_read_b128 v[142:145], v141
	ds_read_b128 v[146:149], v141 offset:2048
	ds_read_b128 v[150:153], v141 offset:4096
	ds_read_b128 v[154:157], v141 offset:6144
	ds_read_b128 v[174:177], v210 offset:32768
	ds_read_b128 v[182:185], v210 offset:34816
	ds_read_b128 v[186:189], v210 offset:36864
	ds_read_b128 v[190:193], v210 offset:38912
	v_mfma_f32_16x16x32_bf16 v[60:63], v[158:161], v[194:197], v[60:63]
	v_mfma_f32_16x16x32_bf16 v[56:59], v[158:161], v[198:201], v[56:59]
	s_mov_b32 m0, s59
	s_add_u32 s52, s50, s14
	s_addc_u32 s53, s51, s15
	global_load_lds_dwordx4 v178, s[52:53]
	v_mfma_f32_16x16x32_bf16 v[52:55], v[158:161], v[202:205], v[52:55]
	v_mfma_f32_16x16x32_bf16 v[48:51], v[158:161], v[206:209], v[48:51]
	s_add_u32 m0, s59, 0x2000
	s_add_u32 s52, s50, s16
	s_addc_u32 s53, s51, s17
	global_load_lds_dwordx4 v178, s[52:53]
	v_mfma_f32_16x16x32_bf16 v[44:47], v[162:165], v[194:197], v[44:47]
	v_mfma_f32_16x16x32_bf16 v[40:43], v[162:165], v[198:201], v[40:43]
	s_add_u32 m0, s59, 0x4000
	s_add_u32 s52, s50, s18
	s_addc_u32 s53, s51, s19
	global_load_lds_dwordx4 v178, s[52:53]
	v_mfma_f32_16x16x32_bf16 v[36:39], v[162:165], v[202:205], v[36:39]
	v_mfma_f32_16x16x32_bf16 v[32:35], v[162:165], v[206:209], v[32:35]
	s_add_u32 m0, s59, 0x6000
	s_add_u32 s52, s50, s22
	s_addc_u32 s53, s51, s23
	global_load_lds_dwordx4 v178, s[52:53]
	v_mfma_f32_16x16x32_bf16 v[28:31], v[166:169], v[194:197], v[28:31]
	v_mfma_f32_16x16x32_bf16 v[20:23], v[166:169], v[198:201], v[20:23]
	s_add_u32 m0, s59, 0x8000
	s_add_u32 s52, s50, s40
	s_addc_u32 s53, s51, s41
	global_load_lds_dwordx4 v179, s[52:53]
	v_mfma_f32_16x16x32_bf16 v[16:19], v[166:169], v[202:205], v[16:19]
	v_mfma_f32_16x16x32_bf16 v[8:11], v[166:169], v[206:209], v[8:11]
	s_add_u32 m0, s59, 0xa000
	s_add_u32 s52, s50, s42
	s_addc_u32 s53, s51, s43
	global_load_lds_dwordx4 v179, s[52:53]
	v_mfma_f32_16x16x32_bf16 v[4:7], v[170:173], v[194:197], v[4:7]
	v_mfma_f32_16x16x32_bf16 v[0:3], v[170:173], v[198:201], v[0:3]
	s_add_u32 m0, s59, 0xc000
	s_add_u32 s52, s50, s44
	s_addc_u32 s53, s51, s45
	global_load_lds_dwordx4 v179, s[52:53]
	v_mfma_f32_16x16x32_bf16 v[24:27], v[170:173], v[202:205], v[24:27]
	v_mfma_f32_16x16x32_bf16 v[12:15], v[170:173], v[206:209], v[12:15]
	s_add_u32 m0, s59, 0xe000
	s_add_u32 s52, s50, s46
	s_addc_u32 s53, s51, s47
	global_load_lds_dwordx4 v179, s[52:53]
.Lg1_entry:
	ds_read_b128 v[158:161], v141 offset:8192
	ds_read_b128 v[162:165], v141 offset:10240
	ds_read_b128 v[166:169], v141 offset:12288
	ds_read_b128 v[170:173], v141 offset:14336
	s_waitcnt lgkmcnt(4)
	v_mfma_f32_16x16x32_bf16 v[124:127], v[142:145], v[174:177], v[124:127]
	v_mfma_f32_16x16x32_bf16 v[120:123], v[142:145], v[182:185], v[120:123]
	v_mfma_f32_16x16x32_bf16 v[116:119], v[142:145], v[186:189], v[116:119]
	v_mfma_f32_16x16x32_bf16 v[112:115], v[142:145], v[190:193], v[112:115]
	v_mfma_f32_16x16x32_bf16 v[108:111], v[146:149], v[174:177], v[108:111]
	v_mfma_f32_16x16x32_bf16 v[104:107], v[146:149], v[182:185], v[104:107]
	v_mfma_f32_16x16x32_bf16 v[100:103], v[146:149], v[186:189], v[100:103]
	v_mfma_f32_16x16x32_bf16 v[96:99], v[146:149], v[190:193], v[96:99]
	v_mfma_f32_16x16x32_bf16 v[92:95], v[150:153], v[174:177], v[92:95]
	v_mfma_f32_16x16x32_bf16 v[88:91], v[150:153], v[182:185], v[88:91]
	v_mfma_f32_16x16x32_bf16 v[84:87], v[150:153], v[186:189], v[84:87]
	v_mfma_f32_16x16x32_bf16 v[80:83], v[150:153], v[190:193], v[80:83]
	v_mfma_f32_16x16x32_bf16 v[76:79], v[154:157], v[174:177], v[76:79]
	v_mfma_f32_16x16x32_bf16 v[72:75], v[154:157], v[182:185], v[72:75]
	v_mfma_f32_16x16x32_bf16 v[68:71], v[154:157], v[186:189], v[68:71]
	v_mfma_f32_16x16x32_bf16 v[64:67], v[154:157], v[190:193], v[64:67]
	ds_read_b128 v[142:145], v180
	ds_read_b128 v[146:149], v180 offset:2048
	ds_read_b128 v[150:153], v180 offset:4096
	ds_read_b128 v[154:157], v180 offset:6144
	ds_read_b128 v[194:197], v211 offset:32768
	ds_read_b128 v[198:201], v211 offset:34816
	ds_read_b128 v[202:205], v211 offset:36864
	ds_read_b128 v[206:209], v211 offset:38912
	s_waitcnt lgkmcnt(8)
	v_mfma_f32_16x16x32_bf16 v[60:63], v[158:161], v[174:177], v[60:63]
	v_mfma_f32_16x16x32_bf16 v[56:59], v[158:161], v[182:185], v[56:59]
	v_mfma_f32_16x16x32_bf16 v[52:55], v[158:161], v[186:189], v[52:55]
	v_mfma_f32_16x16x32_bf16 v[48:51], v[158:161], v[190:193], v[48:51]
	v_mfma_f32_16x16x32_bf16 v[44:47], v[162:165], v[174:177], v[44:47]
	v_mfma_f32_16x16x32_bf16 v[40:43], v[162:165], v[182:185], v[40:43]
	v_mfma_f32_16x16x32_bf16 v[36:39], v[162:165], v[186:189], v[36:39]
	v_mfma_f32_16x16x32_bf16 v[32:35], v[162:165], v[190:193], v[32:35]
	v_mfma_f32_16x16x32_bf16 v[28:31], v[166:169], v[174:177], v[28:31]
	v_mfma_f32_16x16x32_bf16 v[20:23], v[166:169], v[182:185], v[20:23]
	v_mfma_f32_16x16x32_bf16 v[16:19], v[166:169], v[186:189], v[16:19]
	v_mfma_f32_16x16x32_bf16 v[8:11], v[166:169], v[190:193], v[8:11]
	v_mfma_f32_16x16x32_bf16 v[4:7], v[170:173], v[174:177], v[4:7]
	v_mfma_f32_16x16x32_bf16 v[0:3], v[170:173], v[182:185], v[0:3]
	v_mfma_f32_16x16x32_bf16 v[24:27], v[170:173], v[186:189], v[24:27]
	v_mfma_f32_16x16x32_bf16 v[12:15], v[170:173], v[190:193], v[12:15]
	ds_read_b128 v[158:161], v180 offset:8192
	ds_read_b128 v[162:165], v180 offset:10240
	ds_read_b128 v[166:169], v180 offset:12288
	ds_read_b128 v[170:173], v180 offset:14336
	s_waitcnt lgkmcnt(4)
	v_mfma_f32_16x16x32_bf16 v[124:127], v[142:145], v[194:197], v[124:127]
	v_mfma_f32_16x16x32_bf16 v[120:123], v[142:145], v[198:201], v[120:123]
	v_mfma_f32_16x16x32_bf16 v[116:119], v[142:145], v[202:205], v[116:119]
	v_mfma_f32_16x16x32_bf16 v[112:115], v[142:145], v[206:209], v[112:115]
	v_mfma_f32_16x16x32_bf16 v[108:111], v[146:149], v[194:197], v[108:111]
	v_mfma_f32_16x16x32_bf16 v[104:107], v[146:149], v[198:201], v[104:107]
	v_mfma_f32_16x16x32_bf16 v[100:103], v[146:149], v[202:205], v[100:103]
	v_mfma_f32_16x16x32_bf16 v[96:99], v[146:149], v[206:209], v[96:99]
	v_mfma_f32_16x16x32_bf16 v[92:95], v[150:153], v[194:197], v[92:95]
	v_mfma_f32_16x16x32_bf16 v[88:91], v[150:153], v[198:201], v[88:91]
	v_mfma_f32_16x16x32_bf16 v[84:87], v[150:153], v[202:205], v[84:87]
	v_mfma_f32_16x16x32_bf16 v[80:83], v[150:153], v[206:209], v[80:83]
	v_mfma_f32_16x16x32_bf16 v[76:79], v[154:157], v[194:197], v[76:79]
	v_mfma_f32_16x16x32_bf16 v[72:75], v[154:157], v[198:201], v[72:75]
	v_mfma_f32_16x16x32_bf16 v[68:71], v[154:157], v[202:205], v[68:71]
	v_mfma_f32_16x16x32_bf16 v[64:67], v[154:157], v[206:209], v[64:67]
	s_add_u32 s50, s50, 0x80
	s_addc_u32 s51, s51, 0
	s_add_i32 s49, s49, 1
	s_cmp_lt_u32 s49, 31
	s_cbranch_scc0 .Lg1_last
	s_waitcnt lgkmcnt(0)
	s_waitcnt vmcnt(0)
	s_barrier
	s_xor_b32 s59, s59, 0x10000
	ds_read_b128 v[142:145], v212
	ds_read_b128 v[146:149], v212 offset:2048
	ds_read_b128 v[150:153], v212 offset:4096
	ds_read_b128 v[154:157], v212 offset:6144
	ds_read_b128 v[174:177], v214 offset:32768
	ds_read_b128 v[182:185], v214 offset:34816
	ds_read_b128 v[186:189], v214 offset:36864
	ds_read_b128 v[190:193], v214 offset:38912
	v_mfma_f32_16x16x32_bf16 v[60:63], v[158:161], v[194:197], v[60:63]
	v_mfma_f32_16x16x32_bf16 v[56:59], v[158:161], v[198:201], v[56:59]
	s_mov_b32 m0, s59
	s_add_u32 s52, s50, s14
	s_addc_u32 s53, s51, s15
	global_load_lds_dwordx4 v178, s[52:53]
	v_mfma_f32_16x16x32_bf16 v[52:55], v[158:161], v[202:205], v[52:55]
	v_mfma_f32_16x16x32_bf16 v[48:51], v[158:161], v[206:209], v[48:51]
	s_add_u32 m0, s59, 0x2000
	s_add_u32 s52, s50, s16
	s_addc_u32 s53, s51, s17
	global_load_lds_dwordx4 v178, s[52:53]
	v_mfma_f32_16x16x32_bf16 v[44:47], v[162:165], v[194:197], v[44:47]
	v_mfma_f32_16x16x32_bf16 v[40:43], v[162:165], v[198:201], v[40:43]
	s_add_u32 m0, s59, 0x4000
	s_add_u32 s52, s50, s18
	s_addc_u32 s53, s51, s19
	global_load_lds_dwordx4 v178, s[52:53]
	v_mfma_f32_16x16x32_bf16 v[36:39], v[162:165], v[202:205], v[36:39]
	v_mfma_f32_16x16x32_bf16 v[32:35], v[162:165], v[206:209], v[32:35]
	s_add_u32 m0, s59, 0x6000
	s_add_u32 s52, s50, s22
	s_addc_u32 s53, s51, s23
	global_load_lds_dwordx4 v178, s[52:53]
	v_mfma_f32_16x16x32_bf16 v[28:31], v[166:169], v[194:197], v[28:31]
	v_mfma_f32_16x16x32_bf16 v[20:23], v[166:169], v[198:201], v[20:23]
	s_add_u32 m0, s59, 0x8000
	s_add_u32 s52, s50, s40
	s_addc_u32 s53, s51, s41
	global_load_lds_dwordx4 v179, s[52:53]
	v_mfma_f32_16x16x32_bf16 v[16:19], v[166:169], v[202:205], v[16:19]
	v_mfma_f32_16x16x32_bf16 v[8:11], v[166:169], v[206:209], v[8:11]
	s_add_u32 m0, s59, 0xa000
	s_add_u32 s52, s50, s42
	s_addc_u32 s53, s51, s43
	global_load_lds_dwordx4 v179, s[52:53]
	v_mfma_f32_16x16x32_bf16 v[4:7], v[170:173], v[194:197], v[4:7]
	v_mfma_f32_16x16x32_bf16 v[0:3], v[170:173], v[198:201], v[0:3]
	s_add_u32 m0, s59, 0xc000
	s_add_u32 s52, s50, s44
	s_addc_u32 s53, s51, s45
	global_load_lds_dwordx4 v179, s[52:53]
	v_mfma_f32_16x16x32_bf16 v[24:27], v[170:173], v[202:205], v[24:27]
	v_mfma_f32_16x16x32_bf16 v[12:15], v[170:173], v[206:209], v[12:15]
	s_add_u32 m0, s59, 0xe000
	s_add_u32 s52, s50, s46
	s_addc_u32 s53, s51, s47
	global_load_lds_dwordx4 v179, s[52:53]
	ds_read_b128 v[158:161], v212 offset:8192
	ds_read_b128 v[162:165], v212 offset:10240
	ds_read_b128 v[166:169], v212 offset:12288
	ds_read_b128 v[170:173], v212 offset:14336
	s_waitcnt lgkmcnt(4)
	v_mfma_f32_16x16x32_bf16 v[124:127], v[142:145], v[174:177], v[124:127]
	v_mfma_f32_16x16x32_bf16 v[120:123], v[142:145], v[182:185], v[120:123]
	v_mfma_f32_16x16x32_bf16 v[116:119], v[142:145], v[186:189], v[116:119]
	v_mfma_f32_16x16x32_bf16 v[112:115], v[142:145], v[190:193], v[112:115]
	v_mfma_f32_16x16x32_bf16 v[108:111], v[146:149], v[174:177], v[108:111]
	v_mfma_f32_16x16x32_bf16 v[104:107], v[146:149], v[182:185], v[104:107]
	v_mfma_f32_16x16x32_bf16 v[100:103], v[146:149], v[186:189], v[100:103]
	v_mfma_f32_16x16x32_bf16 v[96:99], v[146:149], v[190:193], v[96:99]
	v_mfma_f32_16x16x32_bf16 v[92:95], v[150:153], v[174:177], v[92:95]
	v_mfma_f32_16x16x32_bf16 v[88:91], v[150:153], v[182:185], v[88:91]
	v_mfma_f32_16x16x32_bf16 v[84:87], v[150:153], v[186:189], v[84:87]
	v_mfma_f32_16x16x32_bf16 v[80:83], v[150:153], v[190:193], v[80:83]
	v_mfma_f32_16x16x32_bf16 v[76:79], v[154:157], v[174:177], v[76:79]
	v_mfma_f32_16x16x32_bf16 v[72:75], v[154:157], v[182:185], v[72:75]
	v_mfma_f32_16x16x32_bf16 v[68:71], v[154:157], v[186:189], v[68:71]
	v_mfma_f32_16x16x32_bf16 v[64:67], v[154:157], v[190:193], v[64:67]
	ds_read_b128 v[142:145], v213
	ds_read_b128 v[146:149], v213 offset:2048
	ds_read_b128 v[150:153], v213 offset:4096
	ds_read_b128 v[154:157], v213 offset:6144
	ds_read_b128 v[194:197], v215 offset:32768
	ds_read_b128 v[198:201], v215 offset:34816
	ds_read_b128 v[202:205], v215 offset:36864
	ds_read_b128 v[206:209], v215 offset:38912
	s_waitcnt lgkmcnt(8)
	v_mfma_f32_16x16x32_bf16 v[60:63], v[158:161], v[174:177], v[60:63]
	v_mfma_f32_16x16x32_bf16 v[56:59], v[158:161], v[182:185], v[56:59]
	v_mfma_f32_16x16x32_bf16 v[52:55], v[158:161], v[186:189], v[52:55]
	v_mfma_f32_16x16x32_bf16 v[48:51], v[158:161], v[190:193], v[48:51]
	v_mfma_f32_16x16x32_bf16 v[44:47], v[162:165], v[174:177], v[44:47]
	v_mfma_f32_16x16x32_bf16 v[40:43], v[162:165], v[182:185], v[40:43]
	v_mfma_f32_16x16x32_bf16 v[36:39], v[162:165], v[186:189], v[36:39]
	v_mfma_f32_16x16x32_bf16 v[32:35], v[162:165], v[190:193], v[32:35]
	v_mfma_f32_16x16x32_bf16 v[28:31], v[166:169], v[174:177], v[28:31]
	v_mfma_f32_16x16x32_bf16 v[20:23], v[166:169], v[182:185], v[20:23]
	v_mfma_f32_16x16x32_bf16 v[16:19], v[166:169], v[186:189], v[16:19]
	v_mfma_f32_16x16x32_bf16 v[8:11], v[166:169], v[190:193], v[8:11]
	v_mfma_f32_16x16x32_bf16 v[4:7], v[170:173], v[174:177], v[4:7]
	v_mfma_f32_16x16x32_bf16 v[0:3], v[170:173], v[182:185], v[0:3]
	v_mfma_f32_16x16x32_bf16 v[24:27], v[170:173], v[186:189], v[24:27]
	v_mfma_f32_16x16x32_bf16 v[12:15], v[170:173], v[190:193], v[12:15]
	ds_read_b128 v[158:161], v213 offset:8192
	ds_read_b128 v[162:165], v213 offset:10240
	ds_read_b128 v[166:169], v213 offset:12288
	ds_read_b128 v[170:173], v213 offset:14336
	s_waitcnt lgkmcnt(4)
	v_mfma_f32_16x16x32_bf16 v[124:127], v[142:145], v[194:197], v[124:127]
	v_mfma_f32_16x16x32_bf16 v[120:123], v[142:145], v[198:201], v[120:123]
	v_mfma_f32_16x16x32_bf16 v[116:119], v[142:145], v[202:205], v[116:119]
	v_mfma_f32_16x16x32_bf16 v[112:115], v[142:145], v[206:209], v[112:115]
	v_mfma_f32_16x16x32_bf16 v[108:111], v[146:149], v[194:197], v[108:111]
	v_mfma_f32_16x16x32_bf16 v[104:107], v[146:149], v[198:201], v[104:107]
	v_mfma_f32_16x16x32_bf16 v[100:103], v[146:149], v[202:205], v[100:103]
	v_mfma_f32_16x16x32_bf16 v[96:99], v[146:149], v[206:209], v[96:99]
	v_mfma_f32_16x16x32_bf16 v[92:95], v[150:153], v[194:197], v[92:95]
	v_mfma_f32_16x16x32_bf16 v[88:91], v[150:153], v[198:201], v[88:91]
	v_mfma_f32_16x16x32_bf16 v[84:87], v[150:153], v[202:205], v[84:87]
	v_mfma_f32_16x16x32_bf16 v[80:83], v[150:153], v[206:209], v[80:83]
	v_mfma_f32_16x16x32_bf16 v[76:79], v[154:157], v[194:197], v[76:79]
	v_mfma_f32_16x16x32_bf16 v[72:75], v[154:157], v[198:201], v[72:75]
	v_mfma_f32_16x16x32_bf16 v[68:71], v[154:157], v[202:205], v[68:71]
	v_mfma_f32_16x16x32_bf16 v[64:67], v[154:157], v[206:209], v[64:67]
	s_add_u32 s50, s50, 0x80
	s_addc_u32 s51, s51, 0
	s_add_i32 s49, s49, 1
	s_branch .Lg1_top
.Lg1_last:
	s_waitcnt lgkmcnt(0)
	s_waitcnt vmcnt(0)
	s_barrier
	s_xor_b32 s59, s59, 0x10000
	ds_read_b128 v[142:145], v212
	ds_read_b128 v[146:149], v212 offset:2048
	ds_read_b128 v[150:153], v212 offset:4096
	ds_read_b128 v[154:157], v212 offset:6144
	ds_read_b128 v[174:177], v214 offset:32768
	ds_read_b128 v[182:185], v214 offset:34816
	ds_read_b128 v[186:189], v214 offset:36864
	ds_read_b128 v[190:193], v214 offset:38912
	v_mfma_f32_16x16x32_bf16 v[60:63], v[158:161], v[194:197], v[60:63]
	v_mfma_f32_16x16x32_bf16 v[56:59], v[158:161], v[198:201], v[56:59]
	v_mfma_f32_16x16x32_bf16 v[52:55], v[158:161], v[202:205], v[52:55]
	v_mfma_f32_16x16x32_bf16 v[48:51], v[158:161], v[206:209], v[48:51]
	v_mfma_f32_16x16x32_bf16 v[44:47], v[162:165], v[194:197], v[44:47]
	v_mfma_f32_16x16x32_bf16 v[40:43], v[162:165], v[198:201], v[40:43]
	v_mfma_f32_16x16x32_bf16 v[36:39], v[162:165], v[202:205], v[36:39]
	v_mfma_f32_16x16x32_bf16 v[32:35], v[162:165], v[206:209], v[32:35]
	v_mfma_f32_16x16x32_bf16 v[28:31], v[166:169], v[194:197], v[28:31]
	v_mfma_f32_16x16x32_bf16 v[20:23], v[166:169], v[198:201], v[20:23]
	v_mfma_f32_16x16x32_bf16 v[16:19], v[166:169], v[202:205], v[16:19]
	v_mfma_f32_16x16x32_bf16 v[8:11], v[166:169], v[206:209], v[8:11]
	v_mfma_f32_16x16x32_bf16 v[4:7], v[170:173], v[194:197], v[4:7]
	v_mfma_f32_16x16x32_bf16 v[0:3], v[170:173], v[198:201], v[0:3]
	v_mfma_f32_16x16x32_bf16 v[24:27], v[170:173], v[202:205], v[24:27]
	v_mfma_f32_16x16x32_bf16 v[12:15], v[170:173], v[206:209], v[12:15]
	ds_read_b128 v[158:161], v212 offset:8192
	ds_read_b128 v[162:165], v212 offset:10240
	ds_read_b128 v[166:169], v212 offset:12288
	ds_read_b128 v[170:173], v212 offset:14336
	s_waitcnt lgkmcnt(4)
	v_mfma_f32_16x16x32_bf16 v[124:127], v[142:145], v[174:177], v[124:127]
	v_mfma_f32_16x16x32_bf16 v[120:123], v[142:145], v[182:185], v[120:123]
	v_mfma_f32_16x16x32_bf16 v[116:119], v[142:145], v[186:189], v[116:119]
	v_mfma_f32_16x16x32_bf16 v[112:115], v[142:145], v[190:193], v[112:115]
	v_mfma_f32_16x16x32_bf16 v[108:111], v[146:149], v[174:177], v[108:111]
	v_mfma_f32_16x16x32_bf16 v[104:107], v[146:149], v[182:185], v[104:107]
	v_mfma_f32_16x16x32_bf16 v[100:103], v[146:149], v[186:189], v[100:103]
	v_mfma_f32_16x16x32_bf16 v[96:99], v[146:149], v[190:193], v[96:99]
	v_mfma_f32_16x16x32_bf16 v[92:95], v[150:153], v[174:177], v[92:95]
	v_mfma_f32_16x16x32_bf16 v[88:91], v[150:153], v[182:185], v[88:91]
	v_mfma_f32_16x16x32_bf16 v[84:87], v[150:153], v[186:189], v[84:87]
	v_mfma_f32_16x16x32_bf16 v[80:83], v[150:153], v[190:193], v[80:83]
	v_mfma_f32_16x16x32_bf16 v[76:79], v[154:157], v[174:177], v[76:79]
	v_mfma_f32_16x16x32_bf16 v[72:75], v[154:157], v[182:185], v[72:75]
	v_mfma_f32_16x16x32_bf16 v[68:71], v[154:157], v[186:189], v[68:71]
	v_mfma_f32_16x16x32_bf16 v[64:67], v[154:157], v[190:193], v[64:67]
	ds_read_b128 v[142:145], v213
	ds_read_b128 v[146:149], v213 offset:2048
	ds_read_b128 v[150:153], v213 offset:4096
	ds_read_b128 v[154:157], v213 offset:6144
	ds_read_b128 v[194:197], v215 offset:32768
	ds_read_b128 v[198:201], v215 offset:34816
	ds_read_b128 v[202:205], v215 offset:36864
	ds_read_b128 v[206:209], v215 offset:38912
	s_waitcnt lgkmcnt(8)
	v_mfma_f32_16x16x32_bf16 v[60:63], v[158:161], v[174:177], v[60:63]
	v_mfma_f32_16x16x32_bf16 v[56:59], v[158:161], v[182:185], v[56:59]
	v_mfma_f32_16x16x32_bf16 v[52:55], v[158:161], v[186:189], v[52:55]
	v_mfma_f32_16x16x32_bf16 v[48:51], v[158:161], v[190:193], v[48:51]
	v_mfma_f32_16x16x32_bf16 v[44:47], v[162:165], v[174:177], v[44:47]
	v_mfma_f32_16x16x32_bf16 v[40:43], v[162:165], v[182:185], v[40:43]
	v_mfma_f32_16x16x32_bf16 v[36:39], v[162:165], v[186:189], v[36:39]
	v_mfma_f32_16x16x32_bf16 v[32:35], v[162:165], v[190:193], v[32:35]
	v_mfma_f32_16x16x32_bf16 v[28:31], v[166:169], v[174:177], v[28:31]
	v_mfma_f32_16x16x32_bf16 v[20:23], v[166:169], v[182:185], v[20:23]
	v_mfma_f32_16x16x32_bf16 v[16:19], v[166:169], v[186:189], v[16:19]
	v_mfma_f32_16x16x32_bf16 v[8:11], v[166:169], v[190:193], v[8:11]
	v_mfma_f32_16x16x32_bf16 v[4:7], v[170:173], v[174:177], v[4:7]
	v_mfma_f32_16x16x32_bf16 v[0:3], v[170:173], v[182:185], v[0:3]
	v_mfma_f32_16x16x32_bf16 v[24:27], v[170:173], v[186:189], v[24:27]
	v_mfma_f32_16x16x32_bf16 v[12:15], v[170:173], v[190:193], v[12:15]
	ds_read_b128 v[158:161], v213 offset:8192
	ds_read_b128 v[162:165], v213 offset:10240
	ds_read_b128 v[166:169], v213 offset:12288
	ds_read_b128 v[170:173], v213 offset:14336
	s_waitcnt lgkmcnt(4)
	v_mfma_f32_16x16x32_bf16 v[124:127], v[142:145], v[194:197], v[124:127]
	v_mfma_f32_16x16x32_bf16 v[120:123], v[142:145], v[198:201], v[120:123]
	v_mfma_f32_16x16x32_bf16 v[116:119], v[142:145], v[202:205], v[116:119]
	v_mfma_f32_16x16x32_bf16 v[112:115], v[142:145], v[206:209], v[112:115]
	v_mfma_f32_16x16x32_bf16 v[108:111], v[146:149], v[194:197], v[108:111]
	v_mfma_f32_16x16x32_bf16 v[104:107], v[146:149], v[198:201], v[104:107]
	v_mfma_f32_16x16x32_bf16 v[100:103], v[146:149], v[202:205], v[100:103]
	v_mfma_f32_16x16x32_bf16 v[96:99], v[146:149], v[206:209], v[96:99]
	v_mfma_f32_16x16x32_bf16 v[92:95], v[150:153], v[194:197], v[92:95]
	v_mfma_f32_16x16x32_bf16 v[88:91], v[150:153], v[198:201], v[88:91]
	v_mfma_f32_16x16x32_bf16 v[84:87], v[150:153], v[202:205], v[84:87]
	v_mfma_f32_16x16x32_bf16 v[80:83], v[150:153], v[206:209], v[80:83]
	v_mfma_f32_16x16x32_bf16 v[76:79], v[154:157], v[194:197], v[76:79]
	v_mfma_f32_16x16x32_bf16 v[72:75], v[154:157], v[198:201], v[72:75]
	v_mfma_f32_16x16x32_bf16 v[68:71], v[154:157], v[202:205], v[68:71]
	v_mfma_f32_16x16x32_bf16 v[64:67], v[154:157], v[206:209], v[64:67]
	s_add_u32 s50, s50, 0x80
	s_addc_u32 s51, s51, 0
	s_add_i32 s49, s49, 1
	s_waitcnt lgkmcnt(0)
	s_waitcnt vmcnt(0)
	s_barrier
	v_mfma_f32_16x16x32_bf16 v[60:63], v[158:161], v[194:197], v[60:63]
	v_mfma_f32_16x16x32_bf16 v[56:59], v[158:161], v[198:201], v[56:59]
	v_mfma_f32_16x16x32_bf16 v[52:55], v[158:161], v[202:205], v[52:55]
	v_mfma_f32_16x16x32_bf16 v[48:51], v[158:161], v[206:209], v[48:51]
	v_mfma_f32_16x16x32_bf16 v[44:47], v[162:165], v[194:197], v[44:47]
	v_mfma_f32_16x16x32_bf16 v[40:43], v[162:165], v[198:201], v[40:43]
	v_mfma_f32_16x16x32_bf16 v[36:39], v[162:165], v[202:205], v[36:39]
	v_mfma_f32_16x16x32_bf16 v[32:35], v[162:165], v[206:209], v[32:35]
	v_mfma_f32_16x16x32_bf16 v[28:31], v[166:169], v[194:197], v[28:31]
	v_mfma_f32_16x16x32_bf16 v[20:23], v[166:169], v[198:201], v[20:23]
	v_mfma_f32_16x16x32_bf16 v[16:19], v[166:169], v[202:205], v[16:19]
	v_mfma_f32_16x16x32_bf16 v[8:11], v[166:169], v[206:209], v[8:11]
	v_mfma_f32_16x16x32_bf16 v[4:7], v[170:173], v[194:197], v[4:7]
	v_mfma_f32_16x16x32_bf16 v[0:3], v[170:173], v[198:201], v[0:3]
	v_mfma_f32_16x16x32_bf16 v[24:27], v[170:173], v[202:205], v[24:27]
	v_mfma_f32_16x16x32_bf16 v[12:15], v[170:173], v[206:209], v[12:15]
	s_nop 7
	s_nop 7
	s_sub_u32 s50, s50, s34
	s_subb_u32 s51, s51, s35
	s_mov_b32 s59, 0x100000
	s_mov_b32 s60, 0x100000
	s_mov_b64 s[52:53], 0
	s_mov_b64 vcc, exec
	s_branch .LBB0_262

.LBB0_452:
	s_ashr_i32 s46, s60, 3
	s_and_b32 s21, s60, 7
	s_and_b32 s62, s46, -8
	v_mov_b32_e32 v6, v181
	s_or_b32 s46, s62, s21
	s_ashr_i32 s47, s46, 31
	v_lshrrev_b32_e32 v7, 4, v6
	v_lshlrev_b32_e32 v1, 6, v6
	v_xor_b32_e32 v0, v7, v6
	v_and_b32_e32 v8, 0x3c0, v1
	v_lshlrev_b32_e32 v1, 7, v6
	s_and_b32 s20, s55, 7
	s_bfe_u32 s61, s60, 0x30003
	s_lshl_b64 s[48:49], s[46:47], 19
	v_lshlrev_b32_e32 v0, 3, v0
	v_and_b32_e32 v1, 0xfffffc00, v1
	s_add_u32 s48, s3, s48
	v_and_or_b32 v0, v0, 56, v1
	s_addc_u32 s49, s54, s49
	s_lshl_b32 s21, s61, 19
	v_ashrrev_i32_e32 v1, 31, v0
	v_lshl_add_u32 v140, v6, 4, 0
	s_add_u32 s50, s34, s21
	v_lshlrev_b64 v[0:1], 1, v[0:1]
	v_readfirstlane_b32 s21, v140
	v_add_u32_e32 v9, 0x2000, v140
	v_lshl_add_u64 v[2:3], s[48:49], 0, v[0:1]
	s_mov_b32 m0, s21
	v_readfirstlane_b32 s21, v9
	v_add_u32_e32 v9, 0x4000, v140
	s_barrier
	global_load_lds_dwordx4 v[2:3], off
	v_lshl_add_u64 v[4:5], v[2:3], 0, s[6:7]
	s_mov_b32 m0, s21
	v_readfirstlane_b32 s21, v9
	global_load_lds_dwordx4 v[4:5], off
	v_lshl_add_u64 v[4:5], v[2:3], 0, s[8:9]
	s_mov_b32 m0, s21
	v_lshl_add_u64 v[2:3], v[2:3], 0, s[10:11]
	global_load_lds_dwordx4 v[4:5], off
	v_add_u32_e32 v4, 0x6000, v140
	s_addc_u32 s51, s35, 0
	v_readfirstlane_b32 s21, v4
	s_mov_b32 m0, s21
	v_add_u32_e32 v4, 0xa000, v140
	global_load_lds_dwordx4 v[2:3], off
	v_add_u32_e32 v2, 0x8000, v140
	v_lshl_add_u64 v[132:133], s[50:51], 0, v[0:1]
	v_readfirstlane_b32 s21, v2
	s_mov_b32 m0, s21
	v_readfirstlane_b32 s21, v4
	v_add_u32_e32 v4, 0xc000, v140
	global_load_lds_dwordx4 v[132:133], off
	v_lshl_add_u64 v[2:3], v[132:133], 0, s[6:7]
	s_mov_b32 m0, s21
	v_readfirstlane_b32 s21, v4
	v_add_u32_e32 v4, 0xe000, v140
	global_load_lds_dwordx4 v[2:3], off
	v_lshl_add_u64 v[2:3], v[132:133], 0, s[8:9]
	s_mov_b32 m0, s21
	v_readfirstlane_b32 s21, v4
	global_load_lds_dwordx4 v[2:3], off
	v_lshl_add_u64 v[2:3], v[132:133], 0, s[10:11]
	s_mov_b32 m0, s21
	v_ashrrev_i32_e32 v4, 6, v6
	global_load_lds_dwordx4 v[2:3], off
	v_lshrrev_b32_e32 v5, 30, v4
	v_add_u32_e32 v5, v4, v5
	s_or_b32 s48, s62, s20
	v_bfe_u32 v2, v6, 4, 2
	v_bfe_u32 v3, v6, 1, 3
	v_and_b32_e32 v6, 0x7fffc, v5
	s_ashr_i32 s49, s48, 31
	v_sub_u32_e32 v4, v4, v6
	s_lshl_b64 s[48:49], s[48:49], 19
	v_lshlrev_b32_e32 v142, 13, v4
	v_bitop3_b32 v4, v7, v3, 3 bitop3:0x6c
	v_bitop3_b32 v2, v2, v3, 4 bitop3:0x36
	s_add_u32 s48, s34, s48
	v_lshlrev_b32_e32 v5, 12, v5
	v_lshlrev_b32_e32 v4, 3, v4
	v_lshlrev_b32_e32 v2, 3, v2
	s_addc_u32 s49, s35, s49
	v_and_b32_e32 v141, 0xffffc000, v5
	v_lshl_add_u64 v[134:135], s[48:49], 0, v[0:1]
	s_mov_b64 s[48:49], 0
	v_lshlrev_b32_e32 v143, 1, v8
	v_lshlrev_b32_e32 v144, 1, v4
	v_lshlrev_b32_e32 v145, 1, v2
	s_mov_b32 s62, 0
	s_mov_b32 s47, 0
	v_mov_b32_e32 v40, 0
	v_mov_b32_e32 v41, v129
	v_mov_b32_e32 v42, v129
	v_mov_b32_e32 v43, v129
	v_mov_b32_e32 v48, 0
	v_mov_b32_e32 v49, v129
	v_mov_b32_e32 v50, v129
	v_mov_b32_e32 v51, v129
	v_mov_b32_e32 v0, 0
	v_mov_b32_e32 v1, v129
	v_mov_b32_e32 v2, v129
	v_mov_b32_e32 v3, v129
	v_mov_b32_e32 v4, 0
	v_mov_b32_e32 v5, v129
	v_mov_b32_e32 v6, v129
	v_mov_b32_e32 v7, v129
	v_mov_b32_e32 v8, 0
	v_mov_b32_e32 v9, v129
	v_mov_b32_e32 v10, v129
	v_mov_b32_e32 v11, v129
	v_mov_b32_e32 v12, 0
	v_mov_b32_e32 v13, v129
	v_mov_b32_e32 v14, v129
	v_mov_b32_e32 v15, v129
	v_mov_b32_e32 v16, 0
	v_mov_b32_e32 v17, v129
	v_mov_b32_e32 v18, v129
	v_mov_b32_e32 v19, v129
	v_mov_b32_e32 v20, 0
	v_mov_b32_e32 v21, v129
	v_mov_b32_e32 v22, v129
	v_mov_b32_e32 v23, v129
	v_mov_b32_e32 v24, 0
	v_mov_b32_e32 v25, v129
	v_mov_b32_e32 v26, v129
	v_mov_b32_e32 v27, v129
	v_mov_b32_e32 v28, 0
	v_mov_b32_e32 v29, v129
	v_mov_b32_e32 v30, v129
	v_mov_b32_e32 v31, v129
	v_mov_b32_e32 v32, 0
	v_mov_b32_e32 v33, v129
	v_mov_b32_e32 v34, v129
	v_mov_b32_e32 v35, v129
	v_mov_b32_e32 v36, 0
	v_mov_b32_e32 v37, v129
	v_mov_b32_e32 v38, v129
	v_mov_b32_e32 v39, v129
	v_mov_b32_e32 v44, 0
	v_mov_b32_e32 v45, v129
	v_mov_b32_e32 v46, v129
	v_mov_b32_e32 v47, v129
	v_mov_b32_e32 v52, 0
	v_mov_b32_e32 v53, v129
	v_mov_b32_e32 v54, v129
	v_mov_b32_e32 v55, v129
	v_mov_b32_e32 v56, 0
	v_mov_b32_e32 v57, v129
	v_mov_b32_e32 v58, v129
	v_mov_b32_e32 v59, v129
	v_mov_b32_e32 v60, 0
	v_mov_b32_e32 v61, v129
	v_mov_b32_e32 v62, v129
	v_mov_b32_e32 v63, v129
	v_mov_b32_e32 v64, 0
	v_mov_b32_e32 v65, v129
	v_mov_b32_e32 v66, v129
	v_mov_b32_e32 v67, v129
	v_mov_b32_e32 v68, 0
	v_mov_b32_e32 v69, v129
	v_mov_b32_e32 v70, v129
	v_mov_b32_e32 v71, v129
	v_mov_b32_e32 v72, 0
	v_mov_b32_e32 v73, v129
	v_mov_b32_e32 v74, v129
	v_mov_b32_e32 v75, v129
	v_mov_b32_e32 v76, 0
	v_mov_b32_e32 v77, v129
	v_mov_b32_e32 v78, v129
	v_mov_b32_e32 v79, v129
	v_mov_b32_e32 v80, 0
	v_mov_b32_e32 v81, v129
	v_mov_b32_e32 v82, v129
	v_mov_b32_e32 v83, v129
	v_mov_b32_e32 v84, 0
	v_mov_b32_e32 v85, v129
	v_mov_b32_e32 v86, v129
	v_mov_b32_e32 v87, v129
	v_mov_b32_e32 v88, 0
	v_mov_b32_e32 v89, v129
	v_mov_b32_e32 v90, v129
	v_mov_b32_e32 v91, v129
	v_mov_b32_e32 v92, 0
	v_mov_b32_e32 v93, v129
	v_mov_b32_e32 v94, v129
	v_mov_b32_e32 v95, v129
	v_mov_b32_e32 v96, 0
	v_mov_b32_e32 v97, v129
	v_mov_b32_e32 v98, v129
	v_mov_b32_e32 v99, v129
	v_mov_b32_e32 v100, 0
	v_mov_b32_e32 v101, v129
	v_mov_b32_e32 v102, v129
	v_mov_b32_e32 v103, v129
	v_mov_b32_e32 v104, 0
	v_mov_b32_e32 v105, v129
	v_mov_b32_e32 v106, v129
	v_mov_b32_e32 v107, v129
	v_mov_b32_e32 v108, 0
	v_mov_b32_e32 v109, v129
	v_mov_b32_e32 v110, v129
	v_mov_b32_e32 v111, v129
	v_mov_b32_e32 v112, 0
	v_mov_b32_e32 v113, v129
	v_mov_b32_e32 v114, v129
	v_mov_b32_e32 v115, v129
	v_mov_b32_e32 v116, 0
	v_mov_b32_e32 v117, v129
	v_mov_b32_e32 v118, v129
	v_mov_b32_e32 v119, v129
	v_mov_b32_e32 v120, 0
	v_mov_b32_e32 v121, v129
	v_mov_b32_e32 v122, v129
	v_mov_b32_e32 v123, v129
	v_mov_b32_e32 v124, 0
	v_mov_b32_e32 v125, v129
	v_mov_b32_e32 v126, v129
	v_mov_b32_e32 v127, v129
	s_waitcnt vmcnt(0) lgkmcnt(0)
	s_barrier
	v_add3_u32 v180, v141, v143, v144
	v_add3_u32 v215, v142, v143, v144
	v_add3_u32 v214, v141, v143, v145
	v_add3_u32 v216, v142, v143, v145
	v_xor_b32_e32 v217, 0x10000, v180
	v_xor_b32_e32 v218, 0x10000, v214
	v_xor_b32_e32 v219, 0x10000, v215
	v_xor_b32_e32 v220, 0x10000, v216
	v_readfirstlane_b32 s62, v140
	ds_read_b128 v[146:149], v180
	ds_read_b128 v[150:153], v180 offset:2048
	ds_read_b128 v[154:157], v180 offset:4096
	ds_read_b128 v[158:161], v180 offset:6144
	ds_read_b128 v[182:185], v215 offset:32768
	ds_read_b128 v[186:189], v215 offset:34816
	ds_read_b128 v[190:193], v215 offset:36864
	ds_read_b128 v[194:197], v215 offset:38912
	s_mov_b32 s47, 0
	s_mov_b64 s[48:49], s[34:35]
	v_subrev_u32_e32 v178, s34, v134
	v_subrev_u32_e32 v179, s34, v132
	s_add_u32 s62, s62, 0x10000
	s_mov_b32 m0, s62
	s_add_u32 s50, s48, s12
	s_addc_u32 s51, s49, s13
	global_load_lds_dwordx4 v178, s[50:51]
	s_add_u32 m0, s62, 0x2000
	s_add_u32 s50, s48, s14
	s_addc_u32 s51, s49, s15
	global_load_lds_dwordx4 v178, s[50:51]
	s_add_u32 m0, s62, 0x4000
	s_add_u32 s50, s48, s16
	s_addc_u32 s51, s49, s17
	global_load_lds_dwordx4 v178, s[50:51]
	s_add_u32 m0, s62, 0x6000
	s_add_u32 s50, s48, s18
	s_addc_u32 s51, s49, s19
	global_load_lds_dwordx4 v178, s[50:51]
	s_add_u32 m0, s62, 0x8000
	s_add_u32 s50, s48, s22
	s_addc_u32 s51, s49, s23
	global_load_lds_dwordx4 v179, s[50:51]
	s_add_u32 m0, s62, 0xa000
	s_add_u32 s50, s48, s36
	s_addc_u32 s51, s49, s37
	global_load_lds_dwordx4 v179, s[50:51]
	s_add_u32 m0, s62, 0xc000
	s_add_u32 s50, s48, s40
	s_addc_u32 s51, s49, s41
	global_load_lds_dwordx4 v179, s[50:51]
	s_add_u32 m0, s62, 0xe000
	s_add_u32 s50, s48, s42
	s_addc_u32 s51, s49, s43
	global_load_lds_dwordx4 v179, s[50:51]
	s_branch .Lg2_entry
.Lg2_top:
	s_waitcnt lgkmcnt(0)
	s_waitcnt vmcnt(0)
	s_barrier
	s_xor_b32 s62, s62, 0x10000
	ds_read_b128 v[146:149], v180
	ds_read_b128 v[150:153], v180 offset:2048
	ds_read_b128 v[154:157], v180 offset:4096
	ds_read_b128 v[158:161], v180 offset:6144
	ds_read_b128 v[182:185], v215 offset:32768
	ds_read_b128 v[186:189], v215 offset:34816
	ds_read_b128 v[190:193], v215 offset:36864
	ds_read_b128 v[194:197], v215 offset:38912
	v_mfma_f32_16x16x32_bf16 v[60:63], v[162:165], v[198:201], v[60:63]
	v_mfma_f32_16x16x32_bf16 v[56:59], v[162:165], v[202:205], v[56:59]
	s_mov_b32 m0, s62
	s_add_u32 s50, s48, s12
	s_addc_u32 s51, s49, s13
	global_load_lds_dwordx4 v178, s[50:51]
	v_mfma_f32_16x16x32_bf16 v[52:55], v[162:165], v[206:209], v[52:55]
	v_mfma_f32_16x16x32_bf16 v[44:47], v[162:165], v[210:213], v[44:47]
	s_add_u32 m0, s62, 0x2000
	s_add_u32 s50, s48, s14
	s_addc_u32 s51, s49, s15
	global_load_lds_dwordx4 v178, s[50:51]
	v_mfma_f32_16x16x32_bf16 v[36:39], v[166:169], v[198:201], v[36:39]
	v_mfma_f32_16x16x32_bf16 v[32:35], v[166:169], v[202:205], v[32:35]
	s_add_u32 m0, s62, 0x4000
	s_add_u32 s50, s48, s16
	s_addc_u32 s51, s49, s17
	global_load_lds_dwordx4 v178, s[50:51]
	v_mfma_f32_16x16x32_bf16 v[28:31], v[166:169], v[206:209], v[28:31]
	v_mfma_f32_16x16x32_bf16 v[24:27], v[166:169], v[210:213], v[24:27]
	s_add_u32 m0, s62, 0x6000
	s_add_u32 s50, s48, s18
	s_addc_u32 s51, s49, s19
	global_load_lds_dwordx4 v178, s[50:51]
	v_mfma_f32_16x16x32_bf16 v[20:23], v[170:173], v[198:201], v[20:23]
	v_mfma_f32_16x16x32_bf16 v[16:19], v[170:173], v[202:205], v[16:19]
	s_add_u32 m0, s62, 0x8000
	s_add_u32 s50, s48, s22
	s_addc_u32 s51, s49, s23
	global_load_lds_dwordx4 v179, s[50:51]
	v_mfma_f32_16x16x32_bf16 v[12:15], v[170:173], v[206:209], v[12:15]
	v_mfma_f32_16x16x32_bf16 v[8:11], v[170:173], v[210:213], v[8:11]
	s_add_u32 m0, s62, 0xa000
	s_add_u32 s50, s48, s36
	s_addc_u32 s51, s49, s37
	global_load_lds_dwordx4 v179, s[50:51]
	v_mfma_f32_16x16x32_bf16 v[4:7], v[174:177], v[198:201], v[4:7]
	v_mfma_f32_16x16x32_bf16 v[0:3], v[174:177], v[202:205], v[0:3]
	s_add_u32 m0, s62, 0xc000
	s_add_u32 s50, s48, s40
	s_addc_u32 s51, s49, s41
	global_load_lds_dwordx4 v179, s[50:51]
	v_mfma_f32_16x16x32_bf16 v[48:51], v[174:177], v[206:209], v[48:51]
	v_mfma_f32_16x16x32_bf16 v[40:43], v[174:177], v[210:213], v[40:43]
	s_add_u32 m0, s62, 0xe000
	s_add_u32 s50, s48, s42
	s_addc_u32 s51, s49, s43
	global_load_lds_dwordx4 v179, s[50:51]
.Lg2_entry:
	ds_read_b128 v[162:165], v180 offset:8192
	ds_read_b128 v[166:169], v180 offset:10240
	ds_read_b128 v[170:173], v180 offset:12288
	ds_read_b128 v[174:177], v180 offset:14336
	s_waitcnt lgkmcnt(4)
	v_mfma_f32_16x16x32_bf16 v[124:127], v[146:149], v[182:185], v[124:127]
	v_mfma_f32_16x16x32_bf16 v[120:123], v[146:149], v[186:189], v[120:123]
	v_mfma_f32_16x16x32_bf16 v[116:119], v[146:149], v[190:193], v[116:119]
	v_mfma_f32_16x16x32_bf16 v[112:115], v[146:149], v[194:197], v[112:115]
	v_mfma_f32_16x16x32_bf16 v[108:111], v[150:153], v[182:185], v[108:111]
	v_mfma_f32_16x16x32_bf16 v[104:107], v[150:153], v[186:189], v[104:107]
	v_mfma_f32_16x16x32_bf16 v[100:103], v[150:153], v[190:193], v[100:103]
	v_mfma_f32_16x16x32_bf16 v[96:99], v[150:153], v[194:197], v[96:99]
	v_mfma_f32_16x16x32_bf16 v[92:95], v[154:157], v[182:185], v[92:95]
	v_mfma_f32_16x16x32_bf16 v[88:91], v[154:157], v[186:189], v[88:91]
	v_mfma_f32_16x16x32_bf16 v[84:87], v[154:157], v[190:193], v[84:87]
	v_mfma_f32_16x16x32_bf16 v[80:83], v[154:157], v[194:197], v[80:83]
	v_mfma_f32_16x16x32_bf16 v[76:79], v[158:161], v[182:185], v[76:79]
	v_mfma_f32_16x16x32_bf16 v[72:75], v[158:161], v[186:189], v[72:75]
	v_mfma_f32_16x16x32_bf16 v[68:71], v[158:161], v[190:193], v[68:71]
	v_mfma_f32_16x16x32_bf16 v[64:67], v[158:161], v[194:197], v[64:67]
	ds_read_b128 v[146:149], v214
	ds_read_b128 v[150:153], v214 offset:2048
	ds_read_b128 v[154:157], v214 offset:4096
	ds_read_b128 v[158:161], v214 offset:6144
	ds_read_b128 v[198:201], v216 offset:32768
	ds_read_b128 v[202:205], v216 offset:34816
	ds_read_b128 v[206:209], v216 offset:36864
	ds_read_b128 v[210:213], v216 offset:38912
	s_waitcnt lgkmcnt(8)
	v_mfma_f32_16x16x32_bf16 v[60:63], v[162:165], v[182:185], v[60:63]
	v_mfma_f32_16x16x32_bf16 v[56:59], v[162:165], v[186:189], v[56:59]
	v_mfma_f32_16x16x32_bf16 v[52:55], v[162:165], v[190:193], v[52:55]
	v_mfma_f32_16x16x32_bf16 v[44:47], v[162:165], v[194:197], v[44:47]
	v_mfma_f32_16x16x32_bf16 v[36:39], v[166:169], v[182:185], v[36:39]
	v_mfma_f32_16x16x32_bf16 v[32:35], v[166:169], v[186:189], v[32:35]
	v_mfma_f32_16x16x32_bf16 v[28:31], v[166:169], v[190:193], v[28:31]
	v_mfma_f32_16x16x32_bf16 v[24:27], v[166:169], v[194:197], v[24:27]
	v_mfma_f32_16x16x32_bf16 v[20:23], v[170:173], v[182:185], v[20:23]
	v_mfma_f32_16x16x32_bf16 v[16:19], v[170:173], v[186:189], v[16:19]
	v_mfma_f32_16x16x32_bf16 v[12:15], v[170:173], v[190:193], v[12:15]
	v_mfma_f32_16x16x32_bf16 v[8:11], v[170:173], v[194:197], v[8:11]
	v_mfma_f32_16x16x32_bf16 v[4:7], v[174:177], v[182:185], v[4:7]
	v_mfma_f32_16x16x32_bf16 v[0:3], v[174:177], v[186:189], v[0:3]
	v_mfma_f32_16x16x32_bf16 v[48:51], v[174:177], v[190:193], v[48:51]
	v_mfma_f32_16x16x32_bf16 v[40:43], v[174:177], v[194:197], v[40:43]
	ds_read_b128 v[162:165], v214 offset:8192
	ds_read_b128 v[166:169], v214 offset:10240
	ds_read_b128 v[170:173], v214 offset:12288
	ds_read_b128 v[174:177], v214 offset:14336
	s_waitcnt lgkmcnt(4)
	v_mfma_f32_16x16x32_bf16 v[124:127], v[146:149], v[198:201], v[124:127]
	v_mfma_f32_16x16x32_bf16 v[120:123], v[146:149], v[202:205], v[120:123]
	v_mfma_f32_16x16x32_bf16 v[116:119], v[146:149], v[206:209], v[116:119]
	v_mfma_f32_16x16x32_bf16 v[112:115], v[146:149], v[210:213], v[112:115]
	v_mfma_f32_16x16x32_bf16 v[108:111], v[150:153], v[198:201], v[108:111]
	v_mfma_f32_16x16x32_bf16 v[104:107], v[150:153], v[202:205], v[104:107]
	v_mfma_f32_16x16x32_bf16 v[100:103], v[150:153], v[206:209], v[100:103]
	v_mfma_f32_16x16x32_bf16 v[96:99], v[150:153], v[210:213], v[96:99]
	v_mfma_f32_16x16x32_bf16 v[92:95], v[154:157], v[198:201], v[92:95]
	v_mfma_f32_16x16x32_bf16 v[88:91], v[154:157], v[202:205], v[88:91]
	v_mfma_f32_16x16x32_bf16 v[84:87], v[154:157], v[206:209], v[84:87]
	v_mfma_f32_16x16x32_bf16 v[80:83], v[154:157], v[210:213], v[80:83]
	v_mfma_f32_16x16x32_bf16 v[76:79], v[158:161], v[198:201], v[76:79]
	v_mfma_f32_16x16x32_bf16 v[72:75], v[158:161], v[202:205], v[72:75]
	v_mfma_f32_16x16x32_bf16 v[68:71], v[158:161], v[206:209], v[68:71]
	v_mfma_f32_16x16x32_bf16 v[64:67], v[158:161], v[210:213], v[64:67]
	s_add_u32 s48, s48, 0x80
	s_addc_u32 s49, s49, 0
	s_add_i32 s47, s47, 1
	s_cmp_lt_u32 s47, 15
	s_cbranch_scc0 .Lg2_last
	s_waitcnt lgkmcnt(0)
	s_waitcnt vmcnt(0)
	s_barrier
	s_xor_b32 s62, s62, 0x10000
	ds_read_b128 v[146:149], v217
	ds_read_b128 v[150:153], v217 offset:2048
	ds_read_b128 v[154:157], v217 offset:4096
	ds_read_b128 v[158:161], v217 offset:6144
	ds_read_b128 v[182:185], v219 offset:32768
	ds_read_b128 v[186:189], v219 offset:34816
	ds_read_b128 v[190:193], v219 offset:36864
	ds_read_b128 v[194:197], v219 offset:38912
	v_mfma_f32_16x16x32_bf16 v[60:63], v[162:165], v[198:201], v[60:63]
	v_mfma_f32_16x16x32_bf16 v[56:59], v[162:165], v[202:205], v[56:59]
	s_mov_b32 m0, s62
	s_add_u32 s50, s48, s12
	s_addc_u32 s51, s49, s13
	global_load_lds_dwordx4 v178, s[50:51]
	v_mfma_f32_16x16x32_bf16 v[52:55], v[162:165], v[206:209], v[52:55]
	v_mfma_f32_16x16x32_bf16 v[44:47], v[162:165], v[210:213], v[44:47]
	s_add_u32 m0, s62, 0x2000
	s_add_u32 s50, s48, s14
	s_addc_u32 s51, s49, s15
	global_load_lds_dwordx4 v178, s[50:51]
	v_mfma_f32_16x16x32_bf16 v[36:39], v[166:169], v[198:201], v[36:39]
	v_mfma_f32_16x16x32_bf16 v[32:35], v[166:169], v[202:205], v[32:35]
	s_add_u32 m0, s62, 0x4000
	s_add_u32 s50, s48, s16
	s_addc_u32 s51, s49, s17
	global_load_lds_dwordx4 v178, s[50:51]
	v_mfma_f32_16x16x32_bf16 v[28:31], v[166:169], v[206:209], v[28:31]
	v_mfma_f32_16x16x32_bf16 v[24:27], v[166:169], v[210:213], v[24:27]
	s_add_u32 m0, s62, 0x6000
	s_add_u32 s50, s48, s18
	s_addc_u32 s51, s49, s19
	global_load_lds_dwordx4 v178, s[50:51]
	v_mfma_f32_16x16x32_bf16 v[20:23], v[170:173], v[198:201], v[20:23]
	v_mfma_f32_16x16x32_bf16 v[16:19], v[170:173], v[202:205], v[16:19]
	s_add_u32 m0, s62, 0x8000
	s_add_u32 s50, s48, s22
	s_addc_u32 s51, s49, s23
	global_load_lds_dwordx4 v179, s[50:51]
	v_mfma_f32_16x16x32_bf16 v[12:15], v[170:173], v[206:209], v[12:15]
	v_mfma_f32_16x16x32_bf16 v[8:11], v[170:173], v[210:213], v[8:11]
	s_add_u32 m0, s62, 0xa000
	s_add_u32 s50, s48, s36
	s_addc_u32 s51, s49, s37
	global_load_lds_dwordx4 v179, s[50:51]
	v_mfma_f32_16x16x32_bf16 v[4:7], v[174:177], v[198:201], v[4:7]
	v_mfma_f32_16x16x32_bf16 v[0:3], v[174:177], v[202:205], v[0:3]
	s_add_u32 m0, s62, 0xc000
	s_add_u32 s50, s48, s40
	s_addc_u32 s51, s49, s41
	global_load_lds_dwordx4 v179, s[50:51]
	v_mfma_f32_16x16x32_bf16 v[48:51], v[174:177], v[206:209], v[48:51]
	v_mfma_f32_16x16x32_bf16 v[40:43], v[174:177], v[210:213], v[40:43]
	s_add_u32 m0, s62, 0xe000
	s_add_u32 s50, s48, s42
	s_addc_u32 s51, s49, s43
	global_load_lds_dwordx4 v179, s[50:51]
	ds_read_b128 v[162:165], v217 offset:8192
	ds_read_b128 v[166:169], v217 offset:10240
	ds_read_b128 v[170:173], v217 offset:12288
	ds_read_b128 v[174:177], v217 offset:14336
	s_waitcnt lgkmcnt(4)
	v_mfma_f32_16x16x32_bf16 v[124:127], v[146:149], v[182:185], v[124:127]
	v_mfma_f32_16x16x32_bf16 v[120:123], v[146:149], v[186:189], v[120:123]
	v_mfma_f32_16x16x32_bf16 v[116:119], v[146:149], v[190:193], v[116:119]
	v_mfma_f32_16x16x32_bf16 v[112:115], v[146:149], v[194:197], v[112:115]
	v_mfma_f32_16x16x32_bf16 v[108:111], v[150:153], v[182:185], v[108:111]
	v_mfma_f32_16x16x32_bf16 v[104:107], v[150:153], v[186:189], v[104:107]
	v_mfma_f32_16x16x32_bf16 v[100:103], v[150:153], v[190:193], v[100:103]
	v_mfma_f32_16x16x32_bf16 v[96:99], v[150:153], v[194:197], v[96:99]
	v_mfma_f32_16x16x32_bf16 v[92:95], v[154:157], v[182:185], v[92:95]
	v_mfma_f32_16x16x32_bf16 v[88:91], v[154:157], v[186:189], v[88:91]
	v_mfma_f32_16x16x32_bf16 v[84:87], v[154:157], v[190:193], v[84:87]
	v_mfma_f32_16x16x32_bf16 v[80:83], v[154:157], v[194:197], v[80:83]
	v_mfma_f32_16x16x32_bf16 v[76:79], v[158:161], v[182:185], v[76:79]
	v_mfma_f32_16x16x32_bf16 v[72:75], v[158:161], v[186:189], v[72:75]
	v_mfma_f32_16x16x32_bf16 v[68:71], v[158:161], v[190:193], v[68:71]
	v_mfma_f32_16x16x32_bf16 v[64:67], v[158:161], v[194:197], v[64:67]
	ds_read_b128 v[146:149], v218
	ds_read_b128 v[150:153], v218 offset:2048
	ds_read_b128 v[154:157], v218 offset:4096
	ds_read_b128 v[158:161], v218 offset:6144
	ds_read_b128 v[198:201], v220 offset:32768
	ds_read_b128 v[202:205], v220 offset:34816
	ds_read_b128 v[206:209], v220 offset:36864
	ds_read_b128 v[210:213], v220 offset:38912
	s_waitcnt lgkmcnt(8)
	v_mfma_f32_16x16x32_bf16 v[60:63], v[162:165], v[182:185], v[60:63]
	v_mfma_f32_16x16x32_bf16 v[56:59], v[162:165], v[186:189], v[56:59]
	v_mfma_f32_16x16x32_bf16 v[52:55], v[162:165], v[190:193], v[52:55]
	v_mfma_f32_16x16x32_bf16 v[44:47], v[162:165], v[194:197], v[44:47]
	v_mfma_f32_16x16x32_bf16 v[36:39], v[166:169], v[182:185], v[36:39]
	v_mfma_f32_16x16x32_bf16 v[32:35], v[166:169], v[186:189], v[32:35]
	v_mfma_f32_16x16x32_bf16 v[28:31], v[166:169], v[190:193], v[28:31]
	v_mfma_f32_16x16x32_bf16 v[24:27], v[166:169], v[194:197], v[24:27]
	v_mfma_f32_16x16x32_bf16 v[20:23], v[170:173], v[182:185], v[20:23]
	v_mfma_f32_16x16x32_bf16 v[16:19], v[170:173], v[186:189], v[16:19]
	v_mfma_f32_16x16x32_bf16 v[12:15], v[170:173], v[190:193], v[12:15]
	v_mfma_f32_16x16x32_bf16 v[8:11], v[170:173], v[194:197], v[8:11]
	v_mfma_f32_16x16x32_bf16 v[4:7], v[174:177], v[182:185], v[4:7]
	v_mfma_f32_16x16x32_bf16 v[0:3], v[174:177], v[186:189], v[0:3]
	v_mfma_f32_16x16x32_bf16 v[48:51], v[174:177], v[190:193], v[48:51]
	v_mfma_f32_16x16x32_bf16 v[40:43], v[174:177], v[194:197], v[40:43]
	ds_read_b128 v[162:165], v218 offset:8192
	ds_read_b128 v[166:169], v218 offset:10240
	ds_read_b128 v[170:173], v218 offset:12288
	ds_read_b128 v[174:177], v218 offset:14336
	s_waitcnt lgkmcnt(4)
	v_mfma_f32_16x16x32_bf16 v[124:127], v[146:149], v[198:201], v[124:127]
	v_mfma_f32_16x16x32_bf16 v[120:123], v[146:149], v[202:205], v[120:123]
	v_mfma_f32_16x16x32_bf16 v[116:119], v[146:149], v[206:209], v[116:119]
	v_mfma_f32_16x16x32_bf16 v[112:115], v[146:149], v[210:213], v[112:115]
	v_mfma_f32_16x16x32_bf16 v[108:111], v[150:153], v[198:201], v[108:111]
	v_mfma_f32_16x16x32_bf16 v[104:107], v[150:153], v[202:205], v[104:107]
	v_mfma_f32_16x16x32_bf16 v[100:103], v[150:153], v[206:209], v[100:103]
	v_mfma_f32_16x16x32_bf16 v[96:99], v[150:153], v[210:213], v[96:99]
	v_mfma_f32_16x16x32_bf16 v[92:95], v[154:157], v[198:201], v[92:95]
	v_mfma_f32_16x16x32_bf16 v[88:91], v[154:157], v[202:205], v[88:91]
	v_mfma_f32_16x16x32_bf16 v[84:87], v[154:157], v[206:209], v[84:87]
	v_mfma_f32_16x16x32_bf16 v[80:83], v[154:157], v[210:213], v[80:83]
	v_mfma_f32_16x16x32_bf16 v[76:79], v[158:161], v[198:201], v[76:79]
	v_mfma_f32_16x16x32_bf16 v[72:75], v[158:161], v[202:205], v[72:75]
	v_mfma_f32_16x16x32_bf16 v[68:71], v[158:161], v[206:209], v[68:71]
	v_mfma_f32_16x16x32_bf16 v[64:67], v[158:161], v[210:213], v[64:67]
	s_add_u32 s48, s48, 0x80
	s_addc_u32 s49, s49, 0
	s_add_i32 s47, s47, 1
	s_branch .Lg2_top
.Lg2_last:
	s_waitcnt lgkmcnt(0)
	s_waitcnt vmcnt(0)
	s_barrier
	s_xor_b32 s62, s62, 0x10000
	ds_read_b128 v[146:149], v217
	ds_read_b128 v[150:153], v217 offset:2048
	ds_read_b128 v[154:157], v217 offset:4096
	ds_read_b128 v[158:161], v217 offset:6144
	ds_read_b128 v[182:185], v219 offset:32768
	ds_read_b128 v[186:189], v219 offset:34816
	ds_read_b128 v[190:193], v219 offset:36864
	ds_read_b128 v[194:197], v219 offset:38912
	v_mfma_f32_16x16x32_bf16 v[60:63], v[162:165], v[198:201], v[60:63]
	v_mfma_f32_16x16x32_bf16 v[56:59], v[162:165], v[202:205], v[56:59]
	v_mfma_f32_16x16x32_bf16 v[52:55], v[162:165], v[206:209], v[52:55]
	v_mfma_f32_16x16x32_bf16 v[44:47], v[162:165], v[210:213], v[44:47]
	v_mfma_f32_16x16x32_bf16 v[36:39], v[166:169], v[198:201], v[36:39]
	v_mfma_f32_16x16x32_bf16 v[32:35], v[166:169], v[202:205], v[32:35]
	v_mfma_f32_16x16x32_bf16 v[28:31], v[166:169], v[206:209], v[28:31]
	v_mfma_f32_16x16x32_bf16 v[24:27], v[166:169], v[210:213], v[24:27]
	v_mfma_f32_16x16x32_bf16 v[20:23], v[170:173], v[198:201], v[20:23]
	v_mfma_f32_16x16x32_bf16 v[16:19], v[170:173], v[202:205], v[16:19]
	v_mfma_f32_16x16x32_bf16 v[12:15], v[170:173], v[206:209], v[12:15]
	v_mfma_f32_16x16x32_bf16 v[8:11], v[170:173], v[210:213], v[8:11]
	v_mfma_f32_16x16x32_bf16 v[4:7], v[174:177], v[198:201], v[4:7]
	v_mfma_f32_16x16x32_bf16 v[0:3], v[174:177], v[202:205], v[0:3]
	v_mfma_f32_16x16x32_bf16 v[48:51], v[174:177], v[206:209], v[48:51]
	v_mfma_f32_16x16x32_bf16 v[40:43], v[174:177], v[210:213], v[40:43]
	ds_read_b128 v[162:165], v217 offset:8192
	ds_read_b128 v[166:169], v217 offset:10240
	ds_read_b128 v[170:173], v217 offset:12288
	ds_read_b128 v[174:177], v217 offset:14336
	s_waitcnt lgkmcnt(4)
	v_mfma_f32_16x16x32_bf16 v[124:127], v[146:149], v[182:185], v[124:127]
	v_mfma_f32_16x16x32_bf16 v[120:123], v[146:149], v[186:189], v[120:123]
	v_mfma_f32_16x16x32_bf16 v[116:119], v[146:149], v[190:193], v[116:119]
	v_mfma_f32_16x16x32_bf16 v[112:115], v[146:149], v[194:197], v[112:115]
	v_mfma_f32_16x16x32_bf16 v[108:111], v[150:153], v[182:185], v[108:111]
	v_mfma_f32_16x16x32_bf16 v[104:107], v[150:153], v[186:189], v[104:107]
	v_mfma_f32_16x16x32_bf16 v[100:103], v[150:153], v[190:193], v[100:103]
	v_mfma_f32_16x16x32_bf16 v[96:99], v[150:153], v[194:197], v[96:99]
	v_mfma_f32_16x16x32_bf16 v[92:95], v[154:157], v[182:185], v[92:95]
	v_mfma_f32_16x16x32_bf16 v[88:91], v[154:157], v[186:189], v[88:91]
	v_mfma_f32_16x16x32_bf16 v[84:87], v[154:157], v[190:193], v[84:87]
	v_mfma_f32_16x16x32_bf16 v[80:83], v[154:157], v[194:197], v[80:83]
	v_mfma_f32_16x16x32_bf16 v[76:79], v[158:161], v[182:185], v[76:79]
	v_mfma_f32_16x16x32_bf16 v[72:75], v[158:161], v[186:189], v[72:75]
	v_mfma_f32_16x16x32_bf16 v[68:71], v[158:161], v[190:193], v[68:71]
	v_mfma_f32_16x16x32_bf16 v[64:67], v[158:161], v[194:197], v[64:67]
	ds_read_b128 v[146:149], v218
	ds_read_b128 v[150:153], v218 offset:2048
	ds_read_b128 v[154:157], v218 offset:4096
	ds_read_b128 v[158:161], v218 offset:6144
	ds_read_b128 v[198:201], v220 offset:32768
	ds_read_b128 v[202:205], v220 offset:34816
	ds_read_b128 v[206:209], v220 offset:36864
	ds_read_b128 v[210:213], v220 offset:38912
	s_waitcnt lgkmcnt(8)
	v_mfma_f32_16x16x32_bf16 v[60:63], v[162:165], v[182:185], v[60:63]
	v_mfma_f32_16x16x32_bf16 v[56:59], v[162:165], v[186:189], v[56:59]
	v_mfma_f32_16x16x32_bf16 v[52:55], v[162:165], v[190:193], v[52:55]
	v_mfma_f32_16x16x32_bf16 v[44:47], v[162:165], v[194:197], v[44:47]
	v_mfma_f32_16x16x32_bf16 v[36:39], v[166:169], v[182:185], v[36:39]
	v_mfma_f32_16x16x32_bf16 v[32:35], v[166:169], v[186:189], v[32:35]
	v_mfma_f32_16x16x32_bf16 v[28:31], v[166:169], v[190:193], v[28:31]
	v_mfma_f32_16x16x32_bf16 v[24:27], v[166:169], v[194:197], v[24:27]
	v_mfma_f32_16x16x32_bf16 v[20:23], v[170:173], v[182:185], v[20:23]
	v_mfma_f32_16x16x32_bf16 v[16:19], v[170:173], v[186:189], v[16:19]
	v_mfma_f32_16x16x32_bf16 v[12:15], v[170:173], v[190:193], v[12:15]
	v_mfma_f32_16x16x32_bf16 v[8:11], v[170:173], v[194:197], v[8:11]
	v_mfma_f32_16x16x32_bf16 v[4:7], v[174:177], v[182:185], v[4:7]
	v_mfma_f32_16x16x32_bf16 v[0:3], v[174:177], v[186:189], v[0:3]
	v_mfma_f32_16x16x32_bf16 v[48:51], v[174:177], v[190:193], v[48:51]
	v_mfma_f32_16x16x32_bf16 v[40:43], v[174:177], v[194:197], v[40:43]
	ds_read_b128 v[162:165], v218 offset:8192
	ds_read_b128 v[166:169], v218 offset:10240
	ds_read_b128 v[170:173], v218 offset:12288
	ds_read_b128 v[174:177], v218 offset:14336
	s_waitcnt lgkmcnt(4)
	v_mfma_f32_16x16x32_bf16 v[124:127], v[146:149], v[198:201], v[124:127]
	v_mfma_f32_16x16x32_bf16 v[120:123], v[146:149], v[202:205], v[120:123]
	v_mfma_f32_16x16x32_bf16 v[116:119], v[146:149], v[206:209], v[116:119]
	v_mfma_f32_16x16x32_bf16 v[112:115], v[146:149], v[210:213], v[112:115]
	v_mfma_f32_16x16x32_bf16 v[108:111], v[150:153], v[198:201], v[108:111]
	v_mfma_f32_16x16x32_bf16 v[104:107], v[150:153], v[202:205], v[104:107]
	v_mfma_f32_16x16x32_bf16 v[100:103], v[150:153], v[206:209], v[100:103]
	v_mfma_f32_16x16x32_bf16 v[96:99], v[150:153], v[210:213], v[96:99]
	v_mfma_f32_16x16x32_bf16 v[92:95], v[154:157], v[198:201], v[92:95]
	v_mfma_f32_16x16x32_bf16 v[88:91], v[154:157], v[202:205], v[88:91]
	v_mfma_f32_16x16x32_bf16 v[84:87], v[154:157], v[206:209], v[84:87]
	v_mfma_f32_16x16x32_bf16 v[80:83], v[154:157], v[210:213], v[80:83]
	v_mfma_f32_16x16x32_bf16 v[76:79], v[158:161], v[198:201], v[76:79]
	v_mfma_f32_16x16x32_bf16 v[72:75], v[158:161], v[202:205], v[72:75]
	v_mfma_f32_16x16x32_bf16 v[68:71], v[158:161], v[206:209], v[68:71]
	v_mfma_f32_16x16x32_bf16 v[64:67], v[158:161], v[210:213], v[64:67]
	s_add_u32 s48, s48, 0x80
	s_addc_u32 s49, s49, 0
	s_add_i32 s47, s47, 1
	s_waitcnt lgkmcnt(0)
	s_waitcnt vmcnt(0)
	s_barrier
	v_mfma_f32_16x16x32_bf16 v[60:63], v[162:165], v[198:201], v[60:63]
	v_mfma_f32_16x16x32_bf16 v[56:59], v[162:165], v[202:205], v[56:59]
	v_mfma_f32_16x16x32_bf16 v[52:55], v[162:165], v[206:209], v[52:55]
	v_mfma_f32_16x16x32_bf16 v[44:47], v[162:165], v[210:213], v[44:47]
	v_mfma_f32_16x16x32_bf16 v[36:39], v[166:169], v[198:201], v[36:39]
	v_mfma_f32_16x16x32_bf16 v[32:35], v[166:169], v[202:205], v[32:35]
	v_mfma_f32_16x16x32_bf16 v[28:31], v[166:169], v[206:209], v[28:31]
	v_mfma_f32_16x16x32_bf16 v[24:27], v[166:169], v[210:213], v[24:27]
	v_mfma_f32_16x16x32_bf16 v[20:23], v[170:173], v[198:201], v[20:23]
	v_mfma_f32_16x16x32_bf16 v[16:19], v[170:173], v[202:205], v[16:19]
	v_mfma_f32_16x16x32_bf16 v[12:15], v[170:173], v[206:209], v[12:15]
	v_mfma_f32_16x16x32_bf16 v[8:11], v[170:173], v[210:213], v[8:11]
	v_mfma_f32_16x16x32_bf16 v[4:7], v[174:177], v[198:201], v[4:7]
	v_mfma_f32_16x16x32_bf16 v[0:3], v[174:177], v[202:205], v[0:3]
	v_mfma_f32_16x16x32_bf16 v[48:51], v[174:177], v[206:209], v[48:51]
	v_mfma_f32_16x16x32_bf16 v[40:43], v[174:177], v[210:213], v[40:43]
	s_nop 7
	s_nop 7
	s_sub_u32 s48, s48, s34
	s_subb_u32 s49, s49, s35
	s_mov_b32 s62, 0x80000
	s_mov_b32 s63, 0x80000
	s_mov_b64 s[50:51], 0
	s_mov_b64 vcc, exec
	s_branch .LBB0_458

.LBB0_660:
	s_ashr_i32 s96, s94, 3
	s_and_b32 s21, s94, 7
	s_and_b32 s70, s96, -8
	s_or_b32 s64, s70, s21
	s_lshl_b32 s20, s91, 11
	s_ashr_i32 s65, s64, 31
	v_mov_b32_e32 v6, v181
	s_and_b32 s97, s93, 7
	s_bfe_u32 s6, s91, 0x30008
	s_and_b32 s20, s20, 0x380000
	s_lshl_b64 s[66:67], s[64:65], 19
	s_add_u32 s66, s3, s66
	v_lshrrev_b32_e32 v7, 4, v6
	v_lshlrev_b32_e32 v1, 6, v6
	v_xor_b32_e32 v0, v7, v6
	v_and_b32_e32 v8, 0x3c0, v1
	v_lshlrev_b32_e32 v1, 7, v6
	s_addc_u32 s67, s72, s67
	s_lshl_b32 s21, s94, 5
	v_lshlrev_b32_e32 v0, 3, v0
	v_and_b32_e32 v1, 0xfffffc00, v1
	s_and_b32 s95, s21, 0x700
	v_and_or_b32 v0, v0, 56, v1
	s_lshl_b32 s21, s95, 11
	v_ashrrev_i32_e32 v1, 31, v0
	v_lshl_add_u32 v142, v6, 4, 0
	s_add_u32 s68, s73, s21
	v_lshlrev_b64 v[0:1], 1, v[0:1]
	v_readfirstlane_b32 s21, v142
	v_add_u32_e32 v9, 0x2000, v142
	v_lshl_add_u64 v[2:3], s[66:67], 0, v[0:1]
	s_mov_b32 m0, s21
	v_readfirstlane_b32 s21, v9
	v_add_u32_e32 v9, 0x4000, v142
	s_waitcnt vmcnt(63) expcnt(7) lgkmcnt(15)
	s_barrier
	global_load_lds_dwordx4 v[2:3], off
	v_lshl_add_u64 v[4:5], v[2:3], 0, s[8:9]
	s_mov_b32 m0, s21
	v_readfirstlane_b32 s21, v9
	global_load_lds_dwordx4 v[4:5], off
	v_lshl_add_u64 v[4:5], v[2:3], 0, s[10:11]
	s_mov_b32 m0, s21
	s_addc_u32 s69, s74, 0
	global_load_lds_dwordx4 v[4:5], off
	v_add_u32_e32 v4, 0x6000, v142
	v_lshl_add_u64 v[2:3], v[2:3], 0, s[12:13]
	v_readfirstlane_b32 s21, v4
	v_add_u32_e32 v4, 0x8000, v142
	s_mov_b32 m0, s21
	v_readfirstlane_b32 s21, v4
	v_add_u32_e32 v9, 0xa000, v142
	global_load_lds_dwordx4 v[2:3], off
	v_lshl_add_u64 v[2:3], s[68:69], 0, v[0:1]
	s_mov_b32 m0, s21
	v_readfirstlane_b32 s21, v9
	v_add_u32_e32 v9, 0xc000, v142
	global_load_lds_dwordx4 v[2:3], off
	v_lshl_add_u64 v[4:5], v[2:3], 0, s[8:9]
	s_mov_b32 m0, s21
	v_readfirstlane_b32 s21, v9
	global_load_lds_dwordx4 v[4:5], off
	v_lshl_add_u64 v[4:5], v[2:3], 0, s[10:11]
	s_mov_b32 m0, s21
	v_lshl_add_u64 v[2:3], v[2:3], 0, s[12:13]
	global_load_lds_dwordx4 v[4:5], off
	v_add_u32_e32 v4, 0xe000, v142
	s_or_b32 s66, s70, s97
	v_readfirstlane_b32 s21, v4
	s_mov_b32 m0, s21
	v_ashrrev_i32_e32 v4, 6, v6
	global_load_lds_dwordx4 v[2:3], off
	v_lshrrev_b32_e32 v5, 30, v4
	s_ashr_i32 s67, s66, 31
	v_add_u32_e32 v5, v4, v5
	s_lshl_b64 s[68:69], s[66:67], 19
	v_bfe_u32 v2, v6, 4, 2
	v_bfe_u32 v3, v6, 1, 3
	v_and_b32_e32 v6, 0x7fffc, v5
	s_add_u32 s68, s34, s68
	v_sub_u32_e32 v4, v4, v6
	s_addc_u32 s69, s35, s69
	v_lshlrev_b32_e32 v144, 13, v4
	v_bitop3_b32 v4, v7, v3, 3 bitop3:0x6c
	v_bitop3_b32 v2, v2, v3, 4 bitop3:0x36
	v_lshl_add_u64 v[138:139], s[68:69], 0, v[0:1]
	s_add_u32 s68, s34, s20
	v_lshlrev_b32_e32 v5, 12, v5
	v_lshlrev_b32_e32 v4, 3, v4
	v_lshlrev_b32_e32 v2, 3, v2
	s_addc_u32 s69, s35, 0
	v_and_b32_e32 v143, 0xffffc000, v5
	v_lshl_add_u64 v[140:141], s[68:69], 0, v[0:1]
	s_mov_b64 s[68:69], 0
	v_lshlrev_b32_e32 v145, 1, v8
	v_lshlrev_b32_e32 v174, 1, v4
	v_lshlrev_b32_e32 v175, 1, v2
	s_mov_b32 vcc_lo, 0
	s_mov_b32 s86, 0
	v_mov_b32_e32 v4, 0
	v_mov_b32_e32 v5, v131
	v_mov_b32_e32 v6, v131
	v_mov_b32_e32 v7, v131
	v_mov_b32_e32 v12, 0
	v_mov_b32_e32 v13, v131
	v_mov_b32_e32 v14, v131
	v_mov_b32_e32 v15, v131
	v_mov_b32_e32 v0, 0
	v_mov_b32_e32 v1, v131
	v_mov_b32_e32 v2, v131
	v_mov_b32_e32 v3, v131
	v_mov_b32_e32 v8, 0
	v_mov_b32_e32 v9, v131
	v_mov_b32_e32 v10, v131
	v_mov_b32_e32 v11, v131
	v_mov_b32_e32 v16, 0
	v_mov_b32_e32 v17, v131
	v_mov_b32_e32 v18, v131
	v_mov_b32_e32 v19, v131
	v_mov_b32_e32 v20, 0
	v_mov_b32_e32 v21, v131
	v_mov_b32_e32 v22, v131
	v_mov_b32_e32 v23, v131
	v_mov_b32_e32 v24, 0
	v_mov_b32_e32 v25, v131
	v_mov_b32_e32 v26, v131
	v_mov_b32_e32 v27, v131
	v_mov_b32_e32 v28, 0
	v_mov_b32_e32 v29, v131
	v_mov_b32_e32 v30, v131
	v_mov_b32_e32 v31, v131
	v_mov_b32_e32 v32, 0
	v_mov_b32_e32 v33, v131
	v_mov_b32_e32 v34, v131
	v_mov_b32_e32 v35, v131
	v_mov_b32_e32 v36, 0
	v_mov_b32_e32 v37, v131
	v_mov_b32_e32 v38, v131
	v_mov_b32_e32 v39, v131
	v_mov_b32_e32 v40, 0
	v_mov_b32_e32 v41, v131
	v_mov_b32_e32 v42, v131
	v_mov_b32_e32 v43, v131
	v_mov_b32_e32 v44, 0
	v_mov_b32_e32 v45, v131
	v_mov_b32_e32 v46, v131
	v_mov_b32_e32 v47, v131
	v_mov_b32_e32 v48, 0
	v_mov_b32_e32 v49, v131
	v_mov_b32_e32 v50, v131
	v_mov_b32_e32 v51, v131
	v_mov_b32_e32 v52, 0
	v_mov_b32_e32 v53, v131
	v_mov_b32_e32 v54, v131
	v_mov_b32_e32 v55, v131
	v_mov_b32_e32 v56, 0
	v_mov_b32_e32 v57, v131
	v_mov_b32_e32 v58, v131
	v_mov_b32_e32 v59, v131
	v_mov_b32_e32 v60, 0
	v_mov_b32_e32 v61, v131
	v_mov_b32_e32 v62, v131
	v_mov_b32_e32 v63, v131
	v_mov_b32_e32 v64, 0
	v_mov_b32_e32 v65, v131
	v_mov_b32_e32 v66, v131
	v_mov_b32_e32 v67, v131
	v_mov_b32_e32 v68, 0
	v_mov_b32_e32 v69, v131
	v_mov_b32_e32 v70, v131
	v_mov_b32_e32 v71, v131
	v_mov_b32_e32 v72, 0
	v_mov_b32_e32 v73, v131
	v_mov_b32_e32 v74, v131
	v_mov_b32_e32 v75, v131
	v_mov_b32_e32 v76, 0
	v_mov_b32_e32 v77, v131
	v_mov_b32_e32 v78, v131
	v_mov_b32_e32 v79, v131
	v_mov_b32_e32 v80, 0
	v_mov_b32_e32 v81, v131
	v_mov_b32_e32 v82, v131
	v_mov_b32_e32 v83, v131
	v_mov_b32_e32 v84, 0
	v_mov_b32_e32 v85, v131
	v_mov_b32_e32 v86, v131
	v_mov_b32_e32 v87, v131
	v_mov_b32_e32 v88, 0
	v_mov_b32_e32 v89, v131
	v_mov_b32_e32 v90, v131
	v_mov_b32_e32 v91, v131
	v_mov_b32_e32 v92, 0
	v_mov_b32_e32 v93, v131
	v_mov_b32_e32 v94, v131
	v_mov_b32_e32 v95, v131
	v_mov_b32_e32 v96, 0
	v_mov_b32_e32 v97, v131
	v_mov_b32_e32 v98, v131
	v_mov_b32_e32 v99, v131
	v_mov_b32_e32 v100, 0
	v_mov_b32_e32 v101, v131
	v_mov_b32_e32 v102, v131
	v_mov_b32_e32 v103, v131
	v_mov_b32_e32 v104, 0
	v_mov_b32_e32 v105, v131
	v_mov_b32_e32 v106, v131
	v_mov_b32_e32 v107, v131
	v_mov_b32_e32 v108, 0
	v_mov_b32_e32 v109, v131
	v_mov_b32_e32 v110, v131
	v_mov_b32_e32 v111, v131
	v_mov_b32_e32 v112, 0
	v_mov_b32_e32 v113, v131
	v_mov_b32_e32 v114, v131
	v_mov_b32_e32 v115, v131
	v_mov_b32_e32 v116, 0
	v_mov_b32_e32 v117, v131
	v_mov_b32_e32 v118, v131
	v_mov_b32_e32 v119, v131
	v_mov_b32_e32 v120, 0
	v_mov_b32_e32 v121, v131
	v_mov_b32_e32 v122, v131
	v_mov_b32_e32 v123, v131
	v_mov_b32_e32 v124, 0
	v_mov_b32_e32 v125, v131
	v_mov_b32_e32 v126, v131
	v_mov_b32_e32 v127, v131
	s_waitcnt vmcnt(0) lgkmcnt(0)
	s_barrier
	v_add3_u32 v180, v143, v145, v174
	v_add3_u32 v245, v144, v145, v174
	v_add3_u32 v244, v143, v145, v175
	v_add3_u32 v246, v144, v145, v175
	v_xor_b32_e32 v247, 0x10000, v180
	v_xor_b32_e32 v248, 0x10000, v244
	v_xor_b32_e32 v249, 0x10000, v245
	v_xor_b32_e32 v250, 0x10000, v246
	v_readfirstlane_b32 s87, v142
	ds_read_b128 v[176:179], v180
	ds_read_b128 v[182:185], v180 offset:2048
	ds_read_b128 v[186:189], v180 offset:4096
	ds_read_b128 v[190:193], v180 offset:6144
	ds_read_b128 v[210:213], v245 offset:32768
	ds_read_b128 v[214:217], v245 offset:34816
	ds_read_b128 v[218:221], v245 offset:36864
	ds_read_b128 v[222:225], v245 offset:38912
	s_mov_b32 s86, 0
	s_mov_b64 s[68:69], s[34:35]
	v_subrev_u32_e32 v242, s34, v138
	v_subrev_u32_e32 v243, s34, v140
	s_add_u32 s87, s87, 0x10000
	s_mov_b32 m0, s87
	s_add_u32 s70, s68, 0x4000080
	s_addc_u32 s71, s69, 0
	global_load_lds_dwordx4 v242, s[70:71]
	s_add_u32 m0, s87, 0x2000
	s_add_u32 s70, s68, 0x4020080
	s_addc_u32 s71, s69, 0
	global_load_lds_dwordx4 v242, s[70:71]
	s_add_u32 m0, s87, 0x4000
	s_add_u32 s70, s68, 0x4040080
	s_addc_u32 s71, s69, 0
	global_load_lds_dwordx4 v242, s[70:71]
	s_add_u32 m0, s87, 0x6000
	s_add_u32 s70, s68, s14
	s_addc_u32 s71, s69, s15
	global_load_lds_dwordx4 v242, s[70:71]
	s_add_u32 m0, s87, 0x8000
	s_add_u32 s70, s68, s16
	s_addc_u32 s71, s69, s17
	global_load_lds_dwordx4 v243, s[70:71]
	s_add_u32 m0, s87, 0xa000
	s_add_u32 s70, s68, s18
	s_addc_u32 s71, s69, s19
	global_load_lds_dwordx4 v243, s[70:71]
	s_add_u32 m0, s87, 0xc000
	s_add_u32 s70, s68, s22
	s_addc_u32 s71, s69, s23
	global_load_lds_dwordx4 v243, s[70:71]
	s_add_u32 m0, s87, 0xe000
	s_add_u32 s70, s68, s36
	s_addc_u32 s71, s69, s37
	global_load_lds_dwordx4 v243, s[70:71]
	s_branch .Lg5_entry
.Lg5_top:
	s_waitcnt lgkmcnt(0)
	s_waitcnt vmcnt(0)
	s_barrier
	s_xor_b32 s87, s87, 0x10000
	ds_read_b128 v[176:179], v180
	ds_read_b128 v[182:185], v180 offset:2048
	ds_read_b128 v[186:189], v180 offset:4096
	ds_read_b128 v[190:193], v180 offset:6144
	ds_read_b128 v[210:213], v245 offset:32768
	ds_read_b128 v[214:217], v245 offset:34816
	ds_read_b128 v[218:221], v245 offset:36864
	ds_read_b128 v[222:225], v245 offset:38912
	v_mfma_f32_16x16x32_bf16 v[60:63], v[194:197], v[226:229], v[60:63]
	v_mfma_f32_16x16x32_bf16 v[56:59], v[194:197], v[230:233], v[56:59]
	s_mov_b32 m0, s87
	s_add_u32 s70, s68, 0x4000080
	s_addc_u32 s71, s69, 0
	global_load_lds_dwordx4 v242, s[70:71]
	v_mfma_f32_16x16x32_bf16 v[52:55], v[194:197], v[234:237], v[52:55]
	v_mfma_f32_16x16x32_bf16 v[48:51], v[194:197], v[238:241], v[48:51]
	s_add_u32 m0, s87, 0x2000
	s_add_u32 s70, s68, 0x4020080
	s_addc_u32 s71, s69, 0
	global_load_lds_dwordx4 v242, s[70:71]
	v_mfma_f32_16x16x32_bf16 v[44:47], v[198:201], v[226:229], v[44:47]
	v_mfma_f32_16x16x32_bf16 v[40:43], v[198:201], v[230:233], v[40:43]
	s_add_u32 m0, s87, 0x4000
	s_add_u32 s70, s68, 0x4040080
	s_addc_u32 s71, s69, 0
	global_load_lds_dwordx4 v242, s[70:71]
	v_mfma_f32_16x16x32_bf16 v[36:39], v[198:201], v[234:237], v[36:39]
	v_mfma_f32_16x16x32_bf16 v[32:35], v[198:201], v[238:241], v[32:35]
	s_add_u32 m0, s87, 0x6000
	s_add_u32 s70, s68, s14
	s_addc_u32 s71, s69, s15
	global_load_lds_dwordx4 v242, s[70:71]
	v_mfma_f32_16x16x32_bf16 v[28:31], v[202:205], v[226:229], v[28:31]
	v_mfma_f32_16x16x32_bf16 v[24:27], v[202:205], v[230:233], v[24:27]
	s_add_u32 m0, s87, 0x8000
	s_add_u32 s70, s68, s16
	s_addc_u32 s71, s69, s17
	global_load_lds_dwordx4 v243, s[70:71]
	v_mfma_f32_16x16x32_bf16 v[20:23], v[202:205], v[234:237], v[20:23]
	v_mfma_f32_16x16x32_bf16 v[16:19], v[202:205], v[238:241], v[16:19]
	s_add_u32 m0, s87, 0xa000
	s_add_u32 s70, s68, s18
	s_addc_u32 s71, s69, s19
	global_load_lds_dwordx4 v243, s[70:71]
	v_mfma_f32_16x16x32_bf16 v[8:11], v[206:209], v[226:229], v[8:11]
	v_mfma_f32_16x16x32_bf16 v[0:3], v[206:209], v[230:233], v[0:3]
	s_add_u32 m0, s87, 0xc000
	s_add_u32 s70, s68, s22
	s_addc_u32 s71, s69, s23
	global_load_lds_dwordx4 v243, s[70:71]
	v_mfma_f32_16x16x32_bf16 v[12:15], v[206:209], v[234:237], v[12:15]
	v_mfma_f32_16x16x32_bf16 v[4:7], v[206:209], v[238:241], v[4:7]
	s_add_u32 m0, s87, 0xe000
	s_add_u32 s70, s68, s36
	s_addc_u32 s71, s69, s37
	global_load_lds_dwordx4 v243, s[70:71]
.Lg5_entry:
	ds_read_b128 v[194:197], v180 offset:8192
	ds_read_b128 v[198:201], v180 offset:10240
	ds_read_b128 v[202:205], v180 offset:12288
	ds_read_b128 v[206:209], v180 offset:14336
	s_waitcnt lgkmcnt(4)
	v_mfma_f32_16x16x32_bf16 v[124:127], v[176:179], v[210:213], v[124:127]
	v_mfma_f32_16x16x32_bf16 v[120:123], v[176:179], v[214:217], v[120:123]
	v_mfma_f32_16x16x32_bf16 v[116:119], v[176:179], v[218:221], v[116:119]
	v_mfma_f32_16x16x32_bf16 v[112:115], v[176:179], v[222:225], v[112:115]
	v_mfma_f32_16x16x32_bf16 v[108:111], v[182:185], v[210:213], v[108:111]
	v_mfma_f32_16x16x32_bf16 v[104:107], v[182:185], v[214:217], v[104:107]
	v_mfma_f32_16x16x32_bf16 v[100:103], v[182:185], v[218:221], v[100:103]
	v_mfma_f32_16x16x32_bf16 v[96:99], v[182:185], v[222:225], v[96:99]
	v_mfma_f32_16x16x32_bf16 v[92:95], v[186:189], v[210:213], v[92:95]
	v_mfma_f32_16x16x32_bf16 v[88:91], v[186:189], v[214:217], v[88:91]
	v_mfma_f32_16x16x32_bf16 v[84:87], v[186:189], v[218:221], v[84:87]
	v_mfma_f32_16x16x32_bf16 v[80:83], v[186:189], v[222:225], v[80:83]
	v_mfma_f32_16x16x32_bf16 v[76:79], v[190:193], v[210:213], v[76:79]
	v_mfma_f32_16x16x32_bf16 v[72:75], v[190:193], v[214:217], v[72:75]
	v_mfma_f32_16x16x32_bf16 v[68:71], v[190:193], v[218:221], v[68:71]
	v_mfma_f32_16x16x32_bf16 v[64:67], v[190:193], v[222:225], v[64:67]
	ds_read_b128 v[176:179], v244
	ds_read_b128 v[182:185], v244 offset:2048
	ds_read_b128 v[186:189], v244 offset:4096
	ds_read_b128 v[190:193], v244 offset:6144
	ds_read_b128 v[226:229], v246 offset:32768
	ds_read_b128 v[230:233], v246 offset:34816
	ds_read_b128 v[234:237], v246 offset:36864
	ds_read_b128 v[238:241], v246 offset:38912
	s_waitcnt lgkmcnt(8)
	v_mfma_f32_16x16x32_bf16 v[60:63], v[194:197], v[210:213], v[60:63]
	v_mfma_f32_16x16x32_bf16 v[56:59], v[194:197], v[214:217], v[56:59]
	v_mfma_f32_16x16x32_bf16 v[52:55], v[194:197], v[218:221], v[52:55]
	v_mfma_f32_16x16x32_bf16 v[48:51], v[194:197], v[222:225], v[48:51]
	v_mfma_f32_16x16x32_bf16 v[44:47], v[198:201], v[210:213], v[44:47]
	v_mfma_f32_16x16x32_bf16 v[40:43], v[198:201], v[214:217], v[40:43]
	v_mfma_f32_16x16x32_bf16 v[36:39], v[198:201], v[218:221], v[36:39]
	v_mfma_f32_16x16x32_bf16 v[32:35], v[198:201], v[222:225], v[32:35]
	v_mfma_f32_16x16x32_bf16 v[28:31], v[202:205], v[210:213], v[28:31]
	v_mfma_f32_16x16x32_bf16 v[24:27], v[202:205], v[214:217], v[24:27]
	v_mfma_f32_16x16x32_bf16 v[20:23], v[202:205], v[218:221], v[20:23]
	v_mfma_f32_16x16x32_bf16 v[16:19], v[202:205], v[222:225], v[16:19]
	v_mfma_f32_16x16x32_bf16 v[8:11], v[206:209], v[210:213], v[8:11]
	v_mfma_f32_16x16x32_bf16 v[0:3], v[206:209], v[214:217], v[0:3]
	v_mfma_f32_16x16x32_bf16 v[12:15], v[206:209], v[218:221], v[12:15]
	v_mfma_f32_16x16x32_bf16 v[4:7], v[206:209], v[222:225], v[4:7]
	ds_read_b128 v[194:197], v244 offset:8192
	ds_read_b128 v[198:201], v244 offset:10240
	ds_read_b128 v[202:205], v244 offset:12288
	ds_read_b128 v[206:209], v244 offset:14336
	s_waitcnt lgkmcnt(4)
	v_mfma_f32_16x16x32_bf16 v[124:127], v[176:179], v[226:229], v[124:127]
	v_mfma_f32_16x16x32_bf16 v[120:123], v[176:179], v[230:233], v[120:123]
	v_mfma_f32_16x16x32_bf16 v[116:119], v[176:179], v[234:237], v[116:119]
	v_mfma_f32_16x16x32_bf16 v[112:115], v[176:179], v[238:241], v[112:115]
	v_mfma_f32_16x16x32_bf16 v[108:111], v[182:185], v[226:229], v[108:111]
	v_mfma_f32_16x16x32_bf16 v[104:107], v[182:185], v[230:233], v[104:107]
	v_mfma_f32_16x16x32_bf16 v[100:103], v[182:185], v[234:237], v[100:103]
	v_mfma_f32_16x16x32_bf16 v[96:99], v[182:185], v[238:241], v[96:99]
	v_mfma_f32_16x16x32_bf16 v[92:95], v[186:189], v[226:229], v[92:95]
	v_mfma_f32_16x16x32_bf16 v[88:91], v[186:189], v[230:233], v[88:91]
	v_mfma_f32_16x16x32_bf16 v[84:87], v[186:189], v[234:237], v[84:87]
	v_mfma_f32_16x16x32_bf16 v[80:83], v[186:189], v[238:241], v[80:83]
	v_mfma_f32_16x16x32_bf16 v[76:79], v[190:193], v[226:229], v[76:79]
	v_mfma_f32_16x16x32_bf16 v[72:75], v[190:193], v[230:233], v[72:75]
	v_mfma_f32_16x16x32_bf16 v[68:71], v[190:193], v[234:237], v[68:71]
	v_mfma_f32_16x16x32_bf16 v[64:67], v[190:193], v[238:241], v[64:67]
	s_add_u32 s68, s68, 0x80
	s_addc_u32 s69, s69, 0
	s_add_i32 s86, s86, 1
	s_cmp_lt_u32 s86, 15
	s_cbranch_scc0 .Lg5_last
	s_waitcnt lgkmcnt(0)
	s_waitcnt vmcnt(0)
	s_barrier
	s_xor_b32 s87, s87, 0x10000
	ds_read_b128 v[176:179], v247
	ds_read_b128 v[182:185], v247 offset:2048
	ds_read_b128 v[186:189], v247 offset:4096
	ds_read_b128 v[190:193], v247 offset:6144
	ds_read_b128 v[210:213], v249 offset:32768
	ds_read_b128 v[214:217], v249 offset:34816
	ds_read_b128 v[218:221], v249 offset:36864
	ds_read_b128 v[222:225], v249 offset:38912
	v_mfma_f32_16x16x32_bf16 v[60:63], v[194:197], v[226:229], v[60:63]
	v_mfma_f32_16x16x32_bf16 v[56:59], v[194:197], v[230:233], v[56:59]
	s_mov_b32 m0, s87
	s_add_u32 s70, s68, 0x4000080
	s_addc_u32 s71, s69, 0
	global_load_lds_dwordx4 v242, s[70:71]
	v_mfma_f32_16x16x32_bf16 v[52:55], v[194:197], v[234:237], v[52:55]
	v_mfma_f32_16x16x32_bf16 v[48:51], v[194:197], v[238:241], v[48:51]
	s_add_u32 m0, s87, 0x2000
	s_add_u32 s70, s68, 0x4020080
	s_addc_u32 s71, s69, 0
	global_load_lds_dwordx4 v242, s[70:71]
	v_mfma_f32_16x16x32_bf16 v[44:47], v[198:201], v[226:229], v[44:47]
	v_mfma_f32_16x16x32_bf16 v[40:43], v[198:201], v[230:233], v[40:43]
	s_add_u32 m0, s87, 0x4000
	s_add_u32 s70, s68, 0x4040080
	s_addc_u32 s71, s69, 0
	global_load_lds_dwordx4 v242, s[70:71]
	v_mfma_f32_16x16x32_bf16 v[36:39], v[198:201], v[234:237], v[36:39]
	v_mfma_f32_16x16x32_bf16 v[32:35], v[198:201], v[238:241], v[32:35]
	s_add_u32 m0, s87, 0x6000
	s_add_u32 s70, s68, s14
	s_addc_u32 s71, s69, s15
	global_load_lds_dwordx4 v242, s[70:71]
	v_mfma_f32_16x16x32_bf16 v[28:31], v[202:205], v[226:229], v[28:31]
	v_mfma_f32_16x16x32_bf16 v[24:27], v[202:205], v[230:233], v[24:27]
	s_add_u32 m0, s87, 0x8000
	s_add_u32 s70, s68, s16
	s_addc_u32 s71, s69, s17
	global_load_lds_dwordx4 v243, s[70:71]
	v_mfma_f32_16x16x32_bf16 v[20:23], v[202:205], v[234:237], v[20:23]
	v_mfma_f32_16x16x32_bf16 v[16:19], v[202:205], v[238:241], v[16:19]
	s_add_u32 m0, s87, 0xa000
	s_add_u32 s70, s68, s18
	s_addc_u32 s71, s69, s19
	global_load_lds_dwordx4 v243, s[70:71]
	v_mfma_f32_16x16x32_bf16 v[8:11], v[206:209], v[226:229], v[8:11]
	v_mfma_f32_16x16x32_bf16 v[0:3], v[206:209], v[230:233], v[0:3]
	s_add_u32 m0, s87, 0xc000
	s_add_u32 s70, s68, s22
	s_addc_u32 s71, s69, s23
	global_load_lds_dwordx4 v243, s[70:71]
	v_mfma_f32_16x16x32_bf16 v[12:15], v[206:209], v[234:237], v[12:15]
	v_mfma_f32_16x16x32_bf16 v[4:7], v[206:209], v[238:241], v[4:7]
	s_add_u32 m0, s87, 0xe000
	s_add_u32 s70, s68, s36
	s_addc_u32 s71, s69, s37
	global_load_lds_dwordx4 v243, s[70:71]
	ds_read_b128 v[194:197], v247 offset:8192
	ds_read_b128 v[198:201], v247 offset:10240
	ds_read_b128 v[202:205], v247 offset:12288
	ds_read_b128 v[206:209], v247 offset:14336
	s_waitcnt lgkmcnt(4)
	v_mfma_f32_16x16x32_bf16 v[124:127], v[176:179], v[210:213], v[124:127]
	v_mfma_f32_16x16x32_bf16 v[120:123], v[176:179], v[214:217], v[120:123]
	v_mfma_f32_16x16x32_bf16 v[116:119], v[176:179], v[218:221], v[116:119]
	v_mfma_f32_16x16x32_bf16 v[112:115], v[176:179], v[222:225], v[112:115]
	v_mfma_f32_16x16x32_bf16 v[108:111], v[182:185], v[210:213], v[108:111]
	v_mfma_f32_16x16x32_bf16 v[104:107], v[182:185], v[214:217], v[104:107]
	v_mfma_f32_16x16x32_bf16 v[100:103], v[182:185], v[218:221], v[100:103]
	v_mfma_f32_16x16x32_bf16 v[96:99], v[182:185], v[222:225], v[96:99]
	v_mfma_f32_16x16x32_bf16 v[92:95], v[186:189], v[210:213], v[92:95]
	v_mfma_f32_16x16x32_bf16 v[88:91], v[186:189], v[214:217], v[88:91]
	v_mfma_f32_16x16x32_bf16 v[84:87], v[186:189], v[218:221], v[84:87]
	v_mfma_f32_16x16x32_bf16 v[80:83], v[186:189], v[222:225], v[80:83]
	v_mfma_f32_16x16x32_bf16 v[76:79], v[190:193], v[210:213], v[76:79]
	v_mfma_f32_16x16x32_bf16 v[72:75], v[190:193], v[214:217], v[72:75]
	v_mfma_f32_16x16x32_bf16 v[68:71], v[190:193], v[218:221], v[68:71]
	v_mfma_f32_16x16x32_bf16 v[64:67], v[190:193], v[222:225], v[64:67]
	ds_read_b128 v[176:179], v248
	ds_read_b128 v[182:185], v248 offset:2048
	ds_read_b128 v[186:189], v248 offset:4096
	ds_read_b128 v[190:193], v248 offset:6144
	ds_read_b128 v[226:229], v250 offset:32768
	ds_read_b128 v[230:233], v250 offset:34816
	ds_read_b128 v[234:237], v250 offset:36864
	ds_read_b128 v[238:241], v250 offset:38912
	s_waitcnt lgkmcnt(8)
	v_mfma_f32_16x16x32_bf16 v[60:63], v[194:197], v[210:213], v[60:63]
	v_mfma_f32_16x16x32_bf16 v[56:59], v[194:197], v[214:217], v[56:59]
	v_mfma_f32_16x16x32_bf16 v[52:55], v[194:197], v[218:221], v[52:55]
	v_mfma_f32_16x16x32_bf16 v[48:51], v[194:197], v[222:225], v[48:51]
	v_mfma_f32_16x16x32_bf16 v[44:47], v[198:201], v[210:213], v[44:47]
	v_mfma_f32_16x16x32_bf16 v[40:43], v[198:201], v[214:217], v[40:43]
	v_mfma_f32_16x16x32_bf16 v[36:39], v[198:201], v[218:221], v[36:39]
	v_mfma_f32_16x16x32_bf16 v[32:35], v[198:201], v[222:225], v[32:35]
	v_mfma_f32_16x16x32_bf16 v[28:31], v[202:205], v[210:213], v[28:31]
	v_mfma_f32_16x16x32_bf16 v[24:27], v[202:205], v[214:217], v[24:27]
	v_mfma_f32_16x16x32_bf16 v[20:23], v[202:205], v[218:221], v[20:23]
	v_mfma_f32_16x16x32_bf16 v[16:19], v[202:205], v[222:225], v[16:19]
	v_mfma_f32_16x16x32_bf16 v[8:11], v[206:209], v[210:213], v[8:11]
	v_mfma_f32_16x16x32_bf16 v[0:3], v[206:209], v[214:217], v[0:3]
	v_mfma_f32_16x16x32_bf16 v[12:15], v[206:209], v[218:221], v[12:15]
	v_mfma_f32_16x16x32_bf16 v[4:7], v[206:209], v[222:225], v[4:7]
	ds_read_b128 v[194:197], v248 offset:8192
	ds_read_b128 v[198:201], v248 offset:10240
	ds_read_b128 v[202:205], v248 offset:12288
	ds_read_b128 v[206:209], v248 offset:14336
	s_waitcnt lgkmcnt(4)
	v_mfma_f32_16x16x32_bf16 v[124:127], v[176:179], v[226:229], v[124:127]
	v_mfma_f32_16x16x32_bf16 v[120:123], v[176:179], v[230:233], v[120:123]
	v_mfma_f32_16x16x32_bf16 v[116:119], v[176:179], v[234:237], v[116:119]
	v_mfma_f32_16x16x32_bf16 v[112:115], v[176:179], v[238:241], v[112:115]
	v_mfma_f32_16x16x32_bf16 v[108:111], v[182:185], v[226:229], v[108:111]
	v_mfma_f32_16x16x32_bf16 v[104:107], v[182:185], v[230:233], v[104:107]
	v_mfma_f32_16x16x32_bf16 v[100:103], v[182:185], v[234:237], v[100:103]
	v_mfma_f32_16x16x32_bf16 v[96:99], v[182:185], v[238:241], v[96:99]
	v_mfma_f32_16x16x32_bf16 v[92:95], v[186:189], v[226:229], v[92:95]
	v_mfma_f32_16x16x32_bf16 v[88:91], v[186:189], v[230:233], v[88:91]
	v_mfma_f32_16x16x32_bf16 v[84:87], v[186:189], v[234:237], v[84:87]
	v_mfma_f32_16x16x32_bf16 v[80:83], v[186:189], v[238:241], v[80:83]
	v_mfma_f32_16x16x32_bf16 v[76:79], v[190:193], v[226:229], v[76:79]
	v_mfma_f32_16x16x32_bf16 v[72:75], v[190:193], v[230:233], v[72:75]
	v_mfma_f32_16x16x32_bf16 v[68:71], v[190:193], v[234:237], v[68:71]
	v_mfma_f32_16x16x32_bf16 v[64:67], v[190:193], v[238:241], v[64:67]
	s_add_u32 s68, s68, 0x80
	s_addc_u32 s69, s69, 0
	s_add_i32 s86, s86, 1
	s_branch .Lg5_top
.Lg5_last:
	s_waitcnt lgkmcnt(0)
	s_waitcnt vmcnt(0)
	s_barrier
	s_xor_b32 s87, s87, 0x10000
	ds_read_b128 v[176:179], v247
	ds_read_b128 v[182:185], v247 offset:2048
	ds_read_b128 v[186:189], v247 offset:4096
	ds_read_b128 v[190:193], v247 offset:6144
	ds_read_b128 v[210:213], v249 offset:32768
	ds_read_b128 v[214:217], v249 offset:34816
	ds_read_b128 v[218:221], v249 offset:36864
	ds_read_b128 v[222:225], v249 offset:38912
	v_mfma_f32_16x16x32_bf16 v[60:63], v[194:197], v[226:229], v[60:63]
	v_mfma_f32_16x16x32_bf16 v[56:59], v[194:197], v[230:233], v[56:59]
	v_mfma_f32_16x16x32_bf16 v[52:55], v[194:197], v[234:237], v[52:55]
	v_mfma_f32_16x16x32_bf16 v[48:51], v[194:197], v[238:241], v[48:51]
	v_mfma_f32_16x16x32_bf16 v[44:47], v[198:201], v[226:229], v[44:47]
	v_mfma_f32_16x16x32_bf16 v[40:43], v[198:201], v[230:233], v[40:43]
	v_mfma_f32_16x16x32_bf16 v[36:39], v[198:201], v[234:237], v[36:39]
	v_mfma_f32_16x16x32_bf16 v[32:35], v[198:201], v[238:241], v[32:35]
	v_mfma_f32_16x16x32_bf16 v[28:31], v[202:205], v[226:229], v[28:31]
	v_mfma_f32_16x16x32_bf16 v[24:27], v[202:205], v[230:233], v[24:27]
	v_mfma_f32_16x16x32_bf16 v[20:23], v[202:205], v[234:237], v[20:23]
	v_mfma_f32_16x16x32_bf16 v[16:19], v[202:205], v[238:241], v[16:19]
	v_mfma_f32_16x16x32_bf16 v[8:11], v[206:209], v[226:229], v[8:11]
	v_mfma_f32_16x16x32_bf16 v[0:3], v[206:209], v[230:233], v[0:3]
	v_mfma_f32_16x16x32_bf16 v[12:15], v[206:209], v[234:237], v[12:15]
	v_mfma_f32_16x16x32_bf16 v[4:7], v[206:209], v[238:241], v[4:7]
	ds_read_b128 v[194:197], v247 offset:8192
	ds_read_b128 v[198:201], v247 offset:10240
	ds_read_b128 v[202:205], v247 offset:12288
	ds_read_b128 v[206:209], v247 offset:14336
	s_waitcnt lgkmcnt(4)
	v_mfma_f32_16x16x32_bf16 v[124:127], v[176:179], v[210:213], v[124:127]
	v_mfma_f32_16x16x32_bf16 v[120:123], v[176:179], v[214:217], v[120:123]
	v_mfma_f32_16x16x32_bf16 v[116:119], v[176:179], v[218:221], v[116:119]
	v_mfma_f32_16x16x32_bf16 v[112:115], v[176:179], v[222:225], v[112:115]
	v_mfma_f32_16x16x32_bf16 v[108:111], v[182:185], v[210:213], v[108:111]
	v_mfma_f32_16x16x32_bf16 v[104:107], v[182:185], v[214:217], v[104:107]
	v_mfma_f32_16x16x32_bf16 v[100:103], v[182:185], v[218:221], v[100:103]
	v_mfma_f32_16x16x32_bf16 v[96:99], v[182:185], v[222:225], v[96:99]
	v_mfma_f32_16x16x32_bf16 v[92:95], v[186:189], v[210:213], v[92:95]
	v_mfma_f32_16x16x32_bf16 v[88:91], v[186:189], v[214:217], v[88:91]
	v_mfma_f32_16x16x32_bf16 v[84:87], v[186:189], v[218:221], v[84:87]
	v_mfma_f32_16x16x32_bf16 v[80:83], v[186:189], v[222:225], v[80:83]
	v_mfma_f32_16x16x32_bf16 v[76:79], v[190:193], v[210:213], v[76:79]
	v_mfma_f32_16x16x32_bf16 v[72:75], v[190:193], v[214:217], v[72:75]
	v_mfma_f32_16x16x32_bf16 v[68:71], v[190:193], v[218:221], v[68:71]
	v_mfma_f32_16x16x32_bf16 v[64:67], v[190:193], v[222:225], v[64:67]
	ds_read_b128 v[176:179], v248
	ds_read_b128 v[182:185], v248 offset:2048
	ds_read_b128 v[186:189], v248 offset:4096
	ds_read_b128 v[190:193], v248 offset:6144
	ds_read_b128 v[226:229], v250 offset:32768
	ds_read_b128 v[230:233], v250 offset:34816
	ds_read_b128 v[234:237], v250 offset:36864
	ds_read_b128 v[238:241], v250 offset:38912
	s_waitcnt lgkmcnt(8)
	v_mfma_f32_16x16x32_bf16 v[60:63], v[194:197], v[210:213], v[60:63]
	v_mfma_f32_16x16x32_bf16 v[56:59], v[194:197], v[214:217], v[56:59]
	v_mfma_f32_16x16x32_bf16 v[52:55], v[194:197], v[218:221], v[52:55]
	v_mfma_f32_16x16x32_bf16 v[48:51], v[194:197], v[222:225], v[48:51]
	v_mfma_f32_16x16x32_bf16 v[44:47], v[198:201], v[210:213], v[44:47]
	v_mfma_f32_16x16x32_bf16 v[40:43], v[198:201], v[214:217], v[40:43]
	v_mfma_f32_16x16x32_bf16 v[36:39], v[198:201], v[218:221], v[36:39]
	v_mfma_f32_16x16x32_bf16 v[32:35], v[198:201], v[222:225], v[32:35]
	v_mfma_f32_16x16x32_bf16 v[28:31], v[202:205], v[210:213], v[28:31]
	v_mfma_f32_16x16x32_bf16 v[24:27], v[202:205], v[214:217], v[24:27]
	v_mfma_f32_16x16x32_bf16 v[20:23], v[202:205], v[218:221], v[20:23]
	v_mfma_f32_16x16x32_bf16 v[16:19], v[202:205], v[222:225], v[16:19]
	v_mfma_f32_16x16x32_bf16 v[8:11], v[206:209], v[210:213], v[8:11]
	v_mfma_f32_16x16x32_bf16 v[0:3], v[206:209], v[214:217], v[0:3]
	v_mfma_f32_16x16x32_bf16 v[12:15], v[206:209], v[218:221], v[12:15]
	v_mfma_f32_16x16x32_bf16 v[4:7], v[206:209], v[222:225], v[4:7]
	ds_read_b128 v[194:197], v248 offset:8192
	ds_read_b128 v[198:201], v248 offset:10240
	ds_read_b128 v[202:205], v248 offset:12288
	ds_read_b128 v[206:209], v248 offset:14336
	s_waitcnt lgkmcnt(4)
	v_mfma_f32_16x16x32_bf16 v[124:127], v[176:179], v[226:229], v[124:127]
	v_mfma_f32_16x16x32_bf16 v[120:123], v[176:179], v[230:233], v[120:123]
	v_mfma_f32_16x16x32_bf16 v[116:119], v[176:179], v[234:237], v[116:119]
	v_mfma_f32_16x16x32_bf16 v[112:115], v[176:179], v[238:241], v[112:115]
	v_mfma_f32_16x16x32_bf16 v[108:111], v[182:185], v[226:229], v[108:111]
	v_mfma_f32_16x16x32_bf16 v[104:107], v[182:185], v[230:233], v[104:107]
	v_mfma_f32_16x16x32_bf16 v[100:103], v[182:185], v[234:237], v[100:103]
	v_mfma_f32_16x16x32_bf16 v[96:99], v[182:185], v[238:241], v[96:99]
	v_mfma_f32_16x16x32_bf16 v[92:95], v[186:189], v[226:229], v[92:95]
	v_mfma_f32_16x16x32_bf16 v[88:91], v[186:189], v[230:233], v[88:91]
	v_mfma_f32_16x16x32_bf16 v[84:87], v[186:189], v[234:237], v[84:87]
	v_mfma_f32_16x16x32_bf16 v[80:83], v[186:189], v[238:241], v[80:83]
	v_mfma_f32_16x16x32_bf16 v[76:79], v[190:193], v[226:229], v[76:79]
	v_mfma_f32_16x16x32_bf16 v[72:75], v[190:193], v[230:233], v[72:75]
	v_mfma_f32_16x16x32_bf16 v[68:71], v[190:193], v[234:237], v[68:71]
	v_mfma_f32_16x16x32_bf16 v[64:67], v[190:193], v[238:241], v[64:67]
	s_add_u32 s68, s68, 0x80
	s_addc_u32 s69, s69, 0
	s_add_i32 s86, s86, 1
	s_waitcnt lgkmcnt(0)
	s_waitcnt vmcnt(0)
	s_barrier
	v_mfma_f32_16x16x32_bf16 v[60:63], v[194:197], v[226:229], v[60:63]
	v_mfma_f32_16x16x32_bf16 v[56:59], v[194:197], v[230:233], v[56:59]
	v_mfma_f32_16x16x32_bf16 v[52:55], v[194:197], v[234:237], v[52:55]
	v_mfma_f32_16x16x32_bf16 v[48:51], v[194:197], v[238:241], v[48:51]
	v_mfma_f32_16x16x32_bf16 v[44:47], v[198:201], v[226:229], v[44:47]
	v_mfma_f32_16x16x32_bf16 v[40:43], v[198:201], v[230:233], v[40:43]
	v_mfma_f32_16x16x32_bf16 v[36:39], v[198:201], v[234:237], v[36:39]
	v_mfma_f32_16x16x32_bf16 v[32:35], v[198:201], v[238:241], v[32:35]
	v_mfma_f32_16x16x32_bf16 v[28:31], v[202:205], v[226:229], v[28:31]
	v_mfma_f32_16x16x32_bf16 v[24:27], v[202:205], v[230:233], v[24:27]
	v_mfma_f32_16x16x32_bf16 v[20:23], v[202:205], v[234:237], v[20:23]
	v_mfma_f32_16x16x32_bf16 v[16:19], v[202:205], v[238:241], v[16:19]
	v_mfma_f32_16x16x32_bf16 v[8:11], v[206:209], v[226:229], v[8:11]
	v_mfma_f32_16x16x32_bf16 v[0:3], v[206:209], v[230:233], v[0:3]
	v_mfma_f32_16x16x32_bf16 v[12:15], v[206:209], v[234:237], v[12:15]
	v_mfma_f32_16x16x32_bf16 v[4:7], v[206:209], v[238:241], v[4:7]
	s_nop 7
	s_nop 7
	s_sub_u32 s68, s68, s34
	s_subb_u32 s69, s69, s35
	s_mov_b32 s87, 0x80000
	s_mov_b32 s87, 0x80000
	s_mov_b64 s[70:71], 0
	s_mov_b64 vcc, exec
	s_branch .LBB0_666

.LBB0_746:
	s_ashr_i32 s20, s60, 2
	v_mov_b32_e32 v6, v181
	s_and_b32 s6, s60, 7
	s_and_b32 s51, s20, -8
	s_or_b32 s46, s51, s6
	v_lshrrev_b32_e32 v7, 4, v6
	v_lshlrev_b32_e32 v1, 6, v6
	v_xor_b32_e32 v0, v7, v6
	v_and_b32_e32 v8, 0x3c0, v1
	v_lshlrev_b32_e32 v1, 8, v6
	s_ashr_i32 s47, s46, 31
	v_lshlrev_b32_e32 v0, 3, v0
	v_and_b32_e32 v1, 0xfffff800, v1
	s_and_b32 s50, s55, 7
	s_bfe_u32 s6, s60, 0x20003
	s_lshl_b64 s[20:21], s[46:47], 20
	v_and_or_b32 v0, v0, 56, v1
	s_add_u32 s20, s3, s20
	v_ashrrev_i32_e32 v1, 31, v0
	s_addc_u32 s21, s52, s21
	v_lshlrev_b64 v[0:1], 1, v[0:1]
	v_lshl_add_u32 v134, v6, 4, 0
	v_lshl_add_u64 v[2:3], s[20:21], 0, v[0:1]
	v_readfirstlane_b32 s20, v134
	v_add_u32_e32 v9, 0x2000, v134
	s_mov_b32 m0, s20
	v_readfirstlane_b32 s20, v9
	v_add_u32_e32 v9, 0x4000, v134
	s_waitcnt vmcnt(63) expcnt(7) lgkmcnt(15)
	s_barrier
	global_load_lds_dwordx4 v[2:3], off
	v_lshl_add_u64 v[4:5], v[2:3], 0, s[8:9]
	s_mov_b32 m0, s20
	v_readfirstlane_b32 s20, v9
	global_load_lds_dwordx4 v[4:5], off
	v_lshl_add_u64 v[4:5], v[2:3], 0, s[10:11]
	s_mov_b32 m0, s20
	s_lshl_b32 s47, s6, 20
	global_load_lds_dwordx4 v[4:5], off
	v_add_u32_e32 v4, 0x6000, v134
	s_add_u32 s48, s53, s47
	v_readfirstlane_b32 s20, v4
	v_add_u32_e32 v4, 0x8000, v134
	s_addc_u32 s49, s54, 0
	v_lshl_add_u64 v[2:3], v[2:3], 0, s[12:13]
	s_mov_b32 m0, s20
	v_readfirstlane_b32 s20, v4
	v_add_u32_e32 v9, 0xa000, v134
	global_load_lds_dwordx4 v[2:3], off
	v_lshl_add_u64 v[2:3], s[48:49], 0, v[0:1]
	s_mov_b32 m0, s20
	v_readfirstlane_b32 s20, v9
	v_add_u32_e32 v9, 0xc000, v134
	global_load_lds_dwordx4 v[2:3], off
	v_lshl_add_u64 v[4:5], v[2:3], 0, s[8:9]
	s_mov_b32 m0, s20
	v_readfirstlane_b32 s20, v9
	global_load_lds_dwordx4 v[4:5], off
	v_lshl_add_u64 v[4:5], v[2:3], 0, s[10:11]
	s_mov_b32 m0, s20
	v_lshl_add_u64 v[2:3], v[2:3], 0, s[12:13]
	global_load_lds_dwordx4 v[4:5], off
	v_add_u32_e32 v4, 0xe000, v134
	v_mov_b32_e32 v36, 0
	v_readfirstlane_b32 s20, v4
	s_mov_b32 m0, s20
	v_ashrrev_i32_e32 v4, 6, v6
	global_load_lds_dwordx4 v[2:3], off
	s_or_b32 s20, s51, s50
	v_lshrrev_b32_e32 v5, 30, v4
	s_ashr_i32 s21, s20, 31
	v_add_u32_e32 v5, v4, v5
	s_lshl_b64 s[20:21], s[20:21], 20
	v_bfe_u32 v2, v6, 4, 2
	v_bfe_u32 v3, v6, 1, 3
	v_and_b32_e32 v6, 0x7fffc, v5
	s_add_u32 s20, s34, s20
	v_sub_u32_e32 v4, v4, v6
	s_addc_u32 s21, s35, s21
	v_lshlrev_b32_e32 v136, 13, v4
	v_bitop3_b32 v4, v7, v3, 3 bitop3:0x6c
	v_bitop3_b32 v2, v2, v3, 4 bitop3:0x36
	v_lshl_add_u64 v[130:131], s[20:21], 0, v[0:1]
	s_add_u32 s20, s34, s47
	v_lshlrev_b32_e32 v5, 12, v5
	v_lshlrev_b32_e32 v4, 3, v4
	v_lshlrev_b32_e32 v2, 3, v2
	s_addc_u32 s21, s35, 0
	v_and_b32_e32 v135, 0xffffc000, v5
	v_lshl_add_u64 v[132:133], s[20:21], 0, v[0:1]
	s_mov_b64 s[48:49], 0
	v_lshlrev_b32_e32 v137, 1, v8
	v_lshlrev_b32_e32 v138, 1, v4
	v_lshlrev_b32_e32 v139, 1, v2
	s_mov_b32 s61, 0
	s_mov_b32 s47, 0
	v_mov_b32_e32 v37, v36
	v_mov_b32_e32 v38, v36
	v_mov_b32_e32 v39, v36
	v_mov_b32_e32 v40, v36
	v_mov_b32_e32 v41, v36
	v_mov_b32_e32 v42, v36
	v_mov_b32_e32 v43, v36
	v_mov_b32_e32 v0, v36
	v_mov_b32_e32 v1, v36
	v_mov_b32_e32 v2, v36
	v_mov_b32_e32 v3, v36
	v_mov_b32_e32 v4, v36
	v_mov_b32_e32 v5, v36
	v_mov_b32_e32 v6, v36
	v_mov_b32_e32 v7, v36
	v_mov_b32_e32 v8, v36
	v_mov_b32_e32 v9, v36
	v_mov_b32_e32 v10, v36
	v_mov_b32_e32 v11, v36
	v_mov_b32_e32 v12, v36
	v_mov_b32_e32 v13, v36
	v_mov_b32_e32 v14, v36
	v_mov_b32_e32 v15, v36
	v_mov_b32_e32 v16, v36
	v_mov_b32_e32 v17, v36
	v_mov_b32_e32 v18, v36
	v_mov_b32_e32 v19, v36
	v_mov_b32_e32 v20, v36
	v_mov_b32_e32 v21, v36
	v_mov_b32_e32 v22, v36
	v_mov_b32_e32 v23, v36
	v_mov_b32_e32 v24, v36
	v_mov_b32_e32 v25, v36
	v_mov_b32_e32 v26, v36
	v_mov_b32_e32 v27, v36
	v_mov_b32_e32 v28, v36
	v_mov_b32_e32 v29, v36
	v_mov_b32_e32 v30, v36
	v_mov_b32_e32 v31, v36
	v_mov_b32_e32 v32, v36
	v_mov_b32_e32 v33, v36
	v_mov_b32_e32 v34, v36
	v_mov_b32_e32 v35, v36
	v_mov_b32_e32 v44, v36
	v_mov_b32_e32 v45, v36
	v_mov_b32_e32 v46, v36
	v_mov_b32_e32 v47, v36
	v_mov_b32_e32 v48, v36
	v_mov_b32_e32 v49, v36
	v_mov_b32_e32 v50, v36
	v_mov_b32_e32 v51, v36
	v_mov_b32_e32 v52, v36
	v_mov_b32_e32 v53, v36
	v_mov_b32_e32 v54, v36
	v_mov_b32_e32 v55, v36
	v_mov_b32_e32 v56, v36
	v_mov_b32_e32 v57, v36
	v_mov_b32_e32 v58, v36
	v_mov_b32_e32 v59, v36
	v_mov_b32_e32 v60, v36
	v_mov_b32_e32 v61, v36
	v_mov_b32_e32 v62, v36
	v_mov_b32_e32 v63, v36
	v_mov_b32_e32 v64, v36
	v_mov_b32_e32 v65, v36
	v_mov_b32_e32 v66, v36
	v_mov_b32_e32 v67, v36
	v_mov_b32_e32 v68, v36
	v_mov_b32_e32 v69, v36
	v_mov_b32_e32 v70, v36
	v_mov_b32_e32 v71, v36
	v_mov_b32_e32 v72, v36
	v_mov_b32_e32 v73, v36
	v_mov_b32_e32 v74, v36
	v_mov_b32_e32 v75, v36
	v_mov_b32_e32 v76, v36
	v_mov_b32_e32 v77, v36
	v_mov_b32_e32 v78, v36
	v_mov_b32_e32 v79, v36
	v_mov_b32_e32 v80, v36
	v_mov_b32_e32 v81, v36
	v_mov_b32_e32 v82, v36
	v_mov_b32_e32 v83, v36
	v_mov_b32_e32 v84, v36
	v_mov_b32_e32 v85, v36
	v_mov_b32_e32 v86, v36
	v_mov_b32_e32 v87, v36
	v_mov_b32_e32 v88, v36
	v_mov_b32_e32 v89, v36
	v_mov_b32_e32 v90, v36
	v_mov_b32_e32 v91, v36
	v_mov_b32_e32 v92, v36
	v_mov_b32_e32 v93, v36
	v_mov_b32_e32 v94, v36
	v_mov_b32_e32 v95, v36
	v_mov_b32_e32 v96, v36
	v_mov_b32_e32 v97, v36
	v_mov_b32_e32 v98, v36
	v_mov_b32_e32 v99, v36
	v_mov_b32_e32 v100, v36
	v_mov_b32_e32 v101, v36
	v_mov_b32_e32 v102, v36
	v_mov_b32_e32 v103, v36
	v_mov_b32_e32 v104, v36
	v_mov_b32_e32 v105, v36
	v_mov_b32_e32 v106, v36
	v_mov_b32_e32 v107, v36
	v_mov_b32_e32 v108, v36
	v_mov_b32_e32 v109, v36
	v_mov_b32_e32 v110, v36
	v_mov_b32_e32 v111, v36
	v_mov_b32_e32 v112, v36
	v_mov_b32_e32 v113, v36
	v_mov_b32_e32 v114, v36
	v_mov_b32_e32 v115, v36
	v_mov_b32_e32 v116, v36
	v_mov_b32_e32 v117, v36
	v_mov_b32_e32 v118, v36
	v_mov_b32_e32 v119, v36
	v_mov_b32_e32 v120, v36
	v_mov_b32_e32 v121, v36
	v_mov_b32_e32 v122, v36
	v_mov_b32_e32 v123, v36
	v_mov_b32_e32 v124, v36
	v_mov_b32_e32 v125, v36
	v_mov_b32_e32 v126, v36
	v_mov_b32_e32 v127, v36
	s_waitcnt vmcnt(0) lgkmcnt(0)
	s_barrier
	v_add3_u32 v141, v135, v137, v138
	v_add3_u32 v210, v136, v137, v138
	v_add3_u32 v180, v135, v137, v139
	v_add3_u32 v211, v136, v137, v139
	v_xor_b32_e32 v212, 0x10000, v141
	v_xor_b32_e32 v213, 0x10000, v180
	v_xor_b32_e32 v214, 0x10000, v210
	v_xor_b32_e32 v215, 0x10000, v211
	v_readfirstlane_b32 s61, v134
	ds_read_b128 v[142:145], v141
	ds_read_b128 v[146:149], v141 offset:2048
	ds_read_b128 v[150:153], v141 offset:4096
	ds_read_b128 v[154:157], v141 offset:6144
	ds_read_b128 v[174:177], v210 offset:32768
	ds_read_b128 v[182:185], v210 offset:34816
	ds_read_b128 v[186:189], v210 offset:36864
	ds_read_b128 v[190:193], v210 offset:38912
	s_mov_b32 s47, 0
	s_mov_b64 s[48:49], s[34:35]
	v_subrev_u32_e32 v178, s34, v130
	v_subrev_u32_e32 v179, s34, v132
	s_add_u32 s61, s61, 0x10000
	s_mov_b32 m0, s61
	s_add_u32 s50, s48, s14
	s_addc_u32 s51, s49, s15
	global_load_lds_dwordx4 v178, s[50:51]
	s_add_u32 m0, s61, 0x2000
	s_add_u32 s50, s48, s16
	s_addc_u32 s51, s49, s17
	global_load_lds_dwordx4 v178, s[50:51]
	s_add_u32 m0, s61, 0x4000
	s_add_u32 s50, s48, s18
	s_addc_u32 s51, s49, s19
	global_load_lds_dwordx4 v178, s[50:51]
	s_add_u32 m0, s61, 0x6000
	s_add_u32 s50, s48, s22
	s_addc_u32 s51, s49, s23
	global_load_lds_dwordx4 v178, s[50:51]
	s_add_u32 m0, s61, 0x8000
	s_add_u32 s50, s48, s36
	s_addc_u32 s51, s49, s37
	global_load_lds_dwordx4 v179, s[50:51]
	s_add_u32 m0, s61, 0xa000
	s_add_u32 s50, s48, s40
	s_addc_u32 s51, s49, s41
	global_load_lds_dwordx4 v179, s[50:51]
	s_add_u32 m0, s61, 0xc000
	s_add_u32 s50, s48, s42
	s_addc_u32 s51, s49, s43
	global_load_lds_dwordx4 v179, s[50:51]
	s_add_u32 m0, s61, 0xe000
	s_add_u32 s50, s48, s44
	s_addc_u32 s51, s49, s45
	global_load_lds_dwordx4 v179, s[50:51]
	s_branch .Lg7_entry
.Lg7_top:
	s_waitcnt lgkmcnt(0)
	s_waitcnt vmcnt(0)
	s_barrier
	s_xor_b32 s61, s61, 0x10000
	ds_read_b128 v[142:145], v141
	ds_read_b128 v[146:149], v141 offset:2048
	ds_read_b128 v[150:153], v141 offset:4096
	ds_read_b128 v[154:157], v141 offset:6144
	ds_read_b128 v[174:177], v210 offset:32768
	ds_read_b128 v[182:185], v210 offset:34816
	ds_read_b128 v[186:189], v210 offset:36864
	ds_read_b128 v[190:193], v210 offset:38912
	v_mfma_f32_16x16x32_bf16 v[60:63], v[158:161], v[194:197], v[60:63]
	v_mfma_f32_16x16x32_bf16 v[56:59], v[158:161], v[198:201], v[56:59]
	s_mov_b32 m0, s61
	s_add_u32 s50, s48, s14
	s_addc_u32 s51, s49, s15
	global_load_lds_dwordx4 v178, s[50:51]
	v_mfma_f32_16x16x32_bf16 v[52:55], v[158:161], v[202:205], v[52:55]
	v_mfma_f32_16x16x32_bf16 v[48:51], v[158:161], v[206:209], v[48:51]
	s_add_u32 m0, s61, 0x2000
	s_add_u32 s50, s48, s16
	s_addc_u32 s51, s49, s17
	global_load_lds_dwordx4 v178, s[50:51]
	v_mfma_f32_16x16x32_bf16 v[44:47], v[162:165], v[194:197], v[44:47]
	v_mfma_f32_16x16x32_bf16 v[32:35], v[162:165], v[198:201], v[32:35]
	s_add_u32 m0, s61, 0x4000
	s_add_u32 s50, s48, s18
	s_addc_u32 s51, s49, s19
	global_load_lds_dwordx4 v178, s[50:51]
	v_mfma_f32_16x16x32_bf16 v[28:31], v[162:165], v[202:205], v[28:31]
	v_mfma_f32_16x16x32_bf16 v[24:27], v[162:165], v[206:209], v[24:27]
	s_add_u32 m0, s61, 0x6000
	s_add_u32 s50, s48, s22
	s_addc_u32 s51, s49, s23
	global_load_lds_dwordx4 v178, s[50:51]
	v_mfma_f32_16x16x32_bf16 v[20:23], v[166:169], v[194:197], v[20:23]
	v_mfma_f32_16x16x32_bf16 v[16:19], v[166:169], v[198:201], v[16:19]
	s_add_u32 m0, s61, 0x8000
	s_add_u32 s50, s48, s36
	s_addc_u32 s51, s49, s37
	global_load_lds_dwordx4 v179, s[50:51]
	v_mfma_f32_16x16x32_bf16 v[12:15], v[166:169], v[202:205], v[12:15]
	v_mfma_f32_16x16x32_bf16 v[8:11], v[166:169], v[206:209], v[8:11]
	s_add_u32 m0, s61, 0xa000
	s_add_u32 s50, s48, s40
	s_addc_u32 s51, s49, s41
	global_load_lds_dwordx4 v179, s[50:51]
	v_mfma_f32_16x16x32_bf16 v[4:7], v[170:173], v[194:197], v[4:7]
	v_mfma_f32_16x16x32_bf16 v[0:3], v[170:173], v[198:201], v[0:3]
	s_add_u32 m0, s61, 0xc000
	s_add_u32 s50, s48, s42
	s_addc_u32 s51, s49, s43
	global_load_lds_dwordx4 v179, s[50:51]
	v_mfma_f32_16x16x32_bf16 v[40:43], v[170:173], v[202:205], v[40:43]
	v_mfma_f32_16x16x32_bf16 v[36:39], v[170:173], v[206:209], v[36:39]
	s_add_u32 m0, s61, 0xe000
	s_add_u32 s50, s48, s44
	s_addc_u32 s51, s49, s45
	global_load_lds_dwordx4 v179, s[50:51]
.Lg7_entry:
	ds_read_b128 v[158:161], v141 offset:8192
	ds_read_b128 v[162:165], v141 offset:10240
	ds_read_b128 v[166:169], v141 offset:12288
	ds_read_b128 v[170:173], v141 offset:14336
	s_waitcnt lgkmcnt(4)
	v_mfma_f32_16x16x32_bf16 v[124:127], v[142:145], v[174:177], v[124:127]
	v_mfma_f32_16x16x32_bf16 v[120:123], v[142:145], v[182:185], v[120:123]
	v_mfma_f32_16x16x32_bf16 v[116:119], v[142:145], v[186:189], v[116:119]
	v_mfma_f32_16x16x32_bf16 v[112:115], v[142:145], v[190:193], v[112:115]
	v_mfma_f32_16x16x32_bf16 v[108:111], v[146:149], v[174:177], v[108:111]
	v_mfma_f32_16x16x32_bf16 v[104:107], v[146:149], v[182:185], v[104:107]
	v_mfma_f32_16x16x32_bf16 v[100:103], v[146:149], v[186:189], v[100:103]
	v_mfma_f32_16x16x32_bf16 v[96:99], v[146:149], v[190:193], v[96:99]
	v_mfma_f32_16x16x32_bf16 v[92:95], v[150:153], v[174:177], v[92:95]
	v_mfma_f32_16x16x32_bf16 v[88:91], v[150:153], v[182:185], v[88:91]
	v_mfma_f32_16x16x32_bf16 v[84:87], v[150:153], v[186:189], v[84:87]
	v_mfma_f32_16x16x32_bf16 v[80:83], v[150:153], v[190:193], v[80:83]
	v_mfma_f32_16x16x32_bf16 v[76:79], v[154:157], v[174:177], v[76:79]
	v_mfma_f32_16x16x32_bf16 v[72:75], v[154:157], v[182:185], v[72:75]
	v_mfma_f32_16x16x32_bf16 v[68:71], v[154:157], v[186:189], v[68:71]
	v_mfma_f32_16x16x32_bf16 v[64:67], v[154:157], v[190:193], v[64:67]
	ds_read_b128 v[142:145], v180
	ds_read_b128 v[146:149], v180 offset:2048
	ds_read_b128 v[150:153], v180 offset:4096
	ds_read_b128 v[154:157], v180 offset:6144
	ds_read_b128 v[194:197], v211 offset:32768
	ds_read_b128 v[198:201], v211 offset:34816
	ds_read_b128 v[202:205], v211 offset:36864
	ds_read_b128 v[206:209], v211 offset:38912
	s_waitcnt lgkmcnt(8)
	v_mfma_f32_16x16x32_bf16 v[60:63], v[158:161], v[174:177], v[60:63]
	v_mfma_f32_16x16x32_bf16 v[56:59], v[158:161], v[182:185], v[56:59]
	v_mfma_f32_16x16x32_bf16 v[52:55], v[158:161], v[186:189], v[52:55]
	v_mfma_f32_16x16x32_bf16 v[48:51], v[158:161], v[190:193], v[48:51]
	v_mfma_f32_16x16x32_bf16 v[44:47], v[162:165], v[174:177], v[44:47]
	v_mfma_f32_16x16x32_bf16 v[32:35], v[162:165], v[182:185], v[32:35]
	v_mfma_f32_16x16x32_bf16 v[28:31], v[162:165], v[186:189], v[28:31]
	v_mfma_f32_16x16x32_bf16 v[24:27], v[162:165], v[190:193], v[24:27]
	v_mfma_f32_16x16x32_bf16 v[20:23], v[166:169], v[174:177], v[20:23]
	v_mfma_f32_16x16x32_bf16 v[16:19], v[166:169], v[182:185], v[16:19]
	v_mfma_f32_16x16x32_bf16 v[12:15], v[166:169], v[186:189], v[12:15]
	v_mfma_f32_16x16x32_bf16 v[8:11], v[166:169], v[190:193], v[8:11]
	v_mfma_f32_16x16x32_bf16 v[4:7], v[170:173], v[174:177], v[4:7]
	v_mfma_f32_16x16x32_bf16 v[0:3], v[170:173], v[182:185], v[0:3]
	v_mfma_f32_16x16x32_bf16 v[40:43], v[170:173], v[186:189], v[40:43]
	v_mfma_f32_16x16x32_bf16 v[36:39], v[170:173], v[190:193], v[36:39]
	ds_read_b128 v[158:161], v180 offset:8192
	ds_read_b128 v[162:165], v180 offset:10240
	ds_read_b128 v[166:169], v180 offset:12288
	ds_read_b128 v[170:173], v180 offset:14336
	s_waitcnt lgkmcnt(4)
	v_mfma_f32_16x16x32_bf16 v[124:127], v[142:145], v[194:197], v[124:127]
	v_mfma_f32_16x16x32_bf16 v[120:123], v[142:145], v[198:201], v[120:123]
	v_mfma_f32_16x16x32_bf16 v[116:119], v[142:145], v[202:205], v[116:119]
	v_mfma_f32_16x16x32_bf16 v[112:115], v[142:145], v[206:209], v[112:115]
	v_mfma_f32_16x16x32_bf16 v[108:111], v[146:149], v[194:197], v[108:111]
	v_mfma_f32_16x16x32_bf16 v[104:107], v[146:149], v[198:201], v[104:107]
	v_mfma_f32_16x16x32_bf16 v[100:103], v[146:149], v[202:205], v[100:103]
	v_mfma_f32_16x16x32_bf16 v[96:99], v[146:149], v[206:209], v[96:99]
	v_mfma_f32_16x16x32_bf16 v[92:95], v[150:153], v[194:197], v[92:95]
	v_mfma_f32_16x16x32_bf16 v[88:91], v[150:153], v[198:201], v[88:91]
	v_mfma_f32_16x16x32_bf16 v[84:87], v[150:153], v[202:205], v[84:87]
	v_mfma_f32_16x16x32_bf16 v[80:83], v[150:153], v[206:209], v[80:83]
	v_mfma_f32_16x16x32_bf16 v[76:79], v[154:157], v[194:197], v[76:79]
	v_mfma_f32_16x16x32_bf16 v[72:75], v[154:157], v[198:201], v[72:75]
	v_mfma_f32_16x16x32_bf16 v[68:71], v[154:157], v[202:205], v[68:71]
	v_mfma_f32_16x16x32_bf16 v[64:67], v[154:157], v[206:209], v[64:67]
	s_add_u32 s48, s48, 0x80
	s_addc_u32 s49, s49, 0
	s_add_i32 s47, s47, 1
	s_cmp_lt_u32 s47, 31
	s_cbranch_scc0 .Lg7_last
	s_waitcnt lgkmcnt(0)
	s_waitcnt vmcnt(0)
	s_barrier
	s_xor_b32 s61, s61, 0x10000
	ds_read_b128 v[142:145], v212
	ds_read_b128 v[146:149], v212 offset:2048
	ds_read_b128 v[150:153], v212 offset:4096
	ds_read_b128 v[154:157], v212 offset:6144
	ds_read_b128 v[174:177], v214 offset:32768
	ds_read_b128 v[182:185], v214 offset:34816
	ds_read_b128 v[186:189], v214 offset:36864
	ds_read_b128 v[190:193], v214 offset:38912
	v_mfma_f32_16x16x32_bf16 v[60:63], v[158:161], v[194:197], v[60:63]
	v_mfma_f32_16x16x32_bf16 v[56:59], v[158:161], v[198:201], v[56:59]
	s_mov_b32 m0, s61
	s_add_u32 s50, s48, s14
	s_addc_u32 s51, s49, s15
	global_load_lds_dwordx4 v178, s[50:51]
	v_mfma_f32_16x16x32_bf16 v[52:55], v[158:161], v[202:205], v[52:55]
	v_mfma_f32_16x16x32_bf16 v[48:51], v[158:161], v[206:209], v[48:51]
	s_add_u32 m0, s61, 0x2000
	s_add_u32 s50, s48, s16
	s_addc_u32 s51, s49, s17
	global_load_lds_dwordx4 v178, s[50:51]
	v_mfma_f32_16x16x32_bf16 v[44:47], v[162:165], v[194:197], v[44:47]
	v_mfma_f32_16x16x32_bf16 v[32:35], v[162:165], v[198:201], v[32:35]
	s_add_u32 m0, s61, 0x4000
	s_add_u32 s50, s48, s18
	s_addc_u32 s51, s49, s19
	global_load_lds_dwordx4 v178, s[50:51]
	v_mfma_f32_16x16x32_bf16 v[28:31], v[162:165], v[202:205], v[28:31]
	v_mfma_f32_16x16x32_bf16 v[24:27], v[162:165], v[206:209], v[24:27]
	s_add_u32 m0, s61, 0x6000
	s_add_u32 s50, s48, s22
	s_addc_u32 s51, s49, s23
	global_load_lds_dwordx4 v178, s[50:51]
	v_mfma_f32_16x16x32_bf16 v[20:23], v[166:169], v[194:197], v[20:23]
	v_mfma_f32_16x16x32_bf16 v[16:19], v[166:169], v[198:201], v[16:19]
	s_add_u32 m0, s61, 0x8000
	s_add_u32 s50, s48, s36
	s_addc_u32 s51, s49, s37
	global_load_lds_dwordx4 v179, s[50:51]
	v_mfma_f32_16x16x32_bf16 v[12:15], v[166:169], v[202:205], v[12:15]
	v_mfma_f32_16x16x32_bf16 v[8:11], v[166:169], v[206:209], v[8:11]
	s_add_u32 m0, s61, 0xa000
	s_add_u32 s50, s48, s40
	s_addc_u32 s51, s49, s41
	global_load_lds_dwordx4 v179, s[50:51]
	v_mfma_f32_16x16x32_bf16 v[4:7], v[170:173], v[194:197], v[4:7]
	v_mfma_f32_16x16x32_bf16 v[0:3], v[170:173], v[198:201], v[0:3]
	s_add_u32 m0, s61, 0xc000
	s_add_u32 s50, s48, s42
	s_addc_u32 s51, s49, s43
	global_load_lds_dwordx4 v179, s[50:51]
	v_mfma_f32_16x16x32_bf16 v[40:43], v[170:173], v[202:205], v[40:43]
	v_mfma_f32_16x16x32_bf16 v[36:39], v[170:173], v[206:209], v[36:39]
	s_add_u32 m0, s61, 0xe000
	s_add_u32 s50, s48, s44
	s_addc_u32 s51, s49, s45
	global_load_lds_dwordx4 v179, s[50:51]
	ds_read_b128 v[158:161], v212 offset:8192
	ds_read_b128 v[162:165], v212 offset:10240
	ds_read_b128 v[166:169], v212 offset:12288
	ds_read_b128 v[170:173], v212 offset:14336
	s_waitcnt lgkmcnt(4)
	v_mfma_f32_16x16x32_bf16 v[124:127], v[142:145], v[174:177], v[124:127]
	v_mfma_f32_16x16x32_bf16 v[120:123], v[142:145], v[182:185], v[120:123]
	v_mfma_f32_16x16x32_bf16 v[116:119], v[142:145], v[186:189], v[116:119]
	v_mfma_f32_16x16x32_bf16 v[112:115], v[142:145], v[190:193], v[112:115]
	v_mfma_f32_16x16x32_bf16 v[108:111], v[146:149], v[174:177], v[108:111]
	v_mfma_f32_16x16x32_bf16 v[104:107], v[146:149], v[182:185], v[104:107]
	v_mfma_f32_16x16x32_bf16 v[100:103], v[146:149], v[186:189], v[100:103]
	v_mfma_f32_16x16x32_bf16 v[96:99], v[146:149], v[190:193], v[96:99]
	v_mfma_f32_16x16x32_bf16 v[92:95], v[150:153], v[174:177], v[92:95]
	v_mfma_f32_16x16x32_bf16 v[88:91], v[150:153], v[182:185], v[88:91]
	v_mfma_f32_16x16x32_bf16 v[84:87], v[150:153], v[186:189], v[84:87]
	v_mfma_f32_16x16x32_bf16 v[80:83], v[150:153], v[190:193], v[80:83]
	v_mfma_f32_16x16x32_bf16 v[76:79], v[154:157], v[174:177], v[76:79]
	v_mfma_f32_16x16x32_bf16 v[72:75], v[154:157], v[182:185], v[72:75]
	v_mfma_f32_16x16x32_bf16 v[68:71], v[154:157], v[186:189], v[68:71]
	v_mfma_f32_16x16x32_bf16 v[64:67], v[154:157], v[190:193], v[64:67]
	ds_read_b128 v[142:145], v213
	ds_read_b128 v[146:149], v213 offset:2048
	ds_read_b128 v[150:153], v213 offset:4096
	ds_read_b128 v[154:157], v213 offset:6144
	ds_read_b128 v[194:197], v215 offset:32768
	ds_read_b128 v[198:201], v215 offset:34816
	ds_read_b128 v[202:205], v215 offset:36864
	ds_read_b128 v[206:209], v215 offset:38912
	s_waitcnt lgkmcnt(8)
	v_mfma_f32_16x16x32_bf16 v[60:63], v[158:161], v[174:177], v[60:63]
	v_mfma_f32_16x16x32_bf16 v[56:59], v[158:161], v[182:185], v[56:59]
	v_mfma_f32_16x16x32_bf16 v[52:55], v[158:161], v[186:189], v[52:55]
	v_mfma_f32_16x16x32_bf16 v[48:51], v[158:161], v[190:193], v[48:51]
	v_mfma_f32_16x16x32_bf16 v[44:47], v[162:165], v[174:177], v[44:47]
	v_mfma_f32_16x16x32_bf16 v[32:35], v[162:165], v[182:185], v[32:35]
	v_mfma_f32_16x16x32_bf16 v[28:31], v[162:165], v[186:189], v[28:31]
	v_mfma_f32_16x16x32_bf16 v[24:27], v[162:165], v[190:193], v[24:27]
	v_mfma_f32_16x16x32_bf16 v[20:23], v[166:169], v[174:177], v[20:23]
	v_mfma_f32_16x16x32_bf16 v[16:19], v[166:169], v[182:185], v[16:19]
	v_mfma_f32_16x16x32_bf16 v[12:15], v[166:169], v[186:189], v[12:15]
	v_mfma_f32_16x16x32_bf16 v[8:11], v[166:169], v[190:193], v[8:11]
	v_mfma_f32_16x16x32_bf16 v[4:7], v[170:173], v[174:177], v[4:7]
	v_mfma_f32_16x16x32_bf16 v[0:3], v[170:173], v[182:185], v[0:3]
	v_mfma_f32_16x16x32_bf16 v[40:43], v[170:173], v[186:189], v[40:43]
	v_mfma_f32_16x16x32_bf16 v[36:39], v[170:173], v[190:193], v[36:39]
	ds_read_b128 v[158:161], v213 offset:8192
	ds_read_b128 v[162:165], v213 offset:10240
	ds_read_b128 v[166:169], v213 offset:12288
	ds_read_b128 v[170:173], v213 offset:14336
	s_waitcnt lgkmcnt(4)
	v_mfma_f32_16x16x32_bf16 v[124:127], v[142:145], v[194:197], v[124:127]
	v_mfma_f32_16x16x32_bf16 v[120:123], v[142:145], v[198:201], v[120:123]
	v_mfma_f32_16x16x32_bf16 v[116:119], v[142:145], v[202:205], v[116:119]
	v_mfma_f32_16x16x32_bf16 v[112:115], v[142:145], v[206:209], v[112:115]
	v_mfma_f32_16x16x32_bf16 v[108:111], v[146:149], v[194:197], v[108:111]
	v_mfma_f32_16x16x32_bf16 v[104:107], v[146:149], v[198:201], v[104:107]
	v_mfma_f32_16x16x32_bf16 v[100:103], v[146:149], v[202:205], v[100:103]
	v_mfma_f32_16x16x32_bf16 v[96:99], v[146:149], v[206:209], v[96:99]
	v_mfma_f32_16x16x32_bf16 v[92:95], v[150:153], v[194:197], v[92:95]
	v_mfma_f32_16x16x32_bf16 v[88:91], v[150:153], v[198:201], v[88:91]
	v_mfma_f32_16x16x32_bf16 v[84:87], v[150:153], v[202:205], v[84:87]
	v_mfma_f32_16x16x32_bf16 v[80:83], v[150:153], v[206:209], v[80:83]
	v_mfma_f32_16x16x32_bf16 v[76:79], v[154:157], v[194:197], v[76:79]
	v_mfma_f32_16x16x32_bf16 v[72:75], v[154:157], v[198:201], v[72:75]
	v_mfma_f32_16x16x32_bf16 v[68:71], v[154:157], v[202:205], v[68:71]
	v_mfma_f32_16x16x32_bf16 v[64:67], v[154:157], v[206:209], v[64:67]
	s_add_u32 s48, s48, 0x80
	s_addc_u32 s49, s49, 0
	s_add_i32 s47, s47, 1
	s_branch .Lg7_top
.Lg7_last:
	s_waitcnt lgkmcnt(0)
	s_waitcnt vmcnt(0)
	s_barrier
	s_xor_b32 s61, s61, 0x10000
	ds_read_b128 v[142:145], v212
	ds_read_b128 v[146:149], v212 offset:2048
	ds_read_b128 v[150:153], v212 offset:4096
	ds_read_b128 v[154:157], v212 offset:6144
	ds_read_b128 v[174:177], v214 offset:32768
	ds_read_b128 v[182:185], v214 offset:34816
	ds_read_b128 v[186:189], v214 offset:36864
	ds_read_b128 v[190:193], v214 offset:38912
	v_mfma_f32_16x16x32_bf16 v[60:63], v[158:161], v[194:197], v[60:63]
	v_mfma_f32_16x16x32_bf16 v[56:59], v[158:161], v[198:201], v[56:59]
	v_mfma_f32_16x16x32_bf16 v[52:55], v[158:161], v[202:205], v[52:55]
	v_mfma_f32_16x16x32_bf16 v[48:51], v[158:161], v[206:209], v[48:51]
	v_mfma_f32_16x16x32_bf16 v[44:47], v[162:165], v[194:197], v[44:47]
	v_mfma_f32_16x16x32_bf16 v[32:35], v[162:165], v[198:201], v[32:35]
	v_mfma_f32_16x16x32_bf16 v[28:31], v[162:165], v[202:205], v[28:31]
	v_mfma_f32_16x16x32_bf16 v[24:27], v[162:165], v[206:209], v[24:27]
	v_mfma_f32_16x16x32_bf16 v[20:23], v[166:169], v[194:197], v[20:23]
	v_mfma_f32_16x16x32_bf16 v[16:19], v[166:169], v[198:201], v[16:19]
	v_mfma_f32_16x16x32_bf16 v[12:15], v[166:169], v[202:205], v[12:15]
	v_mfma_f32_16x16x32_bf16 v[8:11], v[166:169], v[206:209], v[8:11]
	v_mfma_f32_16x16x32_bf16 v[4:7], v[170:173], v[194:197], v[4:7]
	v_mfma_f32_16x16x32_bf16 v[0:3], v[170:173], v[198:201], v[0:3]
	v_mfma_f32_16x16x32_bf16 v[40:43], v[170:173], v[202:205], v[40:43]
	v_mfma_f32_16x16x32_bf16 v[36:39], v[170:173], v[206:209], v[36:39]
	ds_read_b128 v[158:161], v212 offset:8192
	ds_read_b128 v[162:165], v212 offset:10240
	ds_read_b128 v[166:169], v212 offset:12288
	ds_read_b128 v[170:173], v212 offset:14336
	s_waitcnt lgkmcnt(4)
	v_mfma_f32_16x16x32_bf16 v[124:127], v[142:145], v[174:177], v[124:127]
	v_mfma_f32_16x16x32_bf16 v[120:123], v[142:145], v[182:185], v[120:123]
	v_mfma_f32_16x16x32_bf16 v[116:119], v[142:145], v[186:189], v[116:119]
	v_mfma_f32_16x16x32_bf16 v[112:115], v[142:145], v[190:193], v[112:115]
	v_mfma_f32_16x16x32_bf16 v[108:111], v[146:149], v[174:177], v[108:111]
	v_mfma_f32_16x16x32_bf16 v[104:107], v[146:149], v[182:185], v[104:107]
	v_mfma_f32_16x16x32_bf16 v[100:103], v[146:149], v[186:189], v[100:103]
	v_mfma_f32_16x16x32_bf16 v[96:99], v[146:149], v[190:193], v[96:99]
	v_mfma_f32_16x16x32_bf16 v[92:95], v[150:153], v[174:177], v[92:95]
	v_mfma_f32_16x16x32_bf16 v[88:91], v[150:153], v[182:185], v[88:91]
	v_mfma_f32_16x16x32_bf16 v[84:87], v[150:153], v[186:189], v[84:87]
	v_mfma_f32_16x16x32_bf16 v[80:83], v[150:153], v[190:193], v[80:83]
	v_mfma_f32_16x16x32_bf16 v[76:79], v[154:157], v[174:177], v[76:79]
	v_mfma_f32_16x16x32_bf16 v[72:75], v[154:157], v[182:185], v[72:75]
	v_mfma_f32_16x16x32_bf16 v[68:71], v[154:157], v[186:189], v[68:71]
	v_mfma_f32_16x16x32_bf16 v[64:67], v[154:157], v[190:193], v[64:67]
	ds_read_b128 v[142:145], v213
	ds_read_b128 v[146:149], v213 offset:2048
	ds_read_b128 v[150:153], v213 offset:4096
	ds_read_b128 v[154:157], v213 offset:6144
	ds_read_b128 v[194:197], v215 offset:32768
	ds_read_b128 v[198:201], v215 offset:34816
	ds_read_b128 v[202:205], v215 offset:36864
	ds_read_b128 v[206:209], v215 offset:38912
	s_waitcnt lgkmcnt(8)
	v_mfma_f32_16x16x32_bf16 v[60:63], v[158:161], v[174:177], v[60:63]
	v_mfma_f32_16x16x32_bf16 v[56:59], v[158:161], v[182:185], v[56:59]
	v_mfma_f32_16x16x32_bf16 v[52:55], v[158:161], v[186:189], v[52:55]
	v_mfma_f32_16x16x32_bf16 v[48:51], v[158:161], v[190:193], v[48:51]
	v_mfma_f32_16x16x32_bf16 v[44:47], v[162:165], v[174:177], v[44:47]
	v_mfma_f32_16x16x32_bf16 v[32:35], v[162:165], v[182:185], v[32:35]
	v_mfma_f32_16x16x32_bf16 v[28:31], v[162:165], v[186:189], v[28:31]
	v_mfma_f32_16x16x32_bf16 v[24:27], v[162:165], v[190:193], v[24:27]
	v_mfma_f32_16x16x32_bf16 v[20:23], v[166:169], v[174:177], v[20:23]
	v_mfma_f32_16x16x32_bf16 v[16:19], v[166:169], v[182:185], v[16:19]
	v_mfma_f32_16x16x32_bf16 v[12:15], v[166:169], v[186:189], v[12:15]
	v_mfma_f32_16x16x32_bf16 v[8:11], v[166:169], v[190:193], v[8:11]
	v_mfma_f32_16x16x32_bf16 v[4:7], v[170:173], v[174:177], v[4:7]
	v_mfma_f32_16x16x32_bf16 v[0:3], v[170:173], v[182:185], v[0:3]
	v_mfma_f32_16x16x32_bf16 v[40:43], v[170:173], v[186:189], v[40:43]
	v_mfma_f32_16x16x32_bf16 v[36:39], v[170:173], v[190:193], v[36:39]
	ds_read_b128 v[158:161], v213 offset:8192
	ds_read_b128 v[162:165], v213 offset:10240
	ds_read_b128 v[166:169], v213 offset:12288
	ds_read_b128 v[170:173], v213 offset:14336
	s_waitcnt lgkmcnt(4)
	v_mfma_f32_16x16x32_bf16 v[124:127], v[142:145], v[194:197], v[124:127]
	v_mfma_f32_16x16x32_bf16 v[120:123], v[142:145], v[198:201], v[120:123]
	v_mfma_f32_16x16x32_bf16 v[116:119], v[142:145], v[202:205], v[116:119]
	v_mfma_f32_16x16x32_bf16 v[112:115], v[142:145], v[206:209], v[112:115]
	v_mfma_f32_16x16x32_bf16 v[108:111], v[146:149], v[194:197], v[108:111]
	v_mfma_f32_16x16x32_bf16 v[104:107], v[146:149], v[198:201], v[104:107]
	v_mfma_f32_16x16x32_bf16 v[100:103], v[146:149], v[202:205], v[100:103]
	v_mfma_f32_16x16x32_bf16 v[96:99], v[146:149], v[206:209], v[96:99]
	v_mfma_f32_16x16x32_bf16 v[92:95], v[150:153], v[194:197], v[92:95]
	v_mfma_f32_16x16x32_bf16 v[88:91], v[150:153], v[198:201], v[88:91]
	v_mfma_f32_16x16x32_bf16 v[84:87], v[150:153], v[202:205], v[84:87]
	v_mfma_f32_16x16x32_bf16 v[80:83], v[150:153], v[206:209], v[80:83]
	v_mfma_f32_16x16x32_bf16 v[76:79], v[154:157], v[194:197], v[76:79]
	v_mfma_f32_16x16x32_bf16 v[72:75], v[154:157], v[198:201], v[72:75]
	v_mfma_f32_16x16x32_bf16 v[68:71], v[154:157], v[202:205], v[68:71]
	v_mfma_f32_16x16x32_bf16 v[64:67], v[154:157], v[206:209], v[64:67]
	s_add_u32 s48, s48, 0x80
	s_addc_u32 s49, s49, 0
	s_add_i32 s47, s47, 1
	s_waitcnt lgkmcnt(0)
	s_waitcnt vmcnt(0)
	s_barrier
	v_mfma_f32_16x16x32_bf16 v[60:63], v[158:161], v[194:197], v[60:63]
	v_mfma_f32_16x16x32_bf16 v[56:59], v[158:161], v[198:201], v[56:59]
	v_mfma_f32_16x16x32_bf16 v[52:55], v[158:161], v[202:205], v[52:55]
	v_mfma_f32_16x16x32_bf16 v[48:51], v[158:161], v[206:209], v[48:51]
	v_mfma_f32_16x16x32_bf16 v[44:47], v[162:165], v[194:197], v[44:47]
	v_mfma_f32_16x16x32_bf16 v[32:35], v[162:165], v[198:201], v[32:35]
	v_mfma_f32_16x16x32_bf16 v[28:31], v[162:165], v[202:205], v[28:31]
	v_mfma_f32_16x16x32_bf16 v[24:27], v[162:165], v[206:209], v[24:27]
	v_mfma_f32_16x16x32_bf16 v[20:23], v[166:169], v[194:197], v[20:23]
	v_mfma_f32_16x16x32_bf16 v[16:19], v[166:169], v[198:201], v[16:19]
	v_mfma_f32_16x16x32_bf16 v[12:15], v[166:169], v[202:205], v[12:15]
	v_mfma_f32_16x16x32_bf16 v[8:11], v[166:169], v[206:209], v[8:11]
	v_mfma_f32_16x16x32_bf16 v[4:7], v[170:173], v[194:197], v[4:7]
	v_mfma_f32_16x16x32_bf16 v[0:3], v[170:173], v[198:201], v[0:3]
	v_mfma_f32_16x16x32_bf16 v[40:43], v[170:173], v[202:205], v[40:43]
	v_mfma_f32_16x16x32_bf16 v[36:39], v[170:173], v[206:209], v[36:39]
	s_nop 7
	s_nop 7
	s_sub_u32 s48, s48, s34
	s_subb_u32 s49, s49, s35
	s_mov_b32 s61, 0x100000
	s_mov_b32 s62, 0x100000
	s_mov_b64 s[50:51], 0
	s_mov_b64 vcc, exec
	s_branch .LBB0_745

.LBB0_933:
	s_mul_hi_i32 s21, s70, 0x2e8ba2e9
	s_lshr_b32 s56, s21, 31
	s_ashr_i32 s71, s21, 4
	s_add_i32 s71, s71, s56
	s_and_b32 s20, s70, 7
	s_lshl_b32 s62, s71, 3
	s_or_b32 s58, s62, s20
	s_ashr_i32 s20, s70, 3
	s_mul_hi_i32 s21, s20, 0x2e8ba2e9
	v_mov_b32_e32 v6, v181
	s_lshr_b32 s56, s21, 31
	s_ashr_i32 s21, s21, 1
	s_add_i32 s21, s21, s56
	v_lshrrev_b32_e32 v7, 4, v6
	v_lshlrev_b32_e32 v1, 6, v6
	v_xor_b32_e32 v0, v7, v6
	v_and_b32_e32 v8, 0x3c0, v1
	v_lshlrev_b32_e32 v1, 7, v6
	s_mul_i32 s21, s21, 11
	s_ashr_i32 s59, s58, 31
	v_lshlrev_b32_e32 v0, 3, v0
	v_and_b32_e32 v1, 0xfffffc00, v1
	s_and_b32 s64, s69, 7
	s_sub_i32 s56, s20, s21
	s_lshl_b64 s[20:21], s[58:59], 19
	v_and_or_b32 v0, v0, 56, v1
	s_add_u32 s20, s3, s20
	v_ashrrev_i32_e32 v1, 31, v0
	s_addc_u32 s21, s66, s21
	v_lshlrev_b64 v[0:1], 1, v[0:1]
	v_lshl_add_u32 v130, v6, 4, 0
	v_lshl_add_u64 v[2:3], s[20:21], 0, v[0:1]
	v_readfirstlane_b32 s20, v130
	v_add_u32_e32 v9, 0x2000, v130
	s_mov_b32 m0, s20
	v_readfirstlane_b32 s20, v9
	v_add_u32_e32 v9, 0x4000, v130
	s_waitcnt vmcnt(63) expcnt(7) lgkmcnt(15)
	s_barrier
	global_load_lds_dwordx4 v[2:3], off
	v_lshl_add_u64 v[4:5], v[2:3], 0, s[14:15]
	s_mov_b32 m0, s20
	v_readfirstlane_b32 s20, v9
	global_load_lds_dwordx4 v[4:5], off
	v_lshl_add_u64 v[4:5], v[2:3], 0, s[16:17]
	s_mov_b32 m0, s20
	s_ashr_i32 s57, s56, 31
	global_load_lds_dwordx4 v[4:5], off
	v_add_u32_e32 v4, 0x6000, v130
	s_lshl_b64 s[60:61], s[56:57], 19
	v_readfirstlane_b32 s20, v4
	v_lshl_add_u64 v[2:3], v[2:3], 0, s[18:19]
	s_mov_b32 m0, s20
	s_add_u32 s60, s34, s60
	global_load_lds_dwordx4 v[2:3], off
	v_add_u32_e32 v2, 0x8000, v130
	s_addc_u32 s61, s35, s61
	v_readfirstlane_b32 s20, v2
	v_add_u32_e32 v4, 0xa000, v130
	v_lshl_add_u64 v[140:141], s[60:61], 0, v[0:1]
	s_mov_b32 m0, s20
	v_readfirstlane_b32 s20, v4
	v_add_u32_e32 v4, 0xc000, v130
	global_load_lds_dwordx4 v[140:141], off
	v_lshl_add_u64 v[2:3], v[140:141], 0, s[14:15]
	s_mov_b32 m0, s20
	v_readfirstlane_b32 s20, v4
	v_add_u32_e32 v4, 0xe000, v130
	global_load_lds_dwordx4 v[2:3], off
	v_lshl_add_u64 v[2:3], v[140:141], 0, s[16:17]
	s_mov_b32 m0, s20
	v_readfirstlane_b32 s20, v4
	global_load_lds_dwordx4 v[2:3], off
	v_lshl_add_u64 v[2:3], v[140:141], 0, s[18:19]
	s_mov_b32 m0, s20
	v_ashrrev_i32_e32 v4, 6, v6
	global_load_lds_dwordx4 v[2:3], off
	v_lshrrev_b32_e32 v5, 30, v4
	v_add_u32_e32 v5, v4, v5
	s_or_b32 s20, s62, s64
	v_bfe_u32 v2, v6, 4, 2
	v_bfe_u32 v3, v6, 1, 3
	v_and_b32_e32 v6, 0x7fffc, v5
	s_ashr_i32 s21, s20, 31
	v_sub_u32_e32 v4, v4, v6
	s_lshl_b64 s[20:21], s[20:21], 19
	v_lshlrev_b32_e32 v150, 13, v4
	v_bitop3_b32 v4, v7, v3, 3 bitop3:0x6c
	v_bitop3_b32 v2, v2, v3, 4 bitop3:0x36
	s_add_u32 s20, s34, s20
	v_lshlrev_b32_e32 v5, 12, v5
	v_lshlrev_b32_e32 v4, 3, v4
	v_lshlrev_b32_e32 v2, 3, v2
	s_addc_u32 s21, s35, s21
	v_and_b32_e32 v149, 0xffffc000, v5
	v_lshl_add_u64 v[142:143], s[20:21], 0, v[0:1]
	s_mov_b64 s[60:61], 0
	v_lshlrev_b32_e32 v151, 1, v8
	v_lshlrev_b32_e32 v152, 1, v4
	v_lshlrev_b32_e32 v153, 1, v2
	s_mov_b32 s59, 0
	s_mov_b32 s57, 0
	v_mov_b32_e32 v40, 0
	v_mov_b32_e32 v41, v131
	v_mov_b32_e32 v42, v131
	v_mov_b32_e32 v43, v131
	v_mov_b32_e32 v48, 0
	v_mov_b32_e32 v49, v131
	v_mov_b32_e32 v50, v131
	v_mov_b32_e32 v51, v131
	v_mov_b32_e32 v0, 0
	v_mov_b32_e32 v1, v131
	v_mov_b32_e32 v2, v131
	v_mov_b32_e32 v3, v131
	v_mov_b32_e32 v4, 0
	v_mov_b32_e32 v5, v131
	v_mov_b32_e32 v6, v131
	v_mov_b32_e32 v7, v131
	v_mov_b32_e32 v8, 0
	v_mov_b32_e32 v9, v131
	v_mov_b32_e32 v10, v131
	v_mov_b32_e32 v11, v131
	v_mov_b32_e32 v12, 0
	v_mov_b32_e32 v13, v131
	v_mov_b32_e32 v14, v131
	v_mov_b32_e32 v15, v131
	v_mov_b32_e32 v16, 0
	v_mov_b32_e32 v17, v131
	v_mov_b32_e32 v18, v131
	v_mov_b32_e32 v19, v131
	v_mov_b32_e32 v20, 0
	v_mov_b32_e32 v21, v131
	v_mov_b32_e32 v22, v131
	v_mov_b32_e32 v23, v131
	v_mov_b32_e32 v24, 0
	v_mov_b32_e32 v25, v131
	v_mov_b32_e32 v26, v131
	v_mov_b32_e32 v27, v131
	v_mov_b32_e32 v28, 0
	v_mov_b32_e32 v29, v131
	v_mov_b32_e32 v30, v131
	v_mov_b32_e32 v31, v131
	v_mov_b32_e32 v32, 0
	v_mov_b32_e32 v33, v131
	v_mov_b32_e32 v34, v131
	v_mov_b32_e32 v35, v131
	v_mov_b32_e32 v36, 0
	v_mov_b32_e32 v37, v131
	v_mov_b32_e32 v38, v131
	v_mov_b32_e32 v39, v131
	v_mov_b32_e32 v44, 0
	v_mov_b32_e32 v45, v131
	v_mov_b32_e32 v46, v131
	v_mov_b32_e32 v47, v131
	v_mov_b32_e32 v52, 0
	v_mov_b32_e32 v53, v131
	v_mov_b32_e32 v54, v131
	v_mov_b32_e32 v55, v131
	v_mov_b32_e32 v56, 0
	v_mov_b32_e32 v57, v131
	v_mov_b32_e32 v58, v131
	v_mov_b32_e32 v59, v131
	v_mov_b32_e32 v60, 0
	v_mov_b32_e32 v61, v131
	v_mov_b32_e32 v62, v131
	v_mov_b32_e32 v63, v131
	v_mov_b32_e32 v64, 0
	v_mov_b32_e32 v65, v131
	v_mov_b32_e32 v66, v131
	v_mov_b32_e32 v67, v131
	v_mov_b32_e32 v68, 0
	v_mov_b32_e32 v69, v131
	v_mov_b32_e32 v70, v131
	v_mov_b32_e32 v71, v131
	v_mov_b32_e32 v72, 0
	v_mov_b32_e32 v73, v131
	v_mov_b32_e32 v74, v131
	v_mov_b32_e32 v75, v131
	v_mov_b32_e32 v76, 0
	v_mov_b32_e32 v77, v131
	v_mov_b32_e32 v78, v131
	v_mov_b32_e32 v79, v131
	v_mov_b32_e32 v80, 0
	v_mov_b32_e32 v81, v131
	v_mov_b32_e32 v82, v131
	v_mov_b32_e32 v83, v131
	v_mov_b32_e32 v84, 0
	v_mov_b32_e32 v85, v131
	v_mov_b32_e32 v86, v131
	v_mov_b32_e32 v87, v131
	v_mov_b32_e32 v88, 0
	v_mov_b32_e32 v89, v131
	v_mov_b32_e32 v90, v131
	v_mov_b32_e32 v91, v131
	v_mov_b32_e32 v92, 0
	v_mov_b32_e32 v93, v131
	v_mov_b32_e32 v94, v131
	v_mov_b32_e32 v95, v131
	v_mov_b32_e32 v96, 0
	v_mov_b32_e32 v97, v131
	v_mov_b32_e32 v98, v131
	v_mov_b32_e32 v99, v131
	v_mov_b32_e32 v100, 0
	v_mov_b32_e32 v101, v131
	v_mov_b32_e32 v102, v131
	v_mov_b32_e32 v103, v131
	v_mov_b32_e32 v104, 0
	v_mov_b32_e32 v105, v131
	v_mov_b32_e32 v106, v131
	v_mov_b32_e32 v107, v131
	v_mov_b32_e32 v108, 0
	v_mov_b32_e32 v109, v131
	v_mov_b32_e32 v110, v131
	v_mov_b32_e32 v111, v131
	v_mov_b32_e32 v112, 0
	v_mov_b32_e32 v113, v131
	v_mov_b32_e32 v114, v131
	v_mov_b32_e32 v115, v131
	v_mov_b32_e32 v116, 0
	v_mov_b32_e32 v117, v131
	v_mov_b32_e32 v118, v131
	v_mov_b32_e32 v119, v131
	v_mov_b32_e32 v120, 0
	v_mov_b32_e32 v121, v131
	v_mov_b32_e32 v122, v131
	v_mov_b32_e32 v123, v131
	v_mov_b32_e32 v124, 0
	v_mov_b32_e32 v125, v131
	v_mov_b32_e32 v126, v131
	v_mov_b32_e32 v127, v131
	s_waitcnt vmcnt(0) lgkmcnt(0)
	s_barrier
	v_add3_u32 v180, v149, v151, v152
	v_add3_u32 v223, v150, v151, v152
	v_add3_u32 v222, v149, v151, v153
	v_add3_u32 v224, v150, v151, v153
	v_xor_b32_e32 v225, 0x10000, v180
	v_xor_b32_e32 v226, 0x10000, v222
	v_xor_b32_e32 v227, 0x10000, v223
	v_xor_b32_e32 v228, 0x10000, v224
	v_readfirstlane_b32 s59, v130
	ds_read_b128 v[154:157], v180
	ds_read_b128 v[158:161], v180 offset:2048
	ds_read_b128 v[162:165], v180 offset:4096
	ds_read_b128 v[166:169], v180 offset:6144
	ds_read_b128 v[190:193], v223 offset:32768
	ds_read_b128 v[194:197], v223 offset:34816
	ds_read_b128 v[198:201], v223 offset:36864
	ds_read_b128 v[202:205], v223 offset:38912
	s_mov_b32 s57, 0
	s_mov_b64 s[60:61], s[34:35]
	v_subrev_u32_e32 v178, s34, v142
	v_subrev_u32_e32 v179, s34, v140
	s_add_u32 s59, s59, 0x10000
	s_mov_b32 m0, s59
	s_add_u32 s62, s60, s22
	s_addc_u32 s63, s61, s23
	global_load_lds_dwordx4 v178, s[62:63]
	s_add_u32 m0, s59, 0x2000
	s_add_u32 s62, s60, s36
	s_addc_u32 s63, s61, s37
	global_load_lds_dwordx4 v178, s[62:63]
	s_add_u32 m0, s59, 0x4000
	s_add_u32 s62, s60, s38
	s_addc_u32 s63, s61, s39
	global_load_lds_dwordx4 v178, s[62:63]
	s_add_u32 m0, s59, 0x6000
	s_add_u32 s62, s60, s40
	s_addc_u32 s63, s61, s41
	global_load_lds_dwordx4 v178, s[62:63]
	s_add_u32 m0, s59, 0x8000
	s_add_u32 s62, s60, s42
	s_addc_u32 s63, s61, s43
	global_load_lds_dwordx4 v179, s[62:63]
	s_add_u32 m0, s59, 0xa000
	s_add_u32 s62, s60, s44
	s_addc_u32 s63, s61, s45
	global_load_lds_dwordx4 v179, s[62:63]
	s_add_u32 m0, s59, 0xc000
	s_add_u32 s62, s60, s46
	s_addc_u32 s63, s61, s47
	global_load_lds_dwordx4 v179, s[62:63]
	s_add_u32 m0, s59, 0xe000
	s_add_u32 s62, s60, s48
	s_addc_u32 s63, s61, s49
	global_load_lds_dwordx4 v179, s[62:63]
	s_branch .Lg8_entry
.Lg8_top:
	s_waitcnt lgkmcnt(0)
	s_waitcnt vmcnt(0)
	s_barrier
	s_xor_b32 s59, s59, 0x10000
	ds_read_b128 v[154:157], v180
	ds_read_b128 v[158:161], v180 offset:2048
	ds_read_b128 v[162:165], v180 offset:4096
	ds_read_b128 v[166:169], v180 offset:6144
	ds_read_b128 v[190:193], v223 offset:32768
	ds_read_b128 v[194:197], v223 offset:34816
	ds_read_b128 v[198:201], v223 offset:36864
	ds_read_b128 v[202:205], v223 offset:38912
	v_mfma_f32_16x16x32_bf16 v[60:63], v[170:173], v[206:209], v[60:63]
	v_mfma_f32_16x16x32_bf16 v[56:59], v[170:173], v[210:213], v[56:59]
	s_mov_b32 m0, s59
	s_add_u32 s62, s60, s22
	s_addc_u32 s63, s61, s23
	global_load_lds_dwordx4 v178, s[62:63]
	v_mfma_f32_16x16x32_bf16 v[52:55], v[170:173], v[214:217], v[52:55]
	v_mfma_f32_16x16x32_bf16 v[44:47], v[170:173], v[218:221], v[44:47]
	s_add_u32 m0, s59, 0x2000
	s_add_u32 s62, s60, s36
	s_addc_u32 s63, s61, s37
	global_load_lds_dwordx4 v178, s[62:63]
	v_mfma_f32_16x16x32_bf16 v[36:39], v[174:177], v[206:209], v[36:39]
	v_mfma_f32_16x16x32_bf16 v[32:35], v[174:177], v[210:213], v[32:35]
	s_add_u32 m0, s59, 0x4000
	s_add_u32 s62, s60, s38
	s_addc_u32 s63, s61, s39
	global_load_lds_dwordx4 v178, s[62:63]
	v_mfma_f32_16x16x32_bf16 v[28:31], v[174:177], v[214:217], v[28:31]
	v_mfma_f32_16x16x32_bf16 v[24:27], v[174:177], v[218:221], v[24:27]
	s_add_u32 m0, s59, 0x6000
	s_add_u32 s62, s60, s40
	s_addc_u32 s63, s61, s41
	global_load_lds_dwordx4 v178, s[62:63]
	v_mfma_f32_16x16x32_bf16 v[20:23], v[182:185], v[206:209], v[20:23]
	v_mfma_f32_16x16x32_bf16 v[16:19], v[182:185], v[210:213], v[16:19]
	s_add_u32 m0, s59, 0x8000
	s_add_u32 s62, s60, s42
	s_addc_u32 s63, s61, s43
	global_load_lds_dwordx4 v179, s[62:63]
	v_mfma_f32_16x16x32_bf16 v[12:15], v[182:185], v[214:217], v[12:15]
	v_mfma_f32_16x16x32_bf16 v[8:11], v[182:185], v[218:221], v[8:11]
	s_add_u32 m0, s59, 0xa000
	s_add_u32 s62, s60, s44
	s_addc_u32 s63, s61, s45
	global_load_lds_dwordx4 v179, s[62:63]
	v_mfma_f32_16x16x32_bf16 v[4:7], v[186:189], v[206:209], v[4:7]
	v_mfma_f32_16x16x32_bf16 v[0:3], v[186:189], v[210:213], v[0:3]
	s_add_u32 m0, s59, 0xc000
	s_add_u32 s62, s60, s46
	s_addc_u32 s63, s61, s47
	global_load_lds_dwordx4 v179, s[62:63]
	v_mfma_f32_16x16x32_bf16 v[48:51], v[186:189], v[214:217], v[48:51]
	v_mfma_f32_16x16x32_bf16 v[40:43], v[186:189], v[218:221], v[40:43]
	s_add_u32 m0, s59, 0xe000
	s_add_u32 s62, s60, s48
	s_addc_u32 s63, s61, s49
	global_load_lds_dwordx4 v179, s[62:63]
.Lg8_entry:
	ds_read_b128 v[170:173], v180 offset:8192
	ds_read_b128 v[174:177], v180 offset:10240
	ds_read_b128 v[182:185], v180 offset:12288
	ds_read_b128 v[186:189], v180 offset:14336
	s_waitcnt lgkmcnt(4)
	v_mfma_f32_16x16x32_bf16 v[124:127], v[154:157], v[190:193], v[124:127]
	v_mfma_f32_16x16x32_bf16 v[120:123], v[154:157], v[194:197], v[120:123]
	v_mfma_f32_16x16x32_bf16 v[116:119], v[154:157], v[198:201], v[116:119]
	v_mfma_f32_16x16x32_bf16 v[112:115], v[154:157], v[202:205], v[112:115]
	v_mfma_f32_16x16x32_bf16 v[108:111], v[158:161], v[190:193], v[108:111]
	v_mfma_f32_16x16x32_bf16 v[104:107], v[158:161], v[194:197], v[104:107]
	v_mfma_f32_16x16x32_bf16 v[100:103], v[158:161], v[198:201], v[100:103]
	v_mfma_f32_16x16x32_bf16 v[96:99], v[158:161], v[202:205], v[96:99]
	v_mfma_f32_16x16x32_bf16 v[92:95], v[162:165], v[190:193], v[92:95]
	v_mfma_f32_16x16x32_bf16 v[88:91], v[162:165], v[194:197], v[88:91]
	v_mfma_f32_16x16x32_bf16 v[84:87], v[162:165], v[198:201], v[84:87]
	v_mfma_f32_16x16x32_bf16 v[80:83], v[162:165], v[202:205], v[80:83]
	v_mfma_f32_16x16x32_bf16 v[76:79], v[166:169], v[190:193], v[76:79]
	v_mfma_f32_16x16x32_bf16 v[72:75], v[166:169], v[194:197], v[72:75]
	v_mfma_f32_16x16x32_bf16 v[68:71], v[166:169], v[198:201], v[68:71]
	v_mfma_f32_16x16x32_bf16 v[64:67], v[166:169], v[202:205], v[64:67]
	ds_read_b128 v[154:157], v222
	ds_read_b128 v[158:161], v222 offset:2048
	ds_read_b128 v[162:165], v222 offset:4096
	ds_read_b128 v[166:169], v222 offset:6144
	ds_read_b128 v[206:209], v224 offset:32768
	ds_read_b128 v[210:213], v224 offset:34816
	ds_read_b128 v[214:217], v224 offset:36864
	ds_read_b128 v[218:221], v224 offset:38912
	s_waitcnt lgkmcnt(8)
	v_mfma_f32_16x16x32_bf16 v[60:63], v[170:173], v[190:193], v[60:63]
	v_mfma_f32_16x16x32_bf16 v[56:59], v[170:173], v[194:197], v[56:59]
	v_mfma_f32_16x16x32_bf16 v[52:55], v[170:173], v[198:201], v[52:55]
	v_mfma_f32_16x16x32_bf16 v[44:47], v[170:173], v[202:205], v[44:47]
	v_mfma_f32_16x16x32_bf16 v[36:39], v[174:177], v[190:193], v[36:39]
	v_mfma_f32_16x16x32_bf16 v[32:35], v[174:177], v[194:197], v[32:35]
	v_mfma_f32_16x16x32_bf16 v[28:31], v[174:177], v[198:201], v[28:31]
	v_mfma_f32_16x16x32_bf16 v[24:27], v[174:177], v[202:205], v[24:27]
	v_mfma_f32_16x16x32_bf16 v[20:23], v[182:185], v[190:193], v[20:23]
	v_mfma_f32_16x16x32_bf16 v[16:19], v[182:185], v[194:197], v[16:19]
	v_mfma_f32_16x16x32_bf16 v[12:15], v[182:185], v[198:201], v[12:15]
	v_mfma_f32_16x16x32_bf16 v[8:11], v[182:185], v[202:205], v[8:11]
	v_mfma_f32_16x16x32_bf16 v[4:7], v[186:189], v[190:193], v[4:7]
	v_mfma_f32_16x16x32_bf16 v[0:3], v[186:189], v[194:197], v[0:3]
	v_mfma_f32_16x16x32_bf16 v[48:51], v[186:189], v[198:201], v[48:51]
	v_mfma_f32_16x16x32_bf16 v[40:43], v[186:189], v[202:205], v[40:43]
	ds_read_b128 v[170:173], v222 offset:8192
	ds_read_b128 v[174:177], v222 offset:10240
	ds_read_b128 v[182:185], v222 offset:12288
	ds_read_b128 v[186:189], v222 offset:14336
	s_waitcnt lgkmcnt(4)
	v_mfma_f32_16x16x32_bf16 v[124:127], v[154:157], v[206:209], v[124:127]
	v_mfma_f32_16x16x32_bf16 v[120:123], v[154:157], v[210:213], v[120:123]
	v_mfma_f32_16x16x32_bf16 v[116:119], v[154:157], v[214:217], v[116:119]
	v_mfma_f32_16x16x32_bf16 v[112:115], v[154:157], v[218:221], v[112:115]
	v_mfma_f32_16x16x32_bf16 v[108:111], v[158:161], v[206:209], v[108:111]
	v_mfma_f32_16x16x32_bf16 v[104:107], v[158:161], v[210:213], v[104:107]
	v_mfma_f32_16x16x32_bf16 v[100:103], v[158:161], v[214:217], v[100:103]
	v_mfma_f32_16x16x32_bf16 v[96:99], v[158:161], v[218:221], v[96:99]
	v_mfma_f32_16x16x32_bf16 v[92:95], v[162:165], v[206:209], v[92:95]
	v_mfma_f32_16x16x32_bf16 v[88:91], v[162:165], v[210:213], v[88:91]
	v_mfma_f32_16x16x32_bf16 v[84:87], v[162:165], v[214:217], v[84:87]
	v_mfma_f32_16x16x32_bf16 v[80:83], v[162:165], v[218:221], v[80:83]
	v_mfma_f32_16x16x32_bf16 v[76:79], v[166:169], v[206:209], v[76:79]
	v_mfma_f32_16x16x32_bf16 v[72:75], v[166:169], v[210:213], v[72:75]
	v_mfma_f32_16x16x32_bf16 v[68:71], v[166:169], v[214:217], v[68:71]
	v_mfma_f32_16x16x32_bf16 v[64:67], v[166:169], v[218:221], v[64:67]
	s_add_u32 s60, s60, 0x80
	s_addc_u32 s61, s61, 0
	s_add_i32 s57, s57, 1
	s_cmp_lt_u32 s57, 15
	s_cbranch_scc0 .Lg8_last
	s_waitcnt lgkmcnt(0)
	s_waitcnt vmcnt(0)
	s_barrier
	s_xor_b32 s59, s59, 0x10000
	ds_read_b128 v[154:157], v225
	ds_read_b128 v[158:161], v225 offset:2048
	ds_read_b128 v[162:165], v225 offset:4096
	ds_read_b128 v[166:169], v225 offset:6144
	ds_read_b128 v[190:193], v227 offset:32768
	ds_read_b128 v[194:197], v227 offset:34816
	ds_read_b128 v[198:201], v227 offset:36864
	ds_read_b128 v[202:205], v227 offset:38912
	v_mfma_f32_16x16x32_bf16 v[60:63], v[170:173], v[206:209], v[60:63]
	v_mfma_f32_16x16x32_bf16 v[56:59], v[170:173], v[210:213], v[56:59]
	s_mov_b32 m0, s59
	s_add_u32 s62, s60, s22
	s_addc_u32 s63, s61, s23
	global_load_lds_dwordx4 v178, s[62:63]
	v_mfma_f32_16x16x32_bf16 v[52:55], v[170:173], v[214:217], v[52:55]
	v_mfma_f32_16x16x32_bf16 v[44:47], v[170:173], v[218:221], v[44:47]
	s_add_u32 m0, s59, 0x2000
	s_add_u32 s62, s60, s36
	s_addc_u32 s63, s61, s37
	global_load_lds_dwordx4 v178, s[62:63]
	v_mfma_f32_16x16x32_bf16 v[36:39], v[174:177], v[206:209], v[36:39]
	v_mfma_f32_16x16x32_bf16 v[32:35], v[174:177], v[210:213], v[32:35]
	s_add_u32 m0, s59, 0x4000
	s_add_u32 s62, s60, s38
	s_addc_u32 s63, s61, s39
	global_load_lds_dwordx4 v178, s[62:63]
	v_mfma_f32_16x16x32_bf16 v[28:31], v[174:177], v[214:217], v[28:31]
	v_mfma_f32_16x16x32_bf16 v[24:27], v[174:177], v[218:221], v[24:27]
	s_add_u32 m0, s59, 0x6000
	s_add_u32 s62, s60, s40
	s_addc_u32 s63, s61, s41
	global_load_lds_dwordx4 v178, s[62:63]
	v_mfma_f32_16x16x32_bf16 v[20:23], v[182:185], v[206:209], v[20:23]
	v_mfma_f32_16x16x32_bf16 v[16:19], v[182:185], v[210:213], v[16:19]
	s_add_u32 m0, s59, 0x8000
	s_add_u32 s62, s60, s42
	s_addc_u32 s63, s61, s43
	global_load_lds_dwordx4 v179, s[62:63]
	v_mfma_f32_16x16x32_bf16 v[12:15], v[182:185], v[214:217], v[12:15]
	v_mfma_f32_16x16x32_bf16 v[8:11], v[182:185], v[218:221], v[8:11]
	s_add_u32 m0, s59, 0xa000
	s_add_u32 s62, s60, s44
	s_addc_u32 s63, s61, s45
	global_load_lds_dwordx4 v179, s[62:63]
	v_mfma_f32_16x16x32_bf16 v[4:7], v[186:189], v[206:209], v[4:7]
	v_mfma_f32_16x16x32_bf16 v[0:3], v[186:189], v[210:213], v[0:3]
	s_add_u32 m0, s59, 0xc000
	s_add_u32 s62, s60, s46
	s_addc_u32 s63, s61, s47
	global_load_lds_dwordx4 v179, s[62:63]
	v_mfma_f32_16x16x32_bf16 v[48:51], v[186:189], v[214:217], v[48:51]
	v_mfma_f32_16x16x32_bf16 v[40:43], v[186:189], v[218:221], v[40:43]
	s_add_u32 m0, s59, 0xe000
	s_add_u32 s62, s60, s48
	s_addc_u32 s63, s61, s49
	global_load_lds_dwordx4 v179, s[62:63]
	ds_read_b128 v[170:173], v225 offset:8192
	ds_read_b128 v[174:177], v225 offset:10240
	ds_read_b128 v[182:185], v225 offset:12288
	ds_read_b128 v[186:189], v225 offset:14336
	s_waitcnt lgkmcnt(4)
	v_mfma_f32_16x16x32_bf16 v[124:127], v[154:157], v[190:193], v[124:127]
	v_mfma_f32_16x16x32_bf16 v[120:123], v[154:157], v[194:197], v[120:123]
	v_mfma_f32_16x16x32_bf16 v[116:119], v[154:157], v[198:201], v[116:119]
	v_mfma_f32_16x16x32_bf16 v[112:115], v[154:157], v[202:205], v[112:115]
	v_mfma_f32_16x16x32_bf16 v[108:111], v[158:161], v[190:193], v[108:111]
	v_mfma_f32_16x16x32_bf16 v[104:107], v[158:161], v[194:197], v[104:107]
	v_mfma_f32_16x16x32_bf16 v[100:103], v[158:161], v[198:201], v[100:103]
	v_mfma_f32_16x16x32_bf16 v[96:99], v[158:161], v[202:205], v[96:99]
	v_mfma_f32_16x16x32_bf16 v[92:95], v[162:165], v[190:193], v[92:95]
	v_mfma_f32_16x16x32_bf16 v[88:91], v[162:165], v[194:197], v[88:91]
	v_mfma_f32_16x16x32_bf16 v[84:87], v[162:165], v[198:201], v[84:87]
	v_mfma_f32_16x16x32_bf16 v[80:83], v[162:165], v[202:205], v[80:83]
	v_mfma_f32_16x16x32_bf16 v[76:79], v[166:169], v[190:193], v[76:79]
	v_mfma_f32_16x16x32_bf16 v[72:75], v[166:169], v[194:197], v[72:75]
	v_mfma_f32_16x16x32_bf16 v[68:71], v[166:169], v[198:201], v[68:71]
	v_mfma_f32_16x16x32_bf16 v[64:67], v[166:169], v[202:205], v[64:67]
	ds_read_b128 v[154:157], v226
	ds_read_b128 v[158:161], v226 offset:2048
	ds_read_b128 v[162:165], v226 offset:4096
	ds_read_b128 v[166:169], v226 offset:6144
	ds_read_b128 v[206:209], v228 offset:32768
	ds_read_b128 v[210:213], v228 offset:34816
	ds_read_b128 v[214:217], v228 offset:36864
	ds_read_b128 v[218:221], v228 offset:38912
	s_waitcnt lgkmcnt(8)
	v_mfma_f32_16x16x32_bf16 v[60:63], v[170:173], v[190:193], v[60:63]
	v_mfma_f32_16x16x32_bf16 v[56:59], v[170:173], v[194:197], v[56:59]
	v_mfma_f32_16x16x32_bf16 v[52:55], v[170:173], v[198:201], v[52:55]
	v_mfma_f32_16x16x32_bf16 v[44:47], v[170:173], v[202:205], v[44:47]
	v_mfma_f32_16x16x32_bf16 v[36:39], v[174:177], v[190:193], v[36:39]
	v_mfma_f32_16x16x32_bf16 v[32:35], v[174:177], v[194:197], v[32:35]
	v_mfma_f32_16x16x32_bf16 v[28:31], v[174:177], v[198:201], v[28:31]
	v_mfma_f32_16x16x32_bf16 v[24:27], v[174:177], v[202:205], v[24:27]
	v_mfma_f32_16x16x32_bf16 v[20:23], v[182:185], v[190:193], v[20:23]
	v_mfma_f32_16x16x32_bf16 v[16:19], v[182:185], v[194:197], v[16:19]
	v_mfma_f32_16x16x32_bf16 v[12:15], v[182:185], v[198:201], v[12:15]
	v_mfma_f32_16x16x32_bf16 v[8:11], v[182:185], v[202:205], v[8:11]
	v_mfma_f32_16x16x32_bf16 v[4:7], v[186:189], v[190:193], v[4:7]
	v_mfma_f32_16x16x32_bf16 v[0:3], v[186:189], v[194:197], v[0:3]
	v_mfma_f32_16x16x32_bf16 v[48:51], v[186:189], v[198:201], v[48:51]
	v_mfma_f32_16x16x32_bf16 v[40:43], v[186:189], v[202:205], v[40:43]
	ds_read_b128 v[170:173], v226 offset:8192
	ds_read_b128 v[174:177], v226 offset:10240
	ds_read_b128 v[182:185], v226 offset:12288
	ds_read_b128 v[186:189], v226 offset:14336
	s_waitcnt lgkmcnt(4)
	v_mfma_f32_16x16x32_bf16 v[124:127], v[154:157], v[206:209], v[124:127]
	v_mfma_f32_16x16x32_bf16 v[120:123], v[154:157], v[210:213], v[120:123]
	v_mfma_f32_16x16x32_bf16 v[116:119], v[154:157], v[214:217], v[116:119]
	v_mfma_f32_16x16x32_bf16 v[112:115], v[154:157], v[218:221], v[112:115]
	v_mfma_f32_16x16x32_bf16 v[108:111], v[158:161], v[206:209], v[108:111]
	v_mfma_f32_16x16x32_bf16 v[104:107], v[158:161], v[210:213], v[104:107]
	v_mfma_f32_16x16x32_bf16 v[100:103], v[158:161], v[214:217], v[100:103]
	v_mfma_f32_16x16x32_bf16 v[96:99], v[158:161], v[218:221], v[96:99]
	v_mfma_f32_16x16x32_bf16 v[92:95], v[162:165], v[206:209], v[92:95]
	v_mfma_f32_16x16x32_bf16 v[88:91], v[162:165], v[210:213], v[88:91]
	v_mfma_f32_16x16x32_bf16 v[84:87], v[162:165], v[214:217], v[84:87]
	v_mfma_f32_16x16x32_bf16 v[80:83], v[162:165], v[218:221], v[80:83]
	v_mfma_f32_16x16x32_bf16 v[76:79], v[166:169], v[206:209], v[76:79]
	v_mfma_f32_16x16x32_bf16 v[72:75], v[166:169], v[210:213], v[72:75]
	v_mfma_f32_16x16x32_bf16 v[68:71], v[166:169], v[214:217], v[68:71]
	v_mfma_f32_16x16x32_bf16 v[64:67], v[166:169], v[218:221], v[64:67]
	s_add_u32 s60, s60, 0x80
	s_addc_u32 s61, s61, 0
	s_add_i32 s57, s57, 1
	s_branch .Lg8_top
.Lg8_last:
	s_waitcnt lgkmcnt(0)
	s_waitcnt vmcnt(0)
	s_barrier
	s_xor_b32 s59, s59, 0x10000
	ds_read_b128 v[154:157], v225
	ds_read_b128 v[158:161], v225 offset:2048
	ds_read_b128 v[162:165], v225 offset:4096
	ds_read_b128 v[166:169], v225 offset:6144
	ds_read_b128 v[190:193], v227 offset:32768
	ds_read_b128 v[194:197], v227 offset:34816
	ds_read_b128 v[198:201], v227 offset:36864
	ds_read_b128 v[202:205], v227 offset:38912
	v_mfma_f32_16x16x32_bf16 v[60:63], v[170:173], v[206:209], v[60:63]
	v_mfma_f32_16x16x32_bf16 v[56:59], v[170:173], v[210:213], v[56:59]
	v_mfma_f32_16x16x32_bf16 v[52:55], v[170:173], v[214:217], v[52:55]
	v_mfma_f32_16x16x32_bf16 v[44:47], v[170:173], v[218:221], v[44:47]
	v_mfma_f32_16x16x32_bf16 v[36:39], v[174:177], v[206:209], v[36:39]
	v_mfma_f32_16x16x32_bf16 v[32:35], v[174:177], v[210:213], v[32:35]
	v_mfma_f32_16x16x32_bf16 v[28:31], v[174:177], v[214:217], v[28:31]
	v_mfma_f32_16x16x32_bf16 v[24:27], v[174:177], v[218:221], v[24:27]
	v_mfma_f32_16x16x32_bf16 v[20:23], v[182:185], v[206:209], v[20:23]
	v_mfma_f32_16x16x32_bf16 v[16:19], v[182:185], v[210:213], v[16:19]
	v_mfma_f32_16x16x32_bf16 v[12:15], v[182:185], v[214:217], v[12:15]
	v_mfma_f32_16x16x32_bf16 v[8:11], v[182:185], v[218:221], v[8:11]
	v_mfma_f32_16x16x32_bf16 v[4:7], v[186:189], v[206:209], v[4:7]
	v_mfma_f32_16x16x32_bf16 v[0:3], v[186:189], v[210:213], v[0:3]
	v_mfma_f32_16x16x32_bf16 v[48:51], v[186:189], v[214:217], v[48:51]
	v_mfma_f32_16x16x32_bf16 v[40:43], v[186:189], v[218:221], v[40:43]
	ds_read_b128 v[170:173], v225 offset:8192
	ds_read_b128 v[174:177], v225 offset:10240
	ds_read_b128 v[182:185], v225 offset:12288
	ds_read_b128 v[186:189], v225 offset:14336
	s_waitcnt lgkmcnt(4)
	v_mfma_f32_16x16x32_bf16 v[124:127], v[154:157], v[190:193], v[124:127]
	v_mfma_f32_16x16x32_bf16 v[120:123], v[154:157], v[194:197], v[120:123]
	v_mfma_f32_16x16x32_bf16 v[116:119], v[154:157], v[198:201], v[116:119]
	v_mfma_f32_16x16x32_bf16 v[112:115], v[154:157], v[202:205], v[112:115]
	v_mfma_f32_16x16x32_bf16 v[108:111], v[158:161], v[190:193], v[108:111]
	v_mfma_f32_16x16x32_bf16 v[104:107], v[158:161], v[194:197], v[104:107]
	v_mfma_f32_16x16x32_bf16 v[100:103], v[158:161], v[198:201], v[100:103]
	v_mfma_f32_16x16x32_bf16 v[96:99], v[158:161], v[202:205], v[96:99]
	v_mfma_f32_16x16x32_bf16 v[92:95], v[162:165], v[190:193], v[92:95]
	v_mfma_f32_16x16x32_bf16 v[88:91], v[162:165], v[194:197], v[88:91]
	v_mfma_f32_16x16x32_bf16 v[84:87], v[162:165], v[198:201], v[84:87]
	v_mfma_f32_16x16x32_bf16 v[80:83], v[162:165], v[202:205], v[80:83]
	v_mfma_f32_16x16x32_bf16 v[76:79], v[166:169], v[190:193], v[76:79]
	v_mfma_f32_16x16x32_bf16 v[72:75], v[166:169], v[194:197], v[72:75]
	v_mfma_f32_16x16x32_bf16 v[68:71], v[166:169], v[198:201], v[68:71]
	v_mfma_f32_16x16x32_bf16 v[64:67], v[166:169], v[202:205], v[64:67]
	ds_read_b128 v[154:157], v226
	ds_read_b128 v[158:161], v226 offset:2048
	ds_read_b128 v[162:165], v226 offset:4096
	ds_read_b128 v[166:169], v226 offset:6144
	ds_read_b128 v[206:209], v228 offset:32768
	ds_read_b128 v[210:213], v228 offset:34816
	ds_read_b128 v[214:217], v228 offset:36864
	ds_read_b128 v[218:221], v228 offset:38912
	s_waitcnt lgkmcnt(8)
	v_mfma_f32_16x16x32_bf16 v[60:63], v[170:173], v[190:193], v[60:63]
	v_mfma_f32_16x16x32_bf16 v[56:59], v[170:173], v[194:197], v[56:59]
	v_mfma_f32_16x16x32_bf16 v[52:55], v[170:173], v[198:201], v[52:55]
	v_mfma_f32_16x16x32_bf16 v[44:47], v[170:173], v[202:205], v[44:47]
	v_mfma_f32_16x16x32_bf16 v[36:39], v[174:177], v[190:193], v[36:39]
	v_mfma_f32_16x16x32_bf16 v[32:35], v[174:177], v[194:197], v[32:35]
	v_mfma_f32_16x16x32_bf16 v[28:31], v[174:177], v[198:201], v[28:31]
	v_mfma_f32_16x16x32_bf16 v[24:27], v[174:177], v[202:205], v[24:27]
	v_mfma_f32_16x16x32_bf16 v[20:23], v[182:185], v[190:193], v[20:23]
	v_mfma_f32_16x16x32_bf16 v[16:19], v[182:185], v[194:197], v[16:19]
	v_mfma_f32_16x16x32_bf16 v[12:15], v[182:185], v[198:201], v[12:15]
	v_mfma_f32_16x16x32_bf16 v[8:11], v[182:185], v[202:205], v[8:11]
	v_mfma_f32_16x16x32_bf16 v[4:7], v[186:189], v[190:193], v[4:7]
	v_mfma_f32_16x16x32_bf16 v[0:3], v[186:189], v[194:197], v[0:3]
	v_mfma_f32_16x16x32_bf16 v[48:51], v[186:189], v[198:201], v[48:51]
	v_mfma_f32_16x16x32_bf16 v[40:43], v[186:189], v[202:205], v[40:43]
	ds_read_b128 v[170:173], v226 offset:8192
	ds_read_b128 v[174:177], v226 offset:10240
	ds_read_b128 v[182:185], v226 offset:12288
	ds_read_b128 v[186:189], v226 offset:14336
	s_waitcnt lgkmcnt(4)
	v_mfma_f32_16x16x32_bf16 v[124:127], v[154:157], v[206:209], v[124:127]
	v_mfma_f32_16x16x32_bf16 v[120:123], v[154:157], v[210:213], v[120:123]
	v_mfma_f32_16x16x32_bf16 v[116:119], v[154:157], v[214:217], v[116:119]
	v_mfma_f32_16x16x32_bf16 v[112:115], v[154:157], v[218:221], v[112:115]
	v_mfma_f32_16x16x32_bf16 v[108:111], v[158:161], v[206:209], v[108:111]
	v_mfma_f32_16x16x32_bf16 v[104:107], v[158:161], v[210:213], v[104:107]
	v_mfma_f32_16x16x32_bf16 v[100:103], v[158:161], v[214:217], v[100:103]
	v_mfma_f32_16x16x32_bf16 v[96:99], v[158:161], v[218:221], v[96:99]
	v_mfma_f32_16x16x32_bf16 v[92:95], v[162:165], v[206:209], v[92:95]
	v_mfma_f32_16x16x32_bf16 v[88:91], v[162:165], v[210:213], v[88:91]
	v_mfma_f32_16x16x32_bf16 v[84:87], v[162:165], v[214:217], v[84:87]
	v_mfma_f32_16x16x32_bf16 v[80:83], v[162:165], v[218:221], v[80:83]
	v_mfma_f32_16x16x32_bf16 v[76:79], v[166:169], v[206:209], v[76:79]
	v_mfma_f32_16x16x32_bf16 v[72:75], v[166:169], v[210:213], v[72:75]
	v_mfma_f32_16x16x32_bf16 v[68:71], v[166:169], v[214:217], v[68:71]
	v_mfma_f32_16x16x32_bf16 v[64:67], v[166:169], v[218:221], v[64:67]
	s_add_u32 s60, s60, 0x80
	s_addc_u32 s61, s61, 0
	s_add_i32 s57, s57, 1
	s_waitcnt lgkmcnt(0)
	s_waitcnt vmcnt(0)
	s_barrier
	v_mfma_f32_16x16x32_bf16 v[60:63], v[170:173], v[206:209], v[60:63]
	v_mfma_f32_16x16x32_bf16 v[56:59], v[170:173], v[210:213], v[56:59]
	v_mfma_f32_16x16x32_bf16 v[52:55], v[170:173], v[214:217], v[52:55]
	v_mfma_f32_16x16x32_bf16 v[44:47], v[170:173], v[218:221], v[44:47]
	v_mfma_f32_16x16x32_bf16 v[36:39], v[174:177], v[206:209], v[36:39]
	v_mfma_f32_16x16x32_bf16 v[32:35], v[174:177], v[210:213], v[32:35]
	v_mfma_f32_16x16x32_bf16 v[28:31], v[174:177], v[214:217], v[28:31]
	v_mfma_f32_16x16x32_bf16 v[24:27], v[174:177], v[218:221], v[24:27]
	v_mfma_f32_16x16x32_bf16 v[20:23], v[182:185], v[206:209], v[20:23]
	v_mfma_f32_16x16x32_bf16 v[16:19], v[182:185], v[210:213], v[16:19]
	v_mfma_f32_16x16x32_bf16 v[12:15], v[182:185], v[214:217], v[12:15]
	v_mfma_f32_16x16x32_bf16 v[8:11], v[182:185], v[218:221], v[8:11]
	v_mfma_f32_16x16x32_bf16 v[4:7], v[186:189], v[206:209], v[4:7]
	v_mfma_f32_16x16x32_bf16 v[0:3], v[186:189], v[210:213], v[0:3]
	v_mfma_f32_16x16x32_bf16 v[48:51], v[186:189], v[214:217], v[48:51]
	v_mfma_f32_16x16x32_bf16 v[40:43], v[186:189], v[218:221], v[40:43]
	s_nop 7
	s_nop 7
	s_sub_u32 s60, s60, s34
	s_subb_u32 s61, s61, s35
	s_mov_b32 s59, 0x80000
	s_mov_b32 s65, 0x80000
	s_mov_b64 s[62:63], 0
	s_mov_b64 vcc, exec
	s_branch .LBB0_939

.LBB0_1331:
	s_ashr_i32 s20, s58, 2
	v_mov_b32_e32 v6, v181
	s_and_b32 s4, s58, 7
	s_and_b32 s47, s20, -8
	s_or_b32 s42, s47, s4
	v_lshrrev_b32_e32 v7, 4, v6
	v_lshlrev_b32_e32 v1, 6, v6
	v_xor_b32_e32 v0, v7, v6
	v_and_b32_e32 v8, 0x3c0, v1
	v_lshlrev_b32_e32 v1, 8, v6
	s_ashr_i32 s43, s42, 31
	v_lshlrev_b32_e32 v0, 3, v0
	v_and_b32_e32 v1, 0xfffff800, v1
	s_and_b32 s46, s57, 7
	s_bfe_u32 s4, s58, 0x20003
	s_lshl_b64 s[20:21], s[42:43], 20
	v_and_or_b32 v0, v0, 56, v1
	s_add_u32 s20, s3, s20
	v_ashrrev_i32_e32 v1, 31, v0
	s_addc_u32 s21, s48, s21
	v_lshlrev_b64 v[0:1], 1, v[0:1]
	v_lshl_add_u32 v134, v6, 4, 0
	v_lshl_add_u64 v[2:3], s[20:21], 0, v[0:1]
	v_readfirstlane_b32 s20, v134
	v_add_u32_e32 v9, 0x2000, v134
	s_mov_b32 m0, s20
	v_readfirstlane_b32 s20, v9
	v_add_u32_e32 v9, 0x4000, v134
	s_waitcnt vmcnt(63) expcnt(7) lgkmcnt(15)
	s_barrier
	global_load_lds_dwordx4 v[2:3], off
	v_lshl_add_u64 v[4:5], v[2:3], 0, s[6:7]
	s_mov_b32 m0, s20
	v_readfirstlane_b32 s20, v9
	global_load_lds_dwordx4 v[4:5], off
	v_lshl_add_u64 v[4:5], v[2:3], 0, s[8:9]
	s_mov_b32 m0, s20
	s_lshl_b32 s43, s4, 20
	global_load_lds_dwordx4 v[4:5], off
	v_add_u32_e32 v4, 0x6000, v134
	s_add_u32 s44, s49, s43
	v_readfirstlane_b32 s20, v4
	v_add_u32_e32 v4, 0x8000, v134
	s_addc_u32 s45, s56, 0
	v_lshl_add_u64 v[2:3], v[2:3], 0, s[10:11]
	s_mov_b32 m0, s20
	v_readfirstlane_b32 s20, v4
	v_add_u32_e32 v9, 0xa000, v134
	global_load_lds_dwordx4 v[2:3], off
	v_lshl_add_u64 v[2:3], s[44:45], 0, v[0:1]
	s_mov_b32 m0, s20
	v_readfirstlane_b32 s20, v9
	v_add_u32_e32 v9, 0xc000, v134
	global_load_lds_dwordx4 v[2:3], off
	v_lshl_add_u64 v[4:5], v[2:3], 0, s[6:7]
	s_mov_b32 m0, s20
	v_readfirstlane_b32 s20, v9
	global_load_lds_dwordx4 v[4:5], off
	v_lshl_add_u64 v[4:5], v[2:3], 0, s[8:9]
	s_mov_b32 m0, s20
	v_lshl_add_u64 v[2:3], v[2:3], 0, s[10:11]
	global_load_lds_dwordx4 v[4:5], off
	v_add_u32_e32 v4, 0xe000, v134
	v_mov_b32_e32 v36, 0
	v_readfirstlane_b32 s20, v4
	s_mov_b32 m0, s20
	v_ashrrev_i32_e32 v4, 6, v6
	global_load_lds_dwordx4 v[2:3], off
	s_or_b32 s20, s47, s46
	v_lshrrev_b32_e32 v5, 30, v4
	s_ashr_i32 s21, s20, 31
	v_add_u32_e32 v5, v4, v5
	s_lshl_b64 s[20:21], s[20:21], 20
	v_bfe_u32 v2, v6, 4, 2
	v_bfe_u32 v3, v6, 1, 3
	v_and_b32_e32 v6, 0x7fffc, v5
	s_add_u32 s20, s34, s20
	v_sub_u32_e32 v4, v4, v6
	s_addc_u32 s21, s35, s21
	v_lshlrev_b32_e32 v136, 13, v4
	v_bitop3_b32 v4, v7, v3, 3 bitop3:0x6c
	v_bitop3_b32 v2, v2, v3, 4 bitop3:0x36
	v_lshl_add_u64 v[130:131], s[20:21], 0, v[0:1]
	s_add_u32 s20, s34, s43
	v_lshlrev_b32_e32 v5, 12, v5
	v_lshlrev_b32_e32 v4, 3, v4
	v_lshlrev_b32_e32 v2, 3, v2
	s_addc_u32 s21, s35, 0
	v_and_b32_e32 v135, 0xffffc000, v5
	v_lshl_add_u64 v[132:133], s[20:21], 0, v[0:1]
	s_mov_b64 s[44:45], 0
	v_lshlrev_b32_e32 v137, 1, v8
	v_lshlrev_b32_e32 v138, 1, v4
	v_lshlrev_b32_e32 v139, 1, v2
	s_mov_b32 s59, 0
	s_mov_b32 s43, 0
	v_mov_b32_e32 v37, v36
	v_mov_b32_e32 v38, v36
	v_mov_b32_e32 v39, v36
	v_mov_b32_e32 v40, v36
	v_mov_b32_e32 v41, v36
	v_mov_b32_e32 v42, v36
	v_mov_b32_e32 v43, v36
	v_mov_b32_e32 v0, v36
	v_mov_b32_e32 v1, v36
	v_mov_b32_e32 v2, v36
	v_mov_b32_e32 v3, v36
	v_mov_b32_e32 v4, v36
	v_mov_b32_e32 v5, v36
	v_mov_b32_e32 v6, v36
	v_mov_b32_e32 v7, v36
	v_mov_b32_e32 v8, v36
	v_mov_b32_e32 v9, v36
	v_mov_b32_e32 v10, v36
	v_mov_b32_e32 v11, v36
	v_mov_b32_e32 v12, v36
	v_mov_b32_e32 v13, v36
	v_mov_b32_e32 v14, v36
	v_mov_b32_e32 v15, v36
	v_mov_b32_e32 v16, v36
	v_mov_b32_e32 v17, v36
	v_mov_b32_e32 v18, v36
	v_mov_b32_e32 v19, v36
	v_mov_b32_e32 v20, v36
	v_mov_b32_e32 v21, v36
	v_mov_b32_e32 v22, v36
	v_mov_b32_e32 v23, v36
	v_mov_b32_e32 v24, v36
	v_mov_b32_e32 v25, v36
	v_mov_b32_e32 v26, v36
	v_mov_b32_e32 v27, v36
	v_mov_b32_e32 v28, v36
	v_mov_b32_e32 v29, v36
	v_mov_b32_e32 v30, v36
	v_mov_b32_e32 v31, v36
	v_mov_b32_e32 v32, v36
	v_mov_b32_e32 v33, v36
	v_mov_b32_e32 v34, v36
	v_mov_b32_e32 v35, v36
	v_mov_b32_e32 v44, v36
	v_mov_b32_e32 v45, v36
	v_mov_b32_e32 v46, v36
	v_mov_b32_e32 v47, v36
	v_mov_b32_e32 v48, v36
	v_mov_b32_e32 v49, v36
	v_mov_b32_e32 v50, v36
	v_mov_b32_e32 v51, v36
	v_mov_b32_e32 v52, v36
	v_mov_b32_e32 v53, v36
	v_mov_b32_e32 v54, v36
	v_mov_b32_e32 v55, v36
	v_mov_b32_e32 v56, v36
	v_mov_b32_e32 v57, v36
	v_mov_b32_e32 v58, v36
	v_mov_b32_e32 v59, v36
	v_mov_b32_e32 v60, v36
	v_mov_b32_e32 v61, v36
	v_mov_b32_e32 v62, v36
	v_mov_b32_e32 v63, v36
	v_mov_b32_e32 v64, v36
	v_mov_b32_e32 v65, v36
	v_mov_b32_e32 v66, v36
	v_mov_b32_e32 v67, v36
	v_mov_b32_e32 v68, v36
	v_mov_b32_e32 v69, v36
	v_mov_b32_e32 v70, v36
	v_mov_b32_e32 v71, v36
	v_mov_b32_e32 v72, v36
	v_mov_b32_e32 v73, v36
	v_mov_b32_e32 v74, v36
	v_mov_b32_e32 v75, v36
	v_mov_b32_e32 v76, v36
	v_mov_b32_e32 v77, v36
	v_mov_b32_e32 v78, v36
	v_mov_b32_e32 v79, v36
	v_mov_b32_e32 v80, v36
	v_mov_b32_e32 v81, v36
	v_mov_b32_e32 v82, v36
	v_mov_b32_e32 v83, v36
	v_mov_b32_e32 v84, v36
	v_mov_b32_e32 v85, v36
	v_mov_b32_e32 v86, v36
	v_mov_b32_e32 v87, v36
	v_mov_b32_e32 v88, v36
	v_mov_b32_e32 v89, v36
	v_mov_b32_e32 v90, v36
	v_mov_b32_e32 v91, v36
	v_mov_b32_e32 v92, v36
	v_mov_b32_e32 v93, v36
	v_mov_b32_e32 v94, v36
	v_mov_b32_e32 v95, v36
	v_mov_b32_e32 v96, v36
	v_mov_b32_e32 v97, v36
	v_mov_b32_e32 v98, v36
	v_mov_b32_e32 v99, v36
	v_mov_b32_e32 v100, v36
	v_mov_b32_e32 v101, v36
	v_mov_b32_e32 v102, v36
	v_mov_b32_e32 v103, v36
	v_mov_b32_e32 v104, v36
	v_mov_b32_e32 v105, v36
	v_mov_b32_e32 v106, v36
	v_mov_b32_e32 v107, v36
	v_mov_b32_e32 v108, v36
	v_mov_b32_e32 v109, v36
	v_mov_b32_e32 v110, v36
	v_mov_b32_e32 v111, v36
	v_mov_b32_e32 v112, v36
	v_mov_b32_e32 v113, v36
	v_mov_b32_e32 v114, v36
	v_mov_b32_e32 v115, v36
	v_mov_b32_e32 v116, v36
	v_mov_b32_e32 v117, v36
	v_mov_b32_e32 v118, v36
	v_mov_b32_e32 v119, v36
	v_mov_b32_e32 v120, v36
	v_mov_b32_e32 v121, v36
	v_mov_b32_e32 v122, v36
	v_mov_b32_e32 v123, v36
	v_mov_b32_e32 v124, v36
	v_mov_b32_e32 v125, v36
	v_mov_b32_e32 v126, v36
	v_mov_b32_e32 v127, v36
	s_waitcnt vmcnt(0) lgkmcnt(0)
	s_barrier
	v_add3_u32 v141, v135, v137, v138
	v_add3_u32 v210, v136, v137, v138
	v_add3_u32 v180, v135, v137, v139
	v_add3_u32 v211, v136, v137, v139
	v_xor_b32_e32 v212, 0x10000, v141
	v_xor_b32_e32 v213, 0x10000, v180
	v_xor_b32_e32 v214, 0x10000, v210
	v_xor_b32_e32 v215, 0x10000, v211
	v_readfirstlane_b32 s59, v134
	ds_read_b128 v[142:145], v141
	ds_read_b128 v[146:149], v141 offset:2048
	ds_read_b128 v[150:153], v141 offset:4096
	ds_read_b128 v[154:157], v141 offset:6144
	ds_read_b128 v[174:177], v210 offset:32768
	ds_read_b128 v[182:185], v210 offset:34816
	ds_read_b128 v[186:189], v210 offset:36864
	ds_read_b128 v[190:193], v210 offset:38912
	s_mov_b32 s43, 0
	s_mov_b64 s[44:45], s[34:35]
	v_subrev_u32_e32 v178, s34, v130
	v_subrev_u32_e32 v179, s34, v132
	s_add_u32 s59, s59, 0x10000
	s_mov_b32 m0, s59
	s_add_u32 s46, s44, s12
	s_addc_u32 s47, s45, s13
	global_load_lds_dwordx4 v178, s[46:47]
	s_add_u32 m0, s59, 0x2000
	s_add_u32 s46, s44, s14
	s_addc_u32 s47, s45, s15
	global_load_lds_dwordx4 v178, s[46:47]
	s_add_u32 m0, s59, 0x4000
	s_add_u32 s46, s44, s16
	s_addc_u32 s47, s45, s17
	global_load_lds_dwordx4 v178, s[46:47]
	s_add_u32 m0, s59, 0x6000
	s_add_u32 s46, s44, s18
	s_addc_u32 s47, s45, s19
	global_load_lds_dwordx4 v178, s[46:47]
	s_add_u32 m0, s59, 0x8000
	s_add_u32 s46, s44, s22
	s_addc_u32 s47, s45, s23
	global_load_lds_dwordx4 v179, s[46:47]
	s_add_u32 m0, s59, 0xa000
	s_add_u32 s46, s44, s36
	s_addc_u32 s47, s45, s37
	global_load_lds_dwordx4 v179, s[46:47]
	s_add_u32 m0, s59, 0xc000
	s_add_u32 s46, s44, s38
	s_addc_u32 s47, s45, s39
	global_load_lds_dwordx4 v179, s[46:47]
	s_add_u32 m0, s59, 0xe000
	s_add_u32 s46, s44, s40
	s_addc_u32 s47, s45, s41
	global_load_lds_dwordx4 v179, s[46:47]
	s_branch .Lg9_entry
.Lg9_top:
	s_waitcnt lgkmcnt(0)
	s_waitcnt vmcnt(0)
	s_barrier
	s_xor_b32 s59, s59, 0x10000
	ds_read_b128 v[142:145], v141
	ds_read_b128 v[146:149], v141 offset:2048
	ds_read_b128 v[150:153], v141 offset:4096
	ds_read_b128 v[154:157], v141 offset:6144
	ds_read_b128 v[174:177], v210 offset:32768
	ds_read_b128 v[182:185], v210 offset:34816
	ds_read_b128 v[186:189], v210 offset:36864
	ds_read_b128 v[190:193], v210 offset:38912
	v_mfma_f32_16x16x32_bf16 v[60:63], v[158:161], v[194:197], v[60:63]
	v_mfma_f32_16x16x32_bf16 v[56:59], v[158:161], v[198:201], v[56:59]
	s_mov_b32 m0, s59
	s_add_u32 s46, s44, s12
	s_addc_u32 s47, s45, s13
	global_load_lds_dwordx4 v178, s[46:47]
	v_mfma_f32_16x16x32_bf16 v[52:55], v[158:161], v[202:205], v[52:55]
	v_mfma_f32_16x16x32_bf16 v[48:51], v[158:161], v[206:209], v[48:51]
	s_add_u32 m0, s59, 0x2000
	s_add_u32 s46, s44, s14
	s_addc_u32 s47, s45, s15
	global_load_lds_dwordx4 v178, s[46:47]
	v_mfma_f32_16x16x32_bf16 v[44:47], v[162:165], v[194:197], v[44:47]
	v_mfma_f32_16x16x32_bf16 v[32:35], v[162:165], v[198:201], v[32:35]
	s_add_u32 m0, s59, 0x4000
	s_add_u32 s46, s44, s16
	s_addc_u32 s47, s45, s17
	global_load_lds_dwordx4 v178, s[46:47]
	v_mfma_f32_16x16x32_bf16 v[28:31], v[162:165], v[202:205], v[28:31]
	v_mfma_f32_16x16x32_bf16 v[24:27], v[162:165], v[206:209], v[24:27]
	s_add_u32 m0, s59, 0x6000
	s_add_u32 s46, s44, s18
	s_addc_u32 s47, s45, s19
	global_load_lds_dwordx4 v178, s[46:47]
	v_mfma_f32_16x16x32_bf16 v[20:23], v[166:169], v[194:197], v[20:23]
	v_mfma_f32_16x16x32_bf16 v[16:19], v[166:169], v[198:201], v[16:19]
	s_add_u32 m0, s59, 0x8000
	s_add_u32 s46, s44, s22
	s_addc_u32 s47, s45, s23
	global_load_lds_dwordx4 v179, s[46:47]
	v_mfma_f32_16x16x32_bf16 v[12:15], v[166:169], v[202:205], v[12:15]
	v_mfma_f32_16x16x32_bf16 v[8:11], v[166:169], v[206:209], v[8:11]
	s_add_u32 m0, s59, 0xa000
	s_add_u32 s46, s44, s36
	s_addc_u32 s47, s45, s37
	global_load_lds_dwordx4 v179, s[46:47]
	v_mfma_f32_16x16x32_bf16 v[4:7], v[170:173], v[194:197], v[4:7]
	v_mfma_f32_16x16x32_bf16 v[0:3], v[170:173], v[198:201], v[0:3]
	s_add_u32 m0, s59, 0xc000
	s_add_u32 s46, s44, s38
	s_addc_u32 s47, s45, s39
	global_load_lds_dwordx4 v179, s[46:47]
	v_mfma_f32_16x16x32_bf16 v[40:43], v[170:173], v[202:205], v[40:43]
	v_mfma_f32_16x16x32_bf16 v[36:39], v[170:173], v[206:209], v[36:39]
	s_add_u32 m0, s59, 0xe000
	s_add_u32 s46, s44, s40
	s_addc_u32 s47, s45, s41
	global_load_lds_dwordx4 v179, s[46:47]
.Lg9_entry:
	ds_read_b128 v[158:161], v141 offset:8192
	ds_read_b128 v[162:165], v141 offset:10240
	ds_read_b128 v[166:169], v141 offset:12288
	ds_read_b128 v[170:173], v141 offset:14336
	s_waitcnt lgkmcnt(4)
	v_mfma_f32_16x16x32_bf16 v[124:127], v[142:145], v[174:177], v[124:127]
	v_mfma_f32_16x16x32_bf16 v[120:123], v[142:145], v[182:185], v[120:123]
	v_mfma_f32_16x16x32_bf16 v[116:119], v[142:145], v[186:189], v[116:119]
	v_mfma_f32_16x16x32_bf16 v[112:115], v[142:145], v[190:193], v[112:115]
	v_mfma_f32_16x16x32_bf16 v[108:111], v[146:149], v[174:177], v[108:111]
	v_mfma_f32_16x16x32_bf16 v[104:107], v[146:149], v[182:185], v[104:107]
	v_mfma_f32_16x16x32_bf16 v[100:103], v[146:149], v[186:189], v[100:103]
	v_mfma_f32_16x16x32_bf16 v[96:99], v[146:149], v[190:193], v[96:99]
	v_mfma_f32_16x16x32_bf16 v[92:95], v[150:153], v[174:177], v[92:95]
	v_mfma_f32_16x16x32_bf16 v[88:91], v[150:153], v[182:185], v[88:91]
	v_mfma_f32_16x16x32_bf16 v[84:87], v[150:153], v[186:189], v[84:87]
	v_mfma_f32_16x16x32_bf16 v[80:83], v[150:153], v[190:193], v[80:83]
	v_mfma_f32_16x16x32_bf16 v[76:79], v[154:157], v[174:177], v[76:79]
	v_mfma_f32_16x16x32_bf16 v[72:75], v[154:157], v[182:185], v[72:75]
	v_mfma_f32_16x16x32_bf16 v[68:71], v[154:157], v[186:189], v[68:71]
	v_mfma_f32_16x16x32_bf16 v[64:67], v[154:157], v[190:193], v[64:67]
	ds_read_b128 v[142:145], v180
	ds_read_b128 v[146:149], v180 offset:2048
	ds_read_b128 v[150:153], v180 offset:4096
	ds_read_b128 v[154:157], v180 offset:6144
	ds_read_b128 v[194:197], v211 offset:32768
	ds_read_b128 v[198:201], v211 offset:34816
	ds_read_b128 v[202:205], v211 offset:36864
	ds_read_b128 v[206:209], v211 offset:38912
	s_waitcnt lgkmcnt(8)
	v_mfma_f32_16x16x32_bf16 v[60:63], v[158:161], v[174:177], v[60:63]
	v_mfma_f32_16x16x32_bf16 v[56:59], v[158:161], v[182:185], v[56:59]
	v_mfma_f32_16x16x32_bf16 v[52:55], v[158:161], v[186:189], v[52:55]
	v_mfma_f32_16x16x32_bf16 v[48:51], v[158:161], v[190:193], v[48:51]
	v_mfma_f32_16x16x32_bf16 v[44:47], v[162:165], v[174:177], v[44:47]
	v_mfma_f32_16x16x32_bf16 v[32:35], v[162:165], v[182:185], v[32:35]
	v_mfma_f32_16x16x32_bf16 v[28:31], v[162:165], v[186:189], v[28:31]
	v_mfma_f32_16x16x32_bf16 v[24:27], v[162:165], v[190:193], v[24:27]
	v_mfma_f32_16x16x32_bf16 v[20:23], v[166:169], v[174:177], v[20:23]
	v_mfma_f32_16x16x32_bf16 v[16:19], v[166:169], v[182:185], v[16:19]
	v_mfma_f32_16x16x32_bf16 v[12:15], v[166:169], v[186:189], v[12:15]
	v_mfma_f32_16x16x32_bf16 v[8:11], v[166:169], v[190:193], v[8:11]
	v_mfma_f32_16x16x32_bf16 v[4:7], v[170:173], v[174:177], v[4:7]
	v_mfma_f32_16x16x32_bf16 v[0:3], v[170:173], v[182:185], v[0:3]
	v_mfma_f32_16x16x32_bf16 v[40:43], v[170:173], v[186:189], v[40:43]
	v_mfma_f32_16x16x32_bf16 v[36:39], v[170:173], v[190:193], v[36:39]
	ds_read_b128 v[158:161], v180 offset:8192
	ds_read_b128 v[162:165], v180 offset:10240
	ds_read_b128 v[166:169], v180 offset:12288
	ds_read_b128 v[170:173], v180 offset:14336
	s_waitcnt lgkmcnt(4)
	v_mfma_f32_16x16x32_bf16 v[124:127], v[142:145], v[194:197], v[124:127]
	v_mfma_f32_16x16x32_bf16 v[120:123], v[142:145], v[198:201], v[120:123]
	v_mfma_f32_16x16x32_bf16 v[116:119], v[142:145], v[202:205], v[116:119]
	v_mfma_f32_16x16x32_bf16 v[112:115], v[142:145], v[206:209], v[112:115]
	v_mfma_f32_16x16x32_bf16 v[108:111], v[146:149], v[194:197], v[108:111]
	v_mfma_f32_16x16x32_bf16 v[104:107], v[146:149], v[198:201], v[104:107]
	v_mfma_f32_16x16x32_bf16 v[100:103], v[146:149], v[202:205], v[100:103]
	v_mfma_f32_16x16x32_bf16 v[96:99], v[146:149], v[206:209], v[96:99]
	v_mfma_f32_16x16x32_bf16 v[92:95], v[150:153], v[194:197], v[92:95]
	v_mfma_f32_16x16x32_bf16 v[88:91], v[150:153], v[198:201], v[88:91]
	v_mfma_f32_16x16x32_bf16 v[84:87], v[150:153], v[202:205], v[84:87]
	v_mfma_f32_16x16x32_bf16 v[80:83], v[150:153], v[206:209], v[80:83]
	v_mfma_f32_16x16x32_bf16 v[76:79], v[154:157], v[194:197], v[76:79]
	v_mfma_f32_16x16x32_bf16 v[72:75], v[154:157], v[198:201], v[72:75]
	v_mfma_f32_16x16x32_bf16 v[68:71], v[154:157], v[202:205], v[68:71]
	v_mfma_f32_16x16x32_bf16 v[64:67], v[154:157], v[206:209], v[64:67]
	s_add_u32 s44, s44, 0x80
	s_addc_u32 s45, s45, 0
	s_add_i32 s43, s43, 1
	s_cmp_lt_u32 s43, 31
	s_cbranch_scc0 .Lg9_last
	s_waitcnt lgkmcnt(0)
	s_waitcnt vmcnt(0)
	s_barrier
	s_xor_b32 s59, s59, 0x10000
	ds_read_b128 v[142:145], v212
	ds_read_b128 v[146:149], v212 offset:2048
	ds_read_b128 v[150:153], v212 offset:4096
	ds_read_b128 v[154:157], v212 offset:6144
	ds_read_b128 v[174:177], v214 offset:32768
	ds_read_b128 v[182:185], v214 offset:34816
	ds_read_b128 v[186:189], v214 offset:36864
	ds_read_b128 v[190:193], v214 offset:38912
	v_mfma_f32_16x16x32_bf16 v[60:63], v[158:161], v[194:197], v[60:63]
	v_mfma_f32_16x16x32_bf16 v[56:59], v[158:161], v[198:201], v[56:59]
	s_mov_b32 m0, s59
	s_add_u32 s46, s44, s12
	s_addc_u32 s47, s45, s13
	global_load_lds_dwordx4 v178, s[46:47]
	v_mfma_f32_16x16x32_bf16 v[52:55], v[158:161], v[202:205], v[52:55]
	v_mfma_f32_16x16x32_bf16 v[48:51], v[158:161], v[206:209], v[48:51]
	s_add_u32 m0, s59, 0x2000
	s_add_u32 s46, s44, s14
	s_addc_u32 s47, s45, s15
	global_load_lds_dwordx4 v178, s[46:47]
	v_mfma_f32_16x16x32_bf16 v[44:47], v[162:165], v[194:197], v[44:47]
	v_mfma_f32_16x16x32_bf16 v[32:35], v[162:165], v[198:201], v[32:35]
	s_add_u32 m0, s59, 0x4000
	s_add_u32 s46, s44, s16
	s_addc_u32 s47, s45, s17
	global_load_lds_dwordx4 v178, s[46:47]
	v_mfma_f32_16x16x32_bf16 v[28:31], v[162:165], v[202:205], v[28:31]
	v_mfma_f32_16x16x32_bf16 v[24:27], v[162:165], v[206:209], v[24:27]
	s_add_u32 m0, s59, 0x6000
	s_add_u32 s46, s44, s18
	s_addc_u32 s47, s45, s19
	global_load_lds_dwordx4 v178, s[46:47]
	v_mfma_f32_16x16x32_bf16 v[20:23], v[166:169], v[194:197], v[20:23]
	v_mfma_f32_16x16x32_bf16 v[16:19], v[166:169], v[198:201], v[16:19]
	s_add_u32 m0, s59, 0x8000
	s_add_u32 s46, s44, s22
	s_addc_u32 s47, s45, s23
	global_load_lds_dwordx4 v179, s[46:47]
	v_mfma_f32_16x16x32_bf16 v[12:15], v[166:169], v[202:205], v[12:15]
	v_mfma_f32_16x16x32_bf16 v[8:11], v[166:169], v[206:209], v[8:11]
	s_add_u32 m0, s59, 0xa000
	s_add_u32 s46, s44, s36
	s_addc_u32 s47, s45, s37
	global_load_lds_dwordx4 v179, s[46:47]
	v_mfma_f32_16x16x32_bf16 v[4:7], v[170:173], v[194:197], v[4:7]
	v_mfma_f32_16x16x32_bf16 v[0:3], v[170:173], v[198:201], v[0:3]
	s_add_u32 m0, s59, 0xc000
	s_add_u32 s46, s44, s38
	s_addc_u32 s47, s45, s39
	global_load_lds_dwordx4 v179, s[46:47]
	v_mfma_f32_16x16x32_bf16 v[40:43], v[170:173], v[202:205], v[40:43]
	v_mfma_f32_16x16x32_bf16 v[36:39], v[170:173], v[206:209], v[36:39]
	s_add_u32 m0, s59, 0xe000
	s_add_u32 s46, s44, s40
	s_addc_u32 s47, s45, s41
	global_load_lds_dwordx4 v179, s[46:47]
	ds_read_b128 v[158:161], v212 offset:8192
	ds_read_b128 v[162:165], v212 offset:10240
	ds_read_b128 v[166:169], v212 offset:12288
	ds_read_b128 v[170:173], v212 offset:14336
	s_waitcnt lgkmcnt(4)
	v_mfma_f32_16x16x32_bf16 v[124:127], v[142:145], v[174:177], v[124:127]
	v_mfma_f32_16x16x32_bf16 v[120:123], v[142:145], v[182:185], v[120:123]
	v_mfma_f32_16x16x32_bf16 v[116:119], v[142:145], v[186:189], v[116:119]
	v_mfma_f32_16x16x32_bf16 v[112:115], v[142:145], v[190:193], v[112:115]
	v_mfma_f32_16x16x32_bf16 v[108:111], v[146:149], v[174:177], v[108:111]
	v_mfma_f32_16x16x32_bf16 v[104:107], v[146:149], v[182:185], v[104:107]
	v_mfma_f32_16x16x32_bf16 v[100:103], v[146:149], v[186:189], v[100:103]
	v_mfma_f32_16x16x32_bf16 v[96:99], v[146:149], v[190:193], v[96:99]
	v_mfma_f32_16x16x32_bf16 v[92:95], v[150:153], v[174:177], v[92:95]
	v_mfma_f32_16x16x32_bf16 v[88:91], v[150:153], v[182:185], v[88:91]
	v_mfma_f32_16x16x32_bf16 v[84:87], v[150:153], v[186:189], v[84:87]
	v_mfma_f32_16x16x32_bf16 v[80:83], v[150:153], v[190:193], v[80:83]
	v_mfma_f32_16x16x32_bf16 v[76:79], v[154:157], v[174:177], v[76:79]
	v_mfma_f32_16x16x32_bf16 v[72:75], v[154:157], v[182:185], v[72:75]
	v_mfma_f32_16x16x32_bf16 v[68:71], v[154:157], v[186:189], v[68:71]
	v_mfma_f32_16x16x32_bf16 v[64:67], v[154:157], v[190:193], v[64:67]
	ds_read_b128 v[142:145], v213
	ds_read_b128 v[146:149], v213 offset:2048
	ds_read_b128 v[150:153], v213 offset:4096
	ds_read_b128 v[154:157], v213 offset:6144
	ds_read_b128 v[194:197], v215 offset:32768
	ds_read_b128 v[198:201], v215 offset:34816
	ds_read_b128 v[202:205], v215 offset:36864
	ds_read_b128 v[206:209], v215 offset:38912
	s_waitcnt lgkmcnt(8)
	v_mfma_f32_16x16x32_bf16 v[60:63], v[158:161], v[174:177], v[60:63]
	v_mfma_f32_16x16x32_bf16 v[56:59], v[158:161], v[182:185], v[56:59]
	v_mfma_f32_16x16x32_bf16 v[52:55], v[158:161], v[186:189], v[52:55]
	v_mfma_f32_16x16x32_bf16 v[48:51], v[158:161], v[190:193], v[48:51]
	v_mfma_f32_16x16x32_bf16 v[44:47], v[162:165], v[174:177], v[44:47]
	v_mfma_f32_16x16x32_bf16 v[32:35], v[162:165], v[182:185], v[32:35]
	v_mfma_f32_16x16x32_bf16 v[28:31], v[162:165], v[186:189], v[28:31]
	v_mfma_f32_16x16x32_bf16 v[24:27], v[162:165], v[190:193], v[24:27]
	v_mfma_f32_16x16x32_bf16 v[20:23], v[166:169], v[174:177], v[20:23]
	v_mfma_f32_16x16x32_bf16 v[16:19], v[166:169], v[182:185], v[16:19]
	v_mfma_f32_16x16x32_bf16 v[12:15], v[166:169], v[186:189], v[12:15]
	v_mfma_f32_16x16x32_bf16 v[8:11], v[166:169], v[190:193], v[8:11]
	v_mfma_f32_16x16x32_bf16 v[4:7], v[170:173], v[174:177], v[4:7]
	v_mfma_f32_16x16x32_bf16 v[0:3], v[170:173], v[182:185], v[0:3]
	v_mfma_f32_16x16x32_bf16 v[40:43], v[170:173], v[186:189], v[40:43]
	v_mfma_f32_16x16x32_bf16 v[36:39], v[170:173], v[190:193], v[36:39]
	ds_read_b128 v[158:161], v213 offset:8192
	ds_read_b128 v[162:165], v213 offset:10240
	ds_read_b128 v[166:169], v213 offset:12288
	ds_read_b128 v[170:173], v213 offset:14336
	s_waitcnt lgkmcnt(4)
	v_mfma_f32_16x16x32_bf16 v[124:127], v[142:145], v[194:197], v[124:127]
	v_mfma_f32_16x16x32_bf16 v[120:123], v[142:145], v[198:201], v[120:123]
	v_mfma_f32_16x16x32_bf16 v[116:119], v[142:145], v[202:205], v[116:119]
	v_mfma_f32_16x16x32_bf16 v[112:115], v[142:145], v[206:209], v[112:115]
	v_mfma_f32_16x16x32_bf16 v[108:111], v[146:149], v[194:197], v[108:111]
	v_mfma_f32_16x16x32_bf16 v[104:107], v[146:149], v[198:201], v[104:107]
	v_mfma_f32_16x16x32_bf16 v[100:103], v[146:149], v[202:205], v[100:103]
	v_mfma_f32_16x16x32_bf16 v[96:99], v[146:149], v[206:209], v[96:99]
	v_mfma_f32_16x16x32_bf16 v[92:95], v[150:153], v[194:197], v[92:95]
	v_mfma_f32_16x16x32_bf16 v[88:91], v[150:153], v[198:201], v[88:91]
	v_mfma_f32_16x16x32_bf16 v[84:87], v[150:153], v[202:205], v[84:87]
	v_mfma_f32_16x16x32_bf16 v[80:83], v[150:153], v[206:209], v[80:83]
	v_mfma_f32_16x16x32_bf16 v[76:79], v[154:157], v[194:197], v[76:79]
	v_mfma_f32_16x16x32_bf16 v[72:75], v[154:157], v[198:201], v[72:75]
	v_mfma_f32_16x16x32_bf16 v[68:71], v[154:157], v[202:205], v[68:71]
	v_mfma_f32_16x16x32_bf16 v[64:67], v[154:157], v[206:209], v[64:67]
	s_add_u32 s44, s44, 0x80
	s_addc_u32 s45, s45, 0
	s_add_i32 s43, s43, 1
	s_branch .Lg9_top
.Lg9_last:
	s_waitcnt lgkmcnt(0)
	s_waitcnt vmcnt(0)
	s_barrier
	s_xor_b32 s59, s59, 0x10000
	ds_read_b128 v[142:145], v212
	ds_read_b128 v[146:149], v212 offset:2048
	ds_read_b128 v[150:153], v212 offset:4096
	ds_read_b128 v[154:157], v212 offset:6144
	ds_read_b128 v[174:177], v214 offset:32768
	ds_read_b128 v[182:185], v214 offset:34816
	ds_read_b128 v[186:189], v214 offset:36864
	ds_read_b128 v[190:193], v214 offset:38912
	v_mfma_f32_16x16x32_bf16 v[60:63], v[158:161], v[194:197], v[60:63]
	v_mfma_f32_16x16x32_bf16 v[56:59], v[158:161], v[198:201], v[56:59]
	v_mfma_f32_16x16x32_bf16 v[52:55], v[158:161], v[202:205], v[52:55]
	v_mfma_f32_16x16x32_bf16 v[48:51], v[158:161], v[206:209], v[48:51]
	v_mfma_f32_16x16x32_bf16 v[44:47], v[162:165], v[194:197], v[44:47]
	v_mfma_f32_16x16x32_bf16 v[32:35], v[162:165], v[198:201], v[32:35]
	v_mfma_f32_16x16x32_bf16 v[28:31], v[162:165], v[202:205], v[28:31]
	v_mfma_f32_16x16x32_bf16 v[24:27], v[162:165], v[206:209], v[24:27]
	v_mfma_f32_16x16x32_bf16 v[20:23], v[166:169], v[194:197], v[20:23]
	v_mfma_f32_16x16x32_bf16 v[16:19], v[166:169], v[198:201], v[16:19]
	v_mfma_f32_16x16x32_bf16 v[12:15], v[166:169], v[202:205], v[12:15]
	v_mfma_f32_16x16x32_bf16 v[8:11], v[166:169], v[206:209], v[8:11]
	v_mfma_f32_16x16x32_bf16 v[4:7], v[170:173], v[194:197], v[4:7]
	v_mfma_f32_16x16x32_bf16 v[0:3], v[170:173], v[198:201], v[0:3]
	v_mfma_f32_16x16x32_bf16 v[40:43], v[170:173], v[202:205], v[40:43]
	v_mfma_f32_16x16x32_bf16 v[36:39], v[170:173], v[206:209], v[36:39]
	ds_read_b128 v[158:161], v212 offset:8192
	ds_read_b128 v[162:165], v212 offset:10240
	ds_read_b128 v[166:169], v212 offset:12288
	ds_read_b128 v[170:173], v212 offset:14336
	s_waitcnt lgkmcnt(4)
	v_mfma_f32_16x16x32_bf16 v[124:127], v[142:145], v[174:177], v[124:127]
	v_mfma_f32_16x16x32_bf16 v[120:123], v[142:145], v[182:185], v[120:123]
	v_mfma_f32_16x16x32_bf16 v[116:119], v[142:145], v[186:189], v[116:119]
	v_mfma_f32_16x16x32_bf16 v[112:115], v[142:145], v[190:193], v[112:115]
	v_mfma_f32_16x16x32_bf16 v[108:111], v[146:149], v[174:177], v[108:111]
	v_mfma_f32_16x16x32_bf16 v[104:107], v[146:149], v[182:185], v[104:107]
	v_mfma_f32_16x16x32_bf16 v[100:103], v[146:149], v[186:189], v[100:103]
	v_mfma_f32_16x16x32_bf16 v[96:99], v[146:149], v[190:193], v[96:99]
	v_mfma_f32_16x16x32_bf16 v[92:95], v[150:153], v[174:177], v[92:95]
	v_mfma_f32_16x16x32_bf16 v[88:91], v[150:153], v[182:185], v[88:91]
	v_mfma_f32_16x16x32_bf16 v[84:87], v[150:153], v[186:189], v[84:87]
	v_mfma_f32_16x16x32_bf16 v[80:83], v[150:153], v[190:193], v[80:83]
	v_mfma_f32_16x16x32_bf16 v[76:79], v[154:157], v[174:177], v[76:79]
	v_mfma_f32_16x16x32_bf16 v[72:75], v[154:157], v[182:185], v[72:75]
	v_mfma_f32_16x16x32_bf16 v[68:71], v[154:157], v[186:189], v[68:71]
	v_mfma_f32_16x16x32_bf16 v[64:67], v[154:157], v[190:193], v[64:67]
	ds_read_b128 v[142:145], v213
	ds_read_b128 v[146:149], v213 offset:2048
	ds_read_b128 v[150:153], v213 offset:4096
	ds_read_b128 v[154:157], v213 offset:6144
	ds_read_b128 v[194:197], v215 offset:32768
	ds_read_b128 v[198:201], v215 offset:34816
	ds_read_b128 v[202:205], v215 offset:36864
	ds_read_b128 v[206:209], v215 offset:38912
	s_waitcnt lgkmcnt(8)
	v_mfma_f32_16x16x32_bf16 v[60:63], v[158:161], v[174:177], v[60:63]
	v_mfma_f32_16x16x32_bf16 v[56:59], v[158:161], v[182:185], v[56:59]
	v_mfma_f32_16x16x32_bf16 v[52:55], v[158:161], v[186:189], v[52:55]
	v_mfma_f32_16x16x32_bf16 v[48:51], v[158:161], v[190:193], v[48:51]
	v_mfma_f32_16x16x32_bf16 v[44:47], v[162:165], v[174:177], v[44:47]
	v_mfma_f32_16x16x32_bf16 v[32:35], v[162:165], v[182:185], v[32:35]
	v_mfma_f32_16x16x32_bf16 v[28:31], v[162:165], v[186:189], v[28:31]
	v_mfma_f32_16x16x32_bf16 v[24:27], v[162:165], v[190:193], v[24:27]
	v_mfma_f32_16x16x32_bf16 v[20:23], v[166:169], v[174:177], v[20:23]
	v_mfma_f32_16x16x32_bf16 v[16:19], v[166:169], v[182:185], v[16:19]
	v_mfma_f32_16x16x32_bf16 v[12:15], v[166:169], v[186:189], v[12:15]
	v_mfma_f32_16x16x32_bf16 v[8:11], v[166:169], v[190:193], v[8:11]
	v_mfma_f32_16x16x32_bf16 v[4:7], v[170:173], v[174:177], v[4:7]
	v_mfma_f32_16x16x32_bf16 v[0:3], v[170:173], v[182:185], v[0:3]
	v_mfma_f32_16x16x32_bf16 v[40:43], v[170:173], v[186:189], v[40:43]
	v_mfma_f32_16x16x32_bf16 v[36:39], v[170:173], v[190:193], v[36:39]
	ds_read_b128 v[158:161], v213 offset:8192
	ds_read_b128 v[162:165], v213 offset:10240
	ds_read_b128 v[166:169], v213 offset:12288
	ds_read_b128 v[170:173], v213 offset:14336
	s_waitcnt lgkmcnt(4)
	v_mfma_f32_16x16x32_bf16 v[124:127], v[142:145], v[194:197], v[124:127]
	v_mfma_f32_16x16x32_bf16 v[120:123], v[142:145], v[198:201], v[120:123]
	v_mfma_f32_16x16x32_bf16 v[116:119], v[142:145], v[202:205], v[116:119]
	v_mfma_f32_16x16x32_bf16 v[112:115], v[142:145], v[206:209], v[112:115]
	v_mfma_f32_16x16x32_bf16 v[108:111], v[146:149], v[194:197], v[108:111]
	v_mfma_f32_16x16x32_bf16 v[104:107], v[146:149], v[198:201], v[104:107]
	v_mfma_f32_16x16x32_bf16 v[100:103], v[146:149], v[202:205], v[100:103]
	v_mfma_f32_16x16x32_bf16 v[96:99], v[146:149], v[206:209], v[96:99]
	v_mfma_f32_16x16x32_bf16 v[92:95], v[150:153], v[194:197], v[92:95]
	v_mfma_f32_16x16x32_bf16 v[88:91], v[150:153], v[198:201], v[88:91]
	v_mfma_f32_16x16x32_bf16 v[84:87], v[150:153], v[202:205], v[84:87]
	v_mfma_f32_16x16x32_bf16 v[80:83], v[150:153], v[206:209], v[80:83]
	v_mfma_f32_16x16x32_bf16 v[76:79], v[154:157], v[194:197], v[76:79]
	v_mfma_f32_16x16x32_bf16 v[72:75], v[154:157], v[198:201], v[72:75]
	v_mfma_f32_16x16x32_bf16 v[68:71], v[154:157], v[202:205], v[68:71]
	v_mfma_f32_16x16x32_bf16 v[64:67], v[154:157], v[206:209], v[64:67]
	s_add_u32 s44, s44, 0x80
	s_addc_u32 s45, s45, 0
	s_add_i32 s43, s43, 1
	s_waitcnt lgkmcnt(0)
	s_waitcnt vmcnt(0)
	s_barrier
	v_mfma_f32_16x16x32_bf16 v[60:63], v[158:161], v[194:197], v[60:63]
	v_mfma_f32_16x16x32_bf16 v[56:59], v[158:161], v[198:201], v[56:59]
	v_mfma_f32_16x16x32_bf16 v[52:55], v[158:161], v[202:205], v[52:55]
	v_mfma_f32_16x16x32_bf16 v[48:51], v[158:161], v[206:209], v[48:51]
	v_mfma_f32_16x16x32_bf16 v[44:47], v[162:165], v[194:197], v[44:47]
	v_mfma_f32_16x16x32_bf16 v[32:35], v[162:165], v[198:201], v[32:35]
	v_mfma_f32_16x16x32_bf16 v[28:31], v[162:165], v[202:205], v[28:31]
	v_mfma_f32_16x16x32_bf16 v[24:27], v[162:165], v[206:209], v[24:27]
	v_mfma_f32_16x16x32_bf16 v[20:23], v[166:169], v[194:197], v[20:23]
	v_mfma_f32_16x16x32_bf16 v[16:19], v[166:169], v[198:201], v[16:19]
	v_mfma_f32_16x16x32_bf16 v[12:15], v[166:169], v[202:205], v[12:15]
	v_mfma_f32_16x16x32_bf16 v[8:11], v[166:169], v[206:209], v[8:11]
	v_mfma_f32_16x16x32_bf16 v[4:7], v[170:173], v[194:197], v[4:7]
	v_mfma_f32_16x16x32_bf16 v[0:3], v[170:173], v[198:201], v[0:3]
	v_mfma_f32_16x16x32_bf16 v[40:43], v[170:173], v[202:205], v[40:43]
	v_mfma_f32_16x16x32_bf16 v[36:39], v[170:173], v[206:209], v[36:39]
	s_nop 7
	s_nop 7
	s_sub_u32 s44, s44, s34
	s_subb_u32 s45, s45, s35
	s_mov_b32 s59, 0x100000
	s_mov_b32 s60, 0x100000
	s_mov_b64 s[46:47], 0
	s_mov_b64 vcc, exec
	s_branch .LBB0_1330

.LBB0_1488:
	v_mov_b32_e32 v6, v181
	s_ashr_i32 s51, s50, 6
	v_lshrrev_b32_e32 v7, 4, v6
	v_lshlrev_b32_e32 v1, 6, v6
	v_xor_b32_e32 v0, v7, v6
	v_and_b32_e32 v8, 0x3c0, v1
	v_lshlrev_b32_e32 v1, 7, v6
	s_bfe_u32 s52, s50, 0x20006
	s_and_b32 s56, s49, 63
	s_and_b32 s53, s50, 63
	s_and_b32 s20, s51, -4
	v_lshlrev_b32_e32 v0, 3, v0
	v_and_b32_e32 v1, 0xfffffc00, v1
	s_lshl_b32 s46, s56, 19
	s_or_b32 s42, s20, s52
	s_lshl_b32 s20, s53, 19
	v_and_or_b32 v0, v0, 56, v1
	s_add_u32 s20, s3, s20
	v_ashrrev_i32_e32 v1, 31, v0
	s_addc_u32 s21, s48, 0
	v_lshlrev_b64 v[0:1], 1, v[0:1]
	v_lshl_add_u32 v129, v6, 4, 0
	v_lshl_add_u64 v[2:3], s[20:21], 0, v[0:1]
	v_readfirstlane_b32 s20, v129
	v_add_u32_e32 v9, 0x2000, v129
	s_mov_b32 m0, s20
	v_readfirstlane_b32 s20, v9
	v_add_u32_e32 v9, 0x4000, v129
	s_waitcnt vmcnt(63) expcnt(7) lgkmcnt(15)
	s_barrier
	global_load_lds_dwordx4 v[2:3], off
	v_lshl_add_u64 v[4:5], v[2:3], 0, s[8:9]
	s_mov_b32 m0, s20
	v_readfirstlane_b32 s20, v9
	global_load_lds_dwordx4 v[4:5], off
	v_lshl_add_u64 v[4:5], v[2:3], 0, s[10:11]
	s_mov_b32 m0, s20
	s_ashr_i32 s43, s42, 31
	global_load_lds_dwordx4 v[4:5], off
	v_add_u32_e32 v4, 0x6000, v129
	s_lshl_b64 s[44:45], s[42:43], 19
	v_readfirstlane_b32 s20, v4
	v_lshl_add_u64 v[2:3], v[2:3], 0, s[12:13]
	s_mov_b32 m0, s20
	s_add_u32 s44, s34, s44
	global_load_lds_dwordx4 v[2:3], off
	v_add_u32_e32 v2, 0x8000, v129
	s_addc_u32 s45, s35, s45
	v_readfirstlane_b32 s20, v2
	v_add_u32_e32 v4, 0xa000, v129
	v_lshl_add_u64 v[134:135], s[44:45], 0, v[0:1]
	s_mov_b32 m0, s20
	v_readfirstlane_b32 s20, v4
	v_add_u32_e32 v4, 0xc000, v129
	global_load_lds_dwordx4 v[134:135], off
	v_lshl_add_u64 v[2:3], v[134:135], 0, s[8:9]
	s_mov_b32 m0, s20
	v_readfirstlane_b32 s20, v4
	v_add_u32_e32 v4, 0xe000, v129
	global_load_lds_dwordx4 v[2:3], off
	v_lshl_add_u64 v[2:3], v[134:135], 0, s[10:11]
	s_mov_b32 m0, s20
	v_readfirstlane_b32 s20, v4
	global_load_lds_dwordx4 v[2:3], off
	v_lshl_add_u64 v[2:3], v[134:135], 0, s[12:13]
	s_mov_b32 m0, s20
	v_ashrrev_i32_e32 v4, 6, v6
	global_load_lds_dwordx4 v[2:3], off
	v_lshrrev_b32_e32 v5, 30, v4
	v_add_u32_e32 v5, v4, v5
	v_bfe_u32 v2, v6, 4, 2
	v_bfe_u32 v3, v6, 1, 3
	v_and_b32_e32 v6, 0x7fffc, v5
	v_sub_u32_e32 v4, v4, v6
	v_lshlrev_b32_e32 v139, 13, v4
	v_bitop3_b32 v4, v7, v3, 3 bitop3:0x6c
	v_bitop3_b32 v2, v2, v3, 4 bitop3:0x36
	s_add_u32 s20, s34, s46
	v_lshlrev_b32_e32 v5, 12, v5
	v_lshlrev_b32_e32 v4, 3, v4
	v_lshlrev_b32_e32 v2, 3, v2
	s_addc_u32 s21, s35, 0
	v_and_b32_e32 v138, 0xffffc000, v5
	v_lshl_add_u64 v[136:137], s[20:21], 0, v[0:1]
	s_mov_b64 s[44:45], 0
	s_waitcnt lgkmcnt(0)
	v_lshlrev_b32_e32 v140, 1, v8
	v_lshlrev_b32_e32 v141, 1, v4
	v_lshlrev_b32_e32 v142, 1, v2
	s_mov_b32 s57, 0
	s_mov_b32 s43, 0
	v_mov_b32_e32 v8, v128
	v_mov_b32_e32 v9, v128
	v_mov_b32_e32 v10, v128
	v_mov_b32_e32 v11, v128
	v_mov_b32_e32 v20, v128
	v_mov_b32_e32 v21, v128
	v_mov_b32_e32 v22, v128
	v_mov_b32_e32 v23, v128
	v_mov_b32_e32 v0, v128
	v_mov_b32_e32 v1, v128
	v_mov_b32_e32 v2, v128
	v_mov_b32_e32 v3, v128
	v_mov_b32_e32 v4, v128
	v_mov_b32_e32 v5, v128
	v_mov_b32_e32 v6, v128
	v_mov_b32_e32 v7, v128
	v_mov_b32_e32 v12, v128
	v_mov_b32_e32 v13, v128
	v_mov_b32_e32 v14, v128
	v_mov_b32_e32 v15, v128
	v_mov_b32_e32 v24, v128
	v_mov_b32_e32 v25, v128
	v_mov_b32_e32 v26, v128
	v_mov_b32_e32 v27, v128
	v_mov_b32_e32 v16, v128
	v_mov_b32_e32 v17, v128
	v_mov_b32_e32 v18, v128
	v_mov_b32_e32 v19, v128
	v_mov_b32_e32 v28, v128
	v_mov_b32_e32 v29, v128
	v_mov_b32_e32 v30, v128
	v_mov_b32_e32 v31, v128
	v_mov_b32_e32 v32, v128
	v_mov_b32_e32 v33, v128
	v_mov_b32_e32 v34, v128
	v_mov_b32_e32 v35, v128
	v_mov_b32_e32 v40, v128
	v_mov_b32_e32 v41, v128
	v_mov_b32_e32 v42, v128
	v_mov_b32_e32 v43, v128
	v_mov_b32_e32 v36, v128
	v_mov_b32_e32 v37, v128
	v_mov_b32_e32 v38, v128
	v_mov_b32_e32 v39, v128
	v_mov_b32_e32 v44, v128
	v_mov_b32_e32 v45, v128
	v_mov_b32_e32 v46, v128
	v_mov_b32_e32 v47, v128
	v_mov_b32_e32 v48, v128
	v_mov_b32_e32 v49, v128
	v_mov_b32_e32 v50, v128
	v_mov_b32_e32 v51, v128
	v_mov_b32_e32 v56, v128
	v_mov_b32_e32 v57, v128
	v_mov_b32_e32 v58, v128
	v_mov_b32_e32 v59, v128
	v_mov_b32_e32 v52, v128
	v_mov_b32_e32 v53, v128
	v_mov_b32_e32 v54, v128
	v_mov_b32_e32 v55, v128
	v_mov_b32_e32 v60, v128
	v_mov_b32_e32 v61, v128
	v_mov_b32_e32 v62, v128
	v_mov_b32_e32 v63, v128
	v_mov_b32_e32 v64, v128
	v_mov_b32_e32 v65, v128
	v_mov_b32_e32 v66, v128
	v_mov_b32_e32 v67, v128
	v_mov_b32_e32 v72, v128
	v_mov_b32_e32 v73, v128
	v_mov_b32_e32 v74, v128
	v_mov_b32_e32 v75, v128
	v_mov_b32_e32 v68, v128
	v_mov_b32_e32 v69, v128
	v_mov_b32_e32 v70, v128
	v_mov_b32_e32 v71, v128
	v_mov_b32_e32 v76, v128
	v_mov_b32_e32 v77, v128
	v_mov_b32_e32 v78, v128
	v_mov_b32_e32 v79, v128
	v_mov_b32_e32 v80, v128
	v_mov_b32_e32 v81, v128
	v_mov_b32_e32 v82, v128
	v_mov_b32_e32 v83, v128
	v_mov_b32_e32 v88, v128
	v_mov_b32_e32 v89, v128
	v_mov_b32_e32 v90, v128
	v_mov_b32_e32 v91, v128
	v_mov_b32_e32 v84, v128
	v_mov_b32_e32 v85, v128
	v_mov_b32_e32 v86, v128
	v_mov_b32_e32 v87, v128
	v_mov_b32_e32 v92, v128
	v_mov_b32_e32 v93, v128
	v_mov_b32_e32 v94, v128
	v_mov_b32_e32 v95, v128
	v_mov_b32_e32 v96, v128
	v_mov_b32_e32 v97, v128
	v_mov_b32_e32 v98, v128
	v_mov_b32_e32 v99, v128
	v_mov_b32_e32 v104, v128
	v_mov_b32_e32 v105, v128
	v_mov_b32_e32 v106, v128
	v_mov_b32_e32 v107, v128
	v_mov_b32_e32 v100, v128
	v_mov_b32_e32 v101, v128
	v_mov_b32_e32 v102, v128
	v_mov_b32_e32 v103, v128
	v_mov_b32_e32 v108, v128
	v_mov_b32_e32 v109, v128
	v_mov_b32_e32 v110, v128
	v_mov_b32_e32 v111, v128
	v_mov_b32_e32 v112, v128
	v_mov_b32_e32 v113, v128
	v_mov_b32_e32 v114, v128
	v_mov_b32_e32 v115, v128
	v_mov_b32_e32 v120, v128
	v_mov_b32_e32 v121, v128
	v_mov_b32_e32 v122, v128
	v_mov_b32_e32 v123, v128
	v_mov_b32_e32 v116, v128
	v_mov_b32_e32 v117, v128
	v_mov_b32_e32 v118, v128
	v_mov_b32_e32 v119, v128
	v_mov_b32_e32 v124, v128
	v_mov_b32_e32 v125, v128
	v_mov_b32_e32 v126, v128
	v_mov_b32_e32 v127, v128
	s_waitcnt vmcnt(0) lgkmcnt(0)
	s_barrier
	v_add3_u32 v143, v138, v140, v141
	v_add3_u32 v180, v139, v140, v141
	v_add3_u32 v155, v138, v140, v142
	v_add3_u32 v222, v139, v140, v142
	v_xor_b32_e32 v223, 0x10000, v143
	v_xor_b32_e32 v224, 0x10000, v155
	v_xor_b32_e32 v225, 0x10000, v180
	v_xor_b32_e32 v226, 0x10000, v222
	v_readfirstlane_b32 s57, v129
	ds_read_b128 v[156:159], v143
	ds_read_b128 v[160:163], v143 offset:2048
	ds_read_b128 v[164:167], v143 offset:4096
	ds_read_b128 v[168:171], v143 offset:6144
	ds_read_b128 v[190:193], v180 offset:32768
	ds_read_b128 v[194:197], v180 offset:34816
	ds_read_b128 v[198:201], v180 offset:36864
	ds_read_b128 v[202:205], v180 offset:38912
	s_mov_b32 s43, 0
	s_mov_b64 s[44:45], s[34:35]
	v_subrev_u32_e32 v144, s34, v136
	v_subrev_u32_e32 v145, s34, v134
	s_add_u32 s57, s57, 0x10000
	s_mov_b32 m0, s57
	s_add_u32 s46, s44, s14
	s_addc_u32 s47, s45, s15
	global_load_lds_dwordx4 v144, s[46:47]
	s_add_u32 m0, s57, 0x2000
	s_add_u32 s46, s44, s16
	s_addc_u32 s47, s45, s17
	global_load_lds_dwordx4 v144, s[46:47]
	s_add_u32 m0, s57, 0x4000
	s_add_u32 s46, s44, s18
	s_addc_u32 s47, s45, s19
	global_load_lds_dwordx4 v144, s[46:47]
	s_add_u32 m0, s57, 0x6000
	s_add_u32 s46, s44, s22
	s_addc_u32 s47, s45, s23
	global_load_lds_dwordx4 v144, s[46:47]
	s_add_u32 m0, s57, 0x8000
	s_add_u32 s46, s44, s30
	s_addc_u32 s47, s45, s31
	global_load_lds_dwordx4 v145, s[46:47]
	s_add_u32 m0, s57, 0xa000
	s_add_u32 s46, s44, s36
	s_addc_u32 s47, s45, s37
	global_load_lds_dwordx4 v145, s[46:47]
	s_add_u32 m0, s57, 0xc000
	s_add_u32 s46, s44, s38
	s_addc_u32 s47, s45, s39
	global_load_lds_dwordx4 v145, s[46:47]
	s_add_u32 m0, s57, 0xe000
	s_add_u32 s46, s44, s40
	s_addc_u32 s47, s45, s41
	global_load_lds_dwordx4 v145, s[46:47]
	s_branch .Lg10_entry
.Lg10_top:
	s_waitcnt lgkmcnt(0)
	s_waitcnt vmcnt(0)
	s_barrier
	s_xor_b32 s57, s57, 0x10000
	ds_read_b128 v[156:159], v143
	ds_read_b128 v[160:163], v143 offset:2048
	ds_read_b128 v[164:167], v143 offset:4096
	ds_read_b128 v[168:171], v143 offset:6144
	ds_read_b128 v[190:193], v180 offset:32768
	ds_read_b128 v[194:197], v180 offset:34816
	ds_read_b128 v[198:201], v180 offset:36864
	ds_read_b128 v[202:205], v180 offset:38912
	v_mfma_f32_16x16x32_bf16 v[60:63], v[172:175], v[206:209], v[60:63]
	v_mfma_f32_16x16x32_bf16 v[52:55], v[172:175], v[210:213], v[52:55]
	s_mov_b32 m0, s57
	s_add_u32 s46, s44, s14
	s_addc_u32 s47, s45, s15
	global_load_lds_dwordx4 v144, s[46:47]
	v_mfma_f32_16x16x32_bf16 v[56:59], v[172:175], v[214:217], v[56:59]
	v_mfma_f32_16x16x32_bf16 v[48:51], v[172:175], v[218:221], v[48:51]
	s_add_u32 m0, s57, 0x2000
	s_add_u32 s46, s44, s16
	s_addc_u32 s47, s45, s17
	global_load_lds_dwordx4 v144, s[46:47]
	v_mfma_f32_16x16x32_bf16 v[44:47], v[176:179], v[206:209], v[44:47]
	v_mfma_f32_16x16x32_bf16 v[36:39], v[176:179], v[210:213], v[36:39]
	s_add_u32 m0, s57, 0x4000
	s_add_u32 s46, s44, s18
	s_addc_u32 s47, s45, s19
	global_load_lds_dwordx4 v144, s[46:47]
	v_mfma_f32_16x16x32_bf16 v[40:43], v[176:179], v[214:217], v[40:43]
	v_mfma_f32_16x16x32_bf16 v[32:35], v[176:179], v[218:221], v[32:35]
	s_add_u32 m0, s57, 0x6000
	s_add_u32 s46, s44, s22
	s_addc_u32 s47, s45, s23
	global_load_lds_dwordx4 v144, s[46:47]
	v_mfma_f32_16x16x32_bf16 v[28:31], v[182:185], v[206:209], v[28:31]
	v_mfma_f32_16x16x32_bf16 v[16:19], v[182:185], v[210:213], v[16:19]
	s_add_u32 m0, s57, 0x8000
	s_add_u32 s46, s44, s30
	s_addc_u32 s47, s45, s31
	global_load_lds_dwordx4 v145, s[46:47]
	v_mfma_f32_16x16x32_bf16 v[24:27], v[182:185], v[214:217], v[24:27]
	v_mfma_f32_16x16x32_bf16 v[12:15], v[182:185], v[218:221], v[12:15]
	s_add_u32 m0, s57, 0xa000
	s_add_u32 s46, s44, s36
	s_addc_u32 s47, s45, s37
	global_load_lds_dwordx4 v145, s[46:47]
	v_mfma_f32_16x16x32_bf16 v[4:7], v[186:189], v[206:209], v[4:7]
	v_mfma_f32_16x16x32_bf16 v[0:3], v[186:189], v[210:213], v[0:3]
	s_add_u32 m0, s57, 0xc000
	s_add_u32 s46, s44, s38
	s_addc_u32 s47, s45, s39
	global_load_lds_dwordx4 v145, s[46:47]
	v_mfma_f32_16x16x32_bf16 v[20:23], v[186:189], v[214:217], v[20:23]
	v_mfma_f32_16x16x32_bf16 v[8:11], v[186:189], v[218:221], v[8:11]
	s_add_u32 m0, s57, 0xe000
	s_add_u32 s46, s44, s40
	s_addc_u32 s47, s45, s41
	global_load_lds_dwordx4 v145, s[46:47]
.Lg10_entry:
	ds_read_b128 v[172:175], v143 offset:8192
	ds_read_b128 v[176:179], v143 offset:10240
	ds_read_b128 v[182:185], v143 offset:12288
	ds_read_b128 v[186:189], v143 offset:14336
	s_waitcnt lgkmcnt(4)
	v_mfma_f32_16x16x32_bf16 v[124:127], v[156:159], v[190:193], v[124:127]
	v_mfma_f32_16x16x32_bf16 v[116:119], v[156:159], v[194:197], v[116:119]
	v_mfma_f32_16x16x32_bf16 v[120:123], v[156:159], v[198:201], v[120:123]
	v_mfma_f32_16x16x32_bf16 v[112:115], v[156:159], v[202:205], v[112:115]
	v_mfma_f32_16x16x32_bf16 v[108:111], v[160:163], v[190:193], v[108:111]
	v_mfma_f32_16x16x32_bf16 v[100:103], v[160:163], v[194:197], v[100:103]
	v_mfma_f32_16x16x32_bf16 v[104:107], v[160:163], v[198:201], v[104:107]
	v_mfma_f32_16x16x32_bf16 v[96:99], v[160:163], v[202:205], v[96:99]
	v_mfma_f32_16x16x32_bf16 v[92:95], v[164:167], v[190:193], v[92:95]
	v_mfma_f32_16x16x32_bf16 v[84:87], v[164:167], v[194:197], v[84:87]
	v_mfma_f32_16x16x32_bf16 v[88:91], v[164:167], v[198:201], v[88:91]
	v_mfma_f32_16x16x32_bf16 v[80:83], v[164:167], v[202:205], v[80:83]
	v_mfma_f32_16x16x32_bf16 v[76:79], v[168:171], v[190:193], v[76:79]
	v_mfma_f32_16x16x32_bf16 v[68:71], v[168:171], v[194:197], v[68:71]
	v_mfma_f32_16x16x32_bf16 v[72:75], v[168:171], v[198:201], v[72:75]
	v_mfma_f32_16x16x32_bf16 v[64:67], v[168:171], v[202:205], v[64:67]
	ds_read_b128 v[156:159], v155
	ds_read_b128 v[160:163], v155 offset:2048
	ds_read_b128 v[164:167], v155 offset:4096
	ds_read_b128 v[168:171], v155 offset:6144
	ds_read_b128 v[206:209], v222 offset:32768
	ds_read_b128 v[210:213], v222 offset:34816
	ds_read_b128 v[214:217], v222 offset:36864
	ds_read_b128 v[218:221], v222 offset:38912
	s_waitcnt lgkmcnt(8)
	v_mfma_f32_16x16x32_bf16 v[60:63], v[172:175], v[190:193], v[60:63]
	v_mfma_f32_16x16x32_bf16 v[52:55], v[172:175], v[194:197], v[52:55]
	v_mfma_f32_16x16x32_bf16 v[56:59], v[172:175], v[198:201], v[56:59]
	v_mfma_f32_16x16x32_bf16 v[48:51], v[172:175], v[202:205], v[48:51]
	v_mfma_f32_16x16x32_bf16 v[44:47], v[176:179], v[190:193], v[44:47]
	v_mfma_f32_16x16x32_bf16 v[36:39], v[176:179], v[194:197], v[36:39]
	v_mfma_f32_16x16x32_bf16 v[40:43], v[176:179], v[198:201], v[40:43]
	v_mfma_f32_16x16x32_bf16 v[32:35], v[176:179], v[202:205], v[32:35]
	v_mfma_f32_16x16x32_bf16 v[28:31], v[182:185], v[190:193], v[28:31]
	v_mfma_f32_16x16x32_bf16 v[16:19], v[182:185], v[194:197], v[16:19]
	v_mfma_f32_16x16x32_bf16 v[24:27], v[182:185], v[198:201], v[24:27]
	v_mfma_f32_16x16x32_bf16 v[12:15], v[182:185], v[202:205], v[12:15]
	v_mfma_f32_16x16x32_bf16 v[4:7], v[186:189], v[190:193], v[4:7]
	v_mfma_f32_16x16x32_bf16 v[0:3], v[186:189], v[194:197], v[0:3]
	v_mfma_f32_16x16x32_bf16 v[20:23], v[186:189], v[198:201], v[20:23]
	v_mfma_f32_16x16x32_bf16 v[8:11], v[186:189], v[202:205], v[8:11]
	ds_read_b128 v[172:175], v155 offset:8192
	ds_read_b128 v[176:179], v155 offset:10240
	ds_read_b128 v[182:185], v155 offset:12288
	ds_read_b128 v[186:189], v155 offset:14336
	s_waitcnt lgkmcnt(4)
	v_mfma_f32_16x16x32_bf16 v[124:127], v[156:159], v[206:209], v[124:127]
	v_mfma_f32_16x16x32_bf16 v[116:119], v[156:159], v[210:213], v[116:119]
	v_mfma_f32_16x16x32_bf16 v[120:123], v[156:159], v[214:217], v[120:123]
	v_mfma_f32_16x16x32_bf16 v[112:115], v[156:159], v[218:221], v[112:115]
	v_mfma_f32_16x16x32_bf16 v[108:111], v[160:163], v[206:209], v[108:111]
	v_mfma_f32_16x16x32_bf16 v[100:103], v[160:163], v[210:213], v[100:103]
	v_mfma_f32_16x16x32_bf16 v[104:107], v[160:163], v[214:217], v[104:107]
	v_mfma_f32_16x16x32_bf16 v[96:99], v[160:163], v[218:221], v[96:99]
	v_mfma_f32_16x16x32_bf16 v[92:95], v[164:167], v[206:209], v[92:95]
	v_mfma_f32_16x16x32_bf16 v[84:87], v[164:167], v[210:213], v[84:87]
	v_mfma_f32_16x16x32_bf16 v[88:91], v[164:167], v[214:217], v[88:91]
	v_mfma_f32_16x16x32_bf16 v[80:83], v[164:167], v[218:221], v[80:83]
	v_mfma_f32_16x16x32_bf16 v[76:79], v[168:171], v[206:209], v[76:79]
	v_mfma_f32_16x16x32_bf16 v[68:71], v[168:171], v[210:213], v[68:71]
	v_mfma_f32_16x16x32_bf16 v[72:75], v[168:171], v[214:217], v[72:75]
	v_mfma_f32_16x16x32_bf16 v[64:67], v[168:171], v[218:221], v[64:67]
	s_add_u32 s44, s44, 0x80
	s_addc_u32 s45, s45, 0
	s_add_i32 s43, s43, 1
	s_cmp_lt_u32 s43, 15
	s_cbranch_scc0 .Lg10_last
	s_waitcnt lgkmcnt(0)
	s_waitcnt vmcnt(0)
	s_barrier
	s_xor_b32 s57, s57, 0x10000
	ds_read_b128 v[156:159], v223
	ds_read_b128 v[160:163], v223 offset:2048
	ds_read_b128 v[164:167], v223 offset:4096
	ds_read_b128 v[168:171], v223 offset:6144
	ds_read_b128 v[190:193], v225 offset:32768
	ds_read_b128 v[194:197], v225 offset:34816
	ds_read_b128 v[198:201], v225 offset:36864
	ds_read_b128 v[202:205], v225 offset:38912
	v_mfma_f32_16x16x32_bf16 v[60:63], v[172:175], v[206:209], v[60:63]
	v_mfma_f32_16x16x32_bf16 v[52:55], v[172:175], v[210:213], v[52:55]
	s_mov_b32 m0, s57
	s_add_u32 s46, s44, s14
	s_addc_u32 s47, s45, s15
	global_load_lds_dwordx4 v144, s[46:47]
	v_mfma_f32_16x16x32_bf16 v[56:59], v[172:175], v[214:217], v[56:59]
	v_mfma_f32_16x16x32_bf16 v[48:51], v[172:175], v[218:221], v[48:51]
	s_add_u32 m0, s57, 0x2000
	s_add_u32 s46, s44, s16
	s_addc_u32 s47, s45, s17
	global_load_lds_dwordx4 v144, s[46:47]
	v_mfma_f32_16x16x32_bf16 v[44:47], v[176:179], v[206:209], v[44:47]
	v_mfma_f32_16x16x32_bf16 v[36:39], v[176:179], v[210:213], v[36:39]
	s_add_u32 m0, s57, 0x4000
	s_add_u32 s46, s44, s18
	s_addc_u32 s47, s45, s19
	global_load_lds_dwordx4 v144, s[46:47]
	v_mfma_f32_16x16x32_bf16 v[40:43], v[176:179], v[214:217], v[40:43]
	v_mfma_f32_16x16x32_bf16 v[32:35], v[176:179], v[218:221], v[32:35]
	s_add_u32 m0, s57, 0x6000
	s_add_u32 s46, s44, s22
	s_addc_u32 s47, s45, s23
	global_load_lds_dwordx4 v144, s[46:47]
	v_mfma_f32_16x16x32_bf16 v[28:31], v[182:185], v[206:209], v[28:31]
	v_mfma_f32_16x16x32_bf16 v[16:19], v[182:185], v[210:213], v[16:19]
	s_add_u32 m0, s57, 0x8000
	s_add_u32 s46, s44, s30
	s_addc_u32 s47, s45, s31
	global_load_lds_dwordx4 v145, s[46:47]
	v_mfma_f32_16x16x32_bf16 v[24:27], v[182:185], v[214:217], v[24:27]
	v_mfma_f32_16x16x32_bf16 v[12:15], v[182:185], v[218:221], v[12:15]
	s_add_u32 m0, s57, 0xa000
	s_add_u32 s46, s44, s36
	s_addc_u32 s47, s45, s37
	global_load_lds_dwordx4 v145, s[46:47]
	v_mfma_f32_16x16x32_bf16 v[4:7], v[186:189], v[206:209], v[4:7]
	v_mfma_f32_16x16x32_bf16 v[0:3], v[186:189], v[210:213], v[0:3]
	s_add_u32 m0, s57, 0xc000
	s_add_u32 s46, s44, s38
	s_addc_u32 s47, s45, s39
	global_load_lds_dwordx4 v145, s[46:47]
	v_mfma_f32_16x16x32_bf16 v[20:23], v[186:189], v[214:217], v[20:23]
	v_mfma_f32_16x16x32_bf16 v[8:11], v[186:189], v[218:221], v[8:11]
	s_add_u32 m0, s57, 0xe000
	s_add_u32 s46, s44, s40
	s_addc_u32 s47, s45, s41
	global_load_lds_dwordx4 v145, s[46:47]
	ds_read_b128 v[172:175], v223 offset:8192
	ds_read_b128 v[176:179], v223 offset:10240
	ds_read_b128 v[182:185], v223 offset:12288
	ds_read_b128 v[186:189], v223 offset:14336
	s_waitcnt lgkmcnt(4)
	v_mfma_f32_16x16x32_bf16 v[124:127], v[156:159], v[190:193], v[124:127]
	v_mfma_f32_16x16x32_bf16 v[116:119], v[156:159], v[194:197], v[116:119]
	v_mfma_f32_16x16x32_bf16 v[120:123], v[156:159], v[198:201], v[120:123]
	v_mfma_f32_16x16x32_bf16 v[112:115], v[156:159], v[202:205], v[112:115]
	v_mfma_f32_16x16x32_bf16 v[108:111], v[160:163], v[190:193], v[108:111]
	v_mfma_f32_16x16x32_bf16 v[100:103], v[160:163], v[194:197], v[100:103]
	v_mfma_f32_16x16x32_bf16 v[104:107], v[160:163], v[198:201], v[104:107]
	v_mfma_f32_16x16x32_bf16 v[96:99], v[160:163], v[202:205], v[96:99]
	v_mfma_f32_16x16x32_bf16 v[92:95], v[164:167], v[190:193], v[92:95]
	v_mfma_f32_16x16x32_bf16 v[84:87], v[164:167], v[194:197], v[84:87]
	v_mfma_f32_16x16x32_bf16 v[88:91], v[164:167], v[198:201], v[88:91]
	v_mfma_f32_16x16x32_bf16 v[80:83], v[164:167], v[202:205], v[80:83]
	v_mfma_f32_16x16x32_bf16 v[76:79], v[168:171], v[190:193], v[76:79]
	v_mfma_f32_16x16x32_bf16 v[68:71], v[168:171], v[194:197], v[68:71]
	v_mfma_f32_16x16x32_bf16 v[72:75], v[168:171], v[198:201], v[72:75]
	v_mfma_f32_16x16x32_bf16 v[64:67], v[168:171], v[202:205], v[64:67]
	ds_read_b128 v[156:159], v224
	ds_read_b128 v[160:163], v224 offset:2048
	ds_read_b128 v[164:167], v224 offset:4096
	ds_read_b128 v[168:171], v224 offset:6144
	ds_read_b128 v[206:209], v226 offset:32768
	ds_read_b128 v[210:213], v226 offset:34816
	ds_read_b128 v[214:217], v226 offset:36864
	ds_read_b128 v[218:221], v226 offset:38912
	s_waitcnt lgkmcnt(8)
	v_mfma_f32_16x16x32_bf16 v[60:63], v[172:175], v[190:193], v[60:63]
	v_mfma_f32_16x16x32_bf16 v[52:55], v[172:175], v[194:197], v[52:55]
	v_mfma_f32_16x16x32_bf16 v[56:59], v[172:175], v[198:201], v[56:59]
	v_mfma_f32_16x16x32_bf16 v[48:51], v[172:175], v[202:205], v[48:51]
	v_mfma_f32_16x16x32_bf16 v[44:47], v[176:179], v[190:193], v[44:47]
	v_mfma_f32_16x16x32_bf16 v[36:39], v[176:179], v[194:197], v[36:39]
	v_mfma_f32_16x16x32_bf16 v[40:43], v[176:179], v[198:201], v[40:43]
	v_mfma_f32_16x16x32_bf16 v[32:35], v[176:179], v[202:205], v[32:35]
	v_mfma_f32_16x16x32_bf16 v[28:31], v[182:185], v[190:193], v[28:31]
	v_mfma_f32_16x16x32_bf16 v[16:19], v[182:185], v[194:197], v[16:19]
	v_mfma_f32_16x16x32_bf16 v[24:27], v[182:185], v[198:201], v[24:27]
	v_mfma_f32_16x16x32_bf16 v[12:15], v[182:185], v[202:205], v[12:15]
	v_mfma_f32_16x16x32_bf16 v[4:7], v[186:189], v[190:193], v[4:7]
	v_mfma_f32_16x16x32_bf16 v[0:3], v[186:189], v[194:197], v[0:3]
	v_mfma_f32_16x16x32_bf16 v[20:23], v[186:189], v[198:201], v[20:23]
	v_mfma_f32_16x16x32_bf16 v[8:11], v[186:189], v[202:205], v[8:11]
	ds_read_b128 v[172:175], v224 offset:8192
	ds_read_b128 v[176:179], v224 offset:10240
	ds_read_b128 v[182:185], v224 offset:12288
	ds_read_b128 v[186:189], v224 offset:14336
	s_waitcnt lgkmcnt(4)
	v_mfma_f32_16x16x32_bf16 v[124:127], v[156:159], v[206:209], v[124:127]
	v_mfma_f32_16x16x32_bf16 v[116:119], v[156:159], v[210:213], v[116:119]
	v_mfma_f32_16x16x32_bf16 v[120:123], v[156:159], v[214:217], v[120:123]
	v_mfma_f32_16x16x32_bf16 v[112:115], v[156:159], v[218:221], v[112:115]
	v_mfma_f32_16x16x32_bf16 v[108:111], v[160:163], v[206:209], v[108:111]
	v_mfma_f32_16x16x32_bf16 v[100:103], v[160:163], v[210:213], v[100:103]
	v_mfma_f32_16x16x32_bf16 v[104:107], v[160:163], v[214:217], v[104:107]
	v_mfma_f32_16x16x32_bf16 v[96:99], v[160:163], v[218:221], v[96:99]
	v_mfma_f32_16x16x32_bf16 v[92:95], v[164:167], v[206:209], v[92:95]
	v_mfma_f32_16x16x32_bf16 v[84:87], v[164:167], v[210:213], v[84:87]
	v_mfma_f32_16x16x32_bf16 v[88:91], v[164:167], v[214:217], v[88:91]
	v_mfma_f32_16x16x32_bf16 v[80:83], v[164:167], v[218:221], v[80:83]
	v_mfma_f32_16x16x32_bf16 v[76:79], v[168:171], v[206:209], v[76:79]
	v_mfma_f32_16x16x32_bf16 v[68:71], v[168:171], v[210:213], v[68:71]
	v_mfma_f32_16x16x32_bf16 v[72:75], v[168:171], v[214:217], v[72:75]
	v_mfma_f32_16x16x32_bf16 v[64:67], v[168:171], v[218:221], v[64:67]
	s_add_u32 s44, s44, 0x80
	s_addc_u32 s45, s45, 0
	s_add_i32 s43, s43, 1
	s_branch .Lg10_top
.Lg10_last:
	s_waitcnt lgkmcnt(0)
	s_waitcnt vmcnt(0)
	s_barrier
	s_xor_b32 s57, s57, 0x10000
	ds_read_b128 v[156:159], v223
	ds_read_b128 v[160:163], v223 offset:2048
	ds_read_b128 v[164:167], v223 offset:4096
	ds_read_b128 v[168:171], v223 offset:6144
	ds_read_b128 v[190:193], v225 offset:32768
	ds_read_b128 v[194:197], v225 offset:34816
	ds_read_b128 v[198:201], v225 offset:36864
	ds_read_b128 v[202:205], v225 offset:38912
	v_mfma_f32_16x16x32_bf16 v[60:63], v[172:175], v[206:209], v[60:63]
	v_mfma_f32_16x16x32_bf16 v[52:55], v[172:175], v[210:213], v[52:55]
	v_mfma_f32_16x16x32_bf16 v[56:59], v[172:175], v[214:217], v[56:59]
	v_mfma_f32_16x16x32_bf16 v[48:51], v[172:175], v[218:221], v[48:51]
	v_mfma_f32_16x16x32_bf16 v[44:47], v[176:179], v[206:209], v[44:47]
	v_mfma_f32_16x16x32_bf16 v[36:39], v[176:179], v[210:213], v[36:39]
	v_mfma_f32_16x16x32_bf16 v[40:43], v[176:179], v[214:217], v[40:43]
	v_mfma_f32_16x16x32_bf16 v[32:35], v[176:179], v[218:221], v[32:35]
	v_mfma_f32_16x16x32_bf16 v[28:31], v[182:185], v[206:209], v[28:31]
	v_mfma_f32_16x16x32_bf16 v[16:19], v[182:185], v[210:213], v[16:19]
	v_mfma_f32_16x16x32_bf16 v[24:27], v[182:185], v[214:217], v[24:27]
	v_mfma_f32_16x16x32_bf16 v[12:15], v[182:185], v[218:221], v[12:15]
	v_mfma_f32_16x16x32_bf16 v[4:7], v[186:189], v[206:209], v[4:7]
	v_mfma_f32_16x16x32_bf16 v[0:3], v[186:189], v[210:213], v[0:3]
	v_mfma_f32_16x16x32_bf16 v[20:23], v[186:189], v[214:217], v[20:23]
	v_mfma_f32_16x16x32_bf16 v[8:11], v[186:189], v[218:221], v[8:11]
	ds_read_b128 v[172:175], v223 offset:8192
	ds_read_b128 v[176:179], v223 offset:10240
	ds_read_b128 v[182:185], v223 offset:12288
	ds_read_b128 v[186:189], v223 offset:14336
	s_waitcnt lgkmcnt(4)
	v_mfma_f32_16x16x32_bf16 v[124:127], v[156:159], v[190:193], v[124:127]
	v_mfma_f32_16x16x32_bf16 v[116:119], v[156:159], v[194:197], v[116:119]
	v_mfma_f32_16x16x32_bf16 v[120:123], v[156:159], v[198:201], v[120:123]
	v_mfma_f32_16x16x32_bf16 v[112:115], v[156:159], v[202:205], v[112:115]
	v_mfma_f32_16x16x32_bf16 v[108:111], v[160:163], v[190:193], v[108:111]
	v_mfma_f32_16x16x32_bf16 v[100:103], v[160:163], v[194:197], v[100:103]
	v_mfma_f32_16x16x32_bf16 v[104:107], v[160:163], v[198:201], v[104:107]
	v_mfma_f32_16x16x32_bf16 v[96:99], v[160:163], v[202:205], v[96:99]
	v_mfma_f32_16x16x32_bf16 v[92:95], v[164:167], v[190:193], v[92:95]
	v_mfma_f32_16x16x32_bf16 v[84:87], v[164:167], v[194:197], v[84:87]
	v_mfma_f32_16x16x32_bf16 v[88:91], v[164:167], v[198:201], v[88:91]
	v_mfma_f32_16x16x32_bf16 v[80:83], v[164:167], v[202:205], v[80:83]
	v_mfma_f32_16x16x32_bf16 v[76:79], v[168:171], v[190:193], v[76:79]
	v_mfma_f32_16x16x32_bf16 v[68:71], v[168:171], v[194:197], v[68:71]
	v_mfma_f32_16x16x32_bf16 v[72:75], v[168:171], v[198:201], v[72:75]
	v_mfma_f32_16x16x32_bf16 v[64:67], v[168:171], v[202:205], v[64:67]
	ds_read_b128 v[156:159], v224
	ds_read_b128 v[160:163], v224 offset:2048
	ds_read_b128 v[164:167], v224 offset:4096
	ds_read_b128 v[168:171], v224 offset:6144
	ds_read_b128 v[206:209], v226 offset:32768
	ds_read_b128 v[210:213], v226 offset:34816
	ds_read_b128 v[214:217], v226 offset:36864
	ds_read_b128 v[218:221], v226 offset:38912
	s_waitcnt lgkmcnt(8)
	v_mfma_f32_16x16x32_bf16 v[60:63], v[172:175], v[190:193], v[60:63]
	v_mfma_f32_16x16x32_bf16 v[52:55], v[172:175], v[194:197], v[52:55]
	v_mfma_f32_16x16x32_bf16 v[56:59], v[172:175], v[198:201], v[56:59]
	v_mfma_f32_16x16x32_bf16 v[48:51], v[172:175], v[202:205], v[48:51]
	v_mfma_f32_16x16x32_bf16 v[44:47], v[176:179], v[190:193], v[44:47]
	v_mfma_f32_16x16x32_bf16 v[36:39], v[176:179], v[194:197], v[36:39]
	v_mfma_f32_16x16x32_bf16 v[40:43], v[176:179], v[198:201], v[40:43]
	v_mfma_f32_16x16x32_bf16 v[32:35], v[176:179], v[202:205], v[32:35]
	v_mfma_f32_16x16x32_bf16 v[28:31], v[182:185], v[190:193], v[28:31]
	v_mfma_f32_16x16x32_bf16 v[16:19], v[182:185], v[194:197], v[16:19]
	v_mfma_f32_16x16x32_bf16 v[24:27], v[182:185], v[198:201], v[24:27]
	v_mfma_f32_16x16x32_bf16 v[12:15], v[182:185], v[202:205], v[12:15]
	v_mfma_f32_16x16x32_bf16 v[4:7], v[186:189], v[190:193], v[4:7]
	v_mfma_f32_16x16x32_bf16 v[0:3], v[186:189], v[194:197], v[0:3]
	v_mfma_f32_16x16x32_bf16 v[20:23], v[186:189], v[198:201], v[20:23]
	v_mfma_f32_16x16x32_bf16 v[8:11], v[186:189], v[202:205], v[8:11]
	ds_read_b128 v[172:175], v224 offset:8192
	ds_read_b128 v[176:179], v224 offset:10240
	ds_read_b128 v[182:185], v224 offset:12288
	ds_read_b128 v[186:189], v224 offset:14336
	s_waitcnt lgkmcnt(4)
	v_mfma_f32_16x16x32_bf16 v[124:127], v[156:159], v[206:209], v[124:127]
	v_mfma_f32_16x16x32_bf16 v[116:119], v[156:159], v[210:213], v[116:119]
	v_mfma_f32_16x16x32_bf16 v[120:123], v[156:159], v[214:217], v[120:123]
	v_mfma_f32_16x16x32_bf16 v[112:115], v[156:159], v[218:221], v[112:115]
	v_mfma_f32_16x16x32_bf16 v[108:111], v[160:163], v[206:209], v[108:111]
	v_mfma_f32_16x16x32_bf16 v[100:103], v[160:163], v[210:213], v[100:103]
	v_mfma_f32_16x16x32_bf16 v[104:107], v[160:163], v[214:217], v[104:107]
	v_mfma_f32_16x16x32_bf16 v[96:99], v[160:163], v[218:221], v[96:99]
	v_mfma_f32_16x16x32_bf16 v[92:95], v[164:167], v[206:209], v[92:95]
	v_mfma_f32_16x16x32_bf16 v[84:87], v[164:167], v[210:213], v[84:87]
	v_mfma_f32_16x16x32_bf16 v[88:91], v[164:167], v[214:217], v[88:91]
	v_mfma_f32_16x16x32_bf16 v[80:83], v[164:167], v[218:221], v[80:83]
	v_mfma_f32_16x16x32_bf16 v[76:79], v[168:171], v[206:209], v[76:79]
	v_mfma_f32_16x16x32_bf16 v[68:71], v[168:171], v[210:213], v[68:71]
	v_mfma_f32_16x16x32_bf16 v[72:75], v[168:171], v[214:217], v[72:75]
	v_mfma_f32_16x16x32_bf16 v[64:67], v[168:171], v[218:221], v[64:67]
	s_add_u32 s44, s44, 0x80
	s_addc_u32 s45, s45, 0
	s_add_i32 s43, s43, 1
	s_waitcnt lgkmcnt(0)
	s_waitcnt vmcnt(0)
	s_barrier
	v_mfma_f32_16x16x32_bf16 v[60:63], v[172:175], v[206:209], v[60:63]
	v_mfma_f32_16x16x32_bf16 v[52:55], v[172:175], v[210:213], v[52:55]
	v_mfma_f32_16x16x32_bf16 v[56:59], v[172:175], v[214:217], v[56:59]
	v_mfma_f32_16x16x32_bf16 v[48:51], v[172:175], v[218:221], v[48:51]
	v_mfma_f32_16x16x32_bf16 v[44:47], v[176:179], v[206:209], v[44:47]
	v_mfma_f32_16x16x32_bf16 v[36:39], v[176:179], v[210:213], v[36:39]
	v_mfma_f32_16x16x32_bf16 v[40:43], v[176:179], v[214:217], v[40:43]
	v_mfma_f32_16x16x32_bf16 v[32:35], v[176:179], v[218:221], v[32:35]
	v_mfma_f32_16x16x32_bf16 v[28:31], v[182:185], v[206:209], v[28:31]
	v_mfma_f32_16x16x32_bf16 v[16:19], v[182:185], v[210:213], v[16:19]
	v_mfma_f32_16x16x32_bf16 v[24:27], v[182:185], v[214:217], v[24:27]
	v_mfma_f32_16x16x32_bf16 v[12:15], v[182:185], v[218:221], v[12:15]
	v_mfma_f32_16x16x32_bf16 v[4:7], v[186:189], v[206:209], v[4:7]
	v_mfma_f32_16x16x32_bf16 v[0:3], v[186:189], v[210:213], v[0:3]
	v_mfma_f32_16x16x32_bf16 v[20:23], v[186:189], v[214:217], v[20:23]
	v_mfma_f32_16x16x32_bf16 v[8:11], v[186:189], v[218:221], v[8:11]
	s_nop 7
	s_nop 7
	s_sub_u32 s44, s44, s34
	s_subb_u32 s45, s45, s35
	s_mov_b32 s57, 0x80000
	s_mov_b32 s58, 0x80000
	s_mov_b64 s[46:47], 0
	s_mov_b64 vcc, exec
	s_branch .LBB0_1494

.LBB0_1636:
	s_ashr_i32 s20, s44, 2
	v_mov_b32_e32 v6, v181
	s_and_b32 s4, s44, 7
	s_and_b32 s39, s20, -8
	s_or_b32 s30, s39, s4
	v_lshrrev_b32_e32 v7, 4, v6
	v_lshlrev_b32_e32 v1, 6, v6
	v_xor_b32_e32 v0, v7, v6
	v_and_b32_e32 v8, 0x3c0, v1
	v_lshlrev_b32_e32 v1, 8, v6
	s_ashr_i32 s31, s30, 31
	v_lshlrev_b32_e32 v0, 3, v0
	v_and_b32_e32 v1, 0xfffff800, v1
	s_and_b32 s38, s43, 7
	s_bfe_u32 s4, s44, 0x20003
	s_lshl_b64 s[20:21], s[30:31], 20
	v_and_or_b32 v0, v0, 56, v1
	s_add_u32 s20, s3, s20
	v_ashrrev_i32_e32 v1, 31, v0
	s_addc_u32 s21, s40, s21
	v_lshlrev_b64 v[0:1], 1, v[0:1]
	v_lshl_add_u32 v134, v6, 4, 0
	v_lshl_add_u64 v[2:3], s[20:21], 0, v[0:1]
	v_readfirstlane_b32 s20, v134
	v_add_u32_e32 v9, 0x2000, v134
	s_mov_b32 m0, s20
	v_readfirstlane_b32 s20, v9
	v_add_u32_e32 v9, 0x4000, v134
	s_waitcnt vmcnt(63) expcnt(7) lgkmcnt(15)
	s_barrier
	global_load_lds_dwordx4 v[2:3], off
	v_lshl_add_u64 v[4:5], v[2:3], 0, s[6:7]
	s_mov_b32 m0, s20
	v_readfirstlane_b32 s20, v9
	global_load_lds_dwordx4 v[4:5], off
	v_lshl_add_u64 v[4:5], v[2:3], 0, s[8:9]
	s_mov_b32 m0, s20
	s_lshl_b32 s31, s4, 20
	global_load_lds_dwordx4 v[4:5], off
	v_add_u32_e32 v4, 0x6000, v134
	s_add_u32 s36, s41, s31
	v_readfirstlane_b32 s20, v4
	v_add_u32_e32 v4, 0x8000, v134
	s_addc_u32 s37, s42, 0
	v_lshl_add_u64 v[2:3], v[2:3], 0, s[10:11]
	s_mov_b32 m0, s20
	v_readfirstlane_b32 s20, v4
	v_add_u32_e32 v9, 0xa000, v134
	global_load_lds_dwordx4 v[2:3], off
	v_lshl_add_u64 v[2:3], s[36:37], 0, v[0:1]
	s_mov_b32 m0, s20
	v_readfirstlane_b32 s20, v9
	v_add_u32_e32 v9, 0xc000, v134
	global_load_lds_dwordx4 v[2:3], off
	v_lshl_add_u64 v[4:5], v[2:3], 0, s[6:7]
	s_mov_b32 m0, s20
	v_readfirstlane_b32 s20, v9
	global_load_lds_dwordx4 v[4:5], off
	v_lshl_add_u64 v[4:5], v[2:3], 0, s[8:9]
	s_mov_b32 m0, s20
	v_lshl_add_u64 v[2:3], v[2:3], 0, s[10:11]
	global_load_lds_dwordx4 v[4:5], off
	v_add_u32_e32 v4, 0xe000, v134
	v_mov_b32_e32 v36, 0
	v_readfirstlane_b32 s20, v4
	s_mov_b32 m0, s20
	v_ashrrev_i32_e32 v4, 6, v6
	global_load_lds_dwordx4 v[2:3], off
	s_or_b32 s20, s39, s38
	v_lshrrev_b32_e32 v5, 30, v4
	s_ashr_i32 s21, s20, 31
	v_add_u32_e32 v5, v4, v5
	s_lshl_b64 s[20:21], s[20:21], 20
	v_bfe_u32 v2, v6, 4, 2
	v_bfe_u32 v3, v6, 1, 3
	v_and_b32_e32 v6, 0x7fffc, v5
	s_add_u32 s20, s34, s20
	v_sub_u32_e32 v4, v4, v6
	s_addc_u32 s21, s35, s21
	v_lshlrev_b32_e32 v136, 13, v4
	v_bitop3_b32 v4, v7, v3, 3 bitop3:0x6c
	v_bitop3_b32 v2, v2, v3, 4 bitop3:0x36
	v_lshl_add_u64 v[130:131], s[20:21], 0, v[0:1]
	s_add_u32 s20, s34, s31
	v_lshlrev_b32_e32 v5, 12, v5
	v_lshlrev_b32_e32 v4, 3, v4
	v_lshlrev_b32_e32 v2, 3, v2
	s_addc_u32 s21, s35, 0
	v_and_b32_e32 v135, 0xffffc000, v5
	v_lshl_add_u64 v[132:133], s[20:21], 0, v[0:1]
	s_mov_b64 s[36:37], 0
	v_lshlrev_b32_e32 v137, 1, v8
	v_lshlrev_b32_e32 v138, 1, v4
	v_lshlrev_b32_e32 v139, 1, v2
	s_mov_b32 s45, 0
	s_mov_b32 s31, 0
	v_mov_b32_e32 v37, v36
	v_mov_b32_e32 v38, v36
	v_mov_b32_e32 v39, v36
	v_mov_b32_e32 v40, v36
	v_mov_b32_e32 v41, v36
	v_mov_b32_e32 v42, v36
	v_mov_b32_e32 v43, v36
	v_mov_b32_e32 v0, v36
	v_mov_b32_e32 v1, v36
	v_mov_b32_e32 v2, v36
	v_mov_b32_e32 v3, v36
	v_mov_b32_e32 v4, v36
	v_mov_b32_e32 v5, v36
	v_mov_b32_e32 v6, v36
	v_mov_b32_e32 v7, v36
	v_mov_b32_e32 v8, v36
	v_mov_b32_e32 v9, v36
	v_mov_b32_e32 v10, v36
	v_mov_b32_e32 v11, v36
	v_mov_b32_e32 v12, v36
	v_mov_b32_e32 v13, v36
	v_mov_b32_e32 v14, v36
	v_mov_b32_e32 v15, v36
	v_mov_b32_e32 v16, v36
	v_mov_b32_e32 v17, v36
	v_mov_b32_e32 v18, v36
	v_mov_b32_e32 v19, v36
	v_mov_b32_e32 v20, v36
	v_mov_b32_e32 v21, v36
	v_mov_b32_e32 v22, v36
	v_mov_b32_e32 v23, v36
	v_mov_b32_e32 v24, v36
	v_mov_b32_e32 v25, v36
	v_mov_b32_e32 v26, v36
	v_mov_b32_e32 v27, v36
	v_mov_b32_e32 v28, v36
	v_mov_b32_e32 v29, v36
	v_mov_b32_e32 v30, v36
	v_mov_b32_e32 v31, v36
	v_mov_b32_e32 v32, v36
	v_mov_b32_e32 v33, v36
	v_mov_b32_e32 v34, v36
	v_mov_b32_e32 v35, v36
	v_mov_b32_e32 v44, v36
	v_mov_b32_e32 v45, v36
	v_mov_b32_e32 v46, v36
	v_mov_b32_e32 v47, v36
	v_mov_b32_e32 v48, v36
	v_mov_b32_e32 v49, v36
	v_mov_b32_e32 v50, v36
	v_mov_b32_e32 v51, v36
	v_mov_b32_e32 v52, v36
	v_mov_b32_e32 v53, v36
	v_mov_b32_e32 v54, v36
	v_mov_b32_e32 v55, v36
	v_mov_b32_e32 v56, v36
	v_mov_b32_e32 v57, v36
	v_mov_b32_e32 v58, v36
	v_mov_b32_e32 v59, v36
	v_mov_b32_e32 v60, v36
	v_mov_b32_e32 v61, v36
	v_mov_b32_e32 v62, v36
	v_mov_b32_e32 v63, v36
	v_mov_b32_e32 v64, v36
	v_mov_b32_e32 v65, v36
	v_mov_b32_e32 v66, v36
	v_mov_b32_e32 v67, v36
	v_mov_b32_e32 v68, v36
	v_mov_b32_e32 v69, v36
	v_mov_b32_e32 v70, v36
	v_mov_b32_e32 v71, v36
	v_mov_b32_e32 v72, v36
	v_mov_b32_e32 v73, v36
	v_mov_b32_e32 v74, v36
	v_mov_b32_e32 v75, v36
	v_mov_b32_e32 v76, v36
	v_mov_b32_e32 v77, v36
	v_mov_b32_e32 v78, v36
	v_mov_b32_e32 v79, v36
	v_mov_b32_e32 v80, v36
	v_mov_b32_e32 v81, v36
	v_mov_b32_e32 v82, v36
	v_mov_b32_e32 v83, v36
	v_mov_b32_e32 v84, v36
	v_mov_b32_e32 v85, v36
	v_mov_b32_e32 v86, v36
	v_mov_b32_e32 v87, v36
	v_mov_b32_e32 v88, v36
	v_mov_b32_e32 v89, v36
	v_mov_b32_e32 v90, v36
	v_mov_b32_e32 v91, v36
	v_mov_b32_e32 v92, v36
	v_mov_b32_e32 v93, v36
	v_mov_b32_e32 v94, v36
	v_mov_b32_e32 v95, v36
	v_mov_b32_e32 v96, v36
	v_mov_b32_e32 v97, v36
	v_mov_b32_e32 v98, v36
	v_mov_b32_e32 v99, v36
	v_mov_b32_e32 v100, v36
	v_mov_b32_e32 v101, v36
	v_mov_b32_e32 v102, v36
	v_mov_b32_e32 v103, v36
	v_mov_b32_e32 v104, v36
	v_mov_b32_e32 v105, v36
	v_mov_b32_e32 v106, v36
	v_mov_b32_e32 v107, v36
	v_mov_b32_e32 v108, v36
	v_mov_b32_e32 v109, v36
	v_mov_b32_e32 v110, v36
	v_mov_b32_e32 v111, v36
	v_mov_b32_e32 v112, v36
	v_mov_b32_e32 v113, v36
	v_mov_b32_e32 v114, v36
	v_mov_b32_e32 v115, v36
	v_mov_b32_e32 v116, v36
	v_mov_b32_e32 v117, v36
	v_mov_b32_e32 v118, v36
	v_mov_b32_e32 v119, v36
	v_mov_b32_e32 v120, v36
	v_mov_b32_e32 v121, v36
	v_mov_b32_e32 v122, v36
	v_mov_b32_e32 v123, v36
	v_mov_b32_e32 v124, v36
	v_mov_b32_e32 v125, v36
	v_mov_b32_e32 v126, v36
	v_mov_b32_e32 v127, v36
	s_waitcnt vmcnt(0) lgkmcnt(0)
	s_barrier
	v_add3_u32 v141, v135, v137, v138
	v_add3_u32 v210, v136, v137, v138
	v_add3_u32 v180, v135, v137, v139
	v_add3_u32 v211, v136, v137, v139
	v_xor_b32_e32 v212, 0x10000, v141
	v_xor_b32_e32 v213, 0x10000, v180
	v_xor_b32_e32 v214, 0x10000, v210
	v_xor_b32_e32 v215, 0x10000, v211
	v_readfirstlane_b32 s45, v134
	ds_read_b128 v[142:145], v141
	ds_read_b128 v[146:149], v141 offset:2048
	ds_read_b128 v[150:153], v141 offset:4096
	ds_read_b128 v[154:157], v141 offset:6144
	ds_read_b128 v[174:177], v210 offset:32768
	ds_read_b128 v[182:185], v210 offset:34816
	ds_read_b128 v[186:189], v210 offset:36864
	ds_read_b128 v[190:193], v210 offset:38912
	s_mov_b32 s31, 0
	s_mov_b64 s[36:37], s[34:35]
	v_subrev_u32_e32 v178, s34, v130
	v_subrev_u32_e32 v179, s34, v132
	s_add_u32 s45, s45, 0x10000
	s_mov_b32 m0, s45
	s_add_u32 s38, s36, s12
	s_addc_u32 s39, s37, s13
	global_load_lds_dwordx4 v178, s[38:39]
	s_add_u32 m0, s45, 0x2000
	s_add_u32 s38, s36, s14
	s_addc_u32 s39, s37, s15
	global_load_lds_dwordx4 v178, s[38:39]
	s_add_u32 m0, s45, 0x4000
	s_add_u32 s38, s36, s16
	s_addc_u32 s39, s37, s17
	global_load_lds_dwordx4 v178, s[38:39]
	s_add_u32 m0, s45, 0x6000
	s_add_u32 s38, s36, s18
	s_addc_u32 s39, s37, s19
	global_load_lds_dwordx4 v178, s[38:39]
	s_add_u32 m0, s45, 0x8000
	s_add_u32 s38, s36, s22
	s_addc_u32 s39, s37, s23
	global_load_lds_dwordx4 v179, s[38:39]
	s_add_u32 m0, s45, 0xa000
	s_add_u32 s38, s36, s24
	s_addc_u32 s39, s37, s25
	global_load_lds_dwordx4 v179, s[38:39]
	s_add_u32 m0, s45, 0xc000
	s_add_u32 s38, s36, s26
	s_addc_u32 s39, s37, s27
	global_load_lds_dwordx4 v179, s[38:39]
	s_add_u32 m0, s45, 0xe000
	s_add_u32 s38, s36, s28
	s_addc_u32 s39, s37, s29
	global_load_lds_dwordx4 v179, s[38:39]
	s_branch .Lg11_entry
.Lg11_top:
	s_waitcnt lgkmcnt(0)
	s_waitcnt vmcnt(0)
	s_barrier
	s_xor_b32 s45, s45, 0x10000
	ds_read_b128 v[142:145], v141
	ds_read_b128 v[146:149], v141 offset:2048
	ds_read_b128 v[150:153], v141 offset:4096
	ds_read_b128 v[154:157], v141 offset:6144
	ds_read_b128 v[174:177], v210 offset:32768
	ds_read_b128 v[182:185], v210 offset:34816
	ds_read_b128 v[186:189], v210 offset:36864
	ds_read_b128 v[190:193], v210 offset:38912
	v_mfma_f32_16x16x32_bf16 v[60:63], v[158:161], v[194:197], v[60:63]
	v_mfma_f32_16x16x32_bf16 v[56:59], v[158:161], v[198:201], v[56:59]
	s_mov_b32 m0, s45
	s_add_u32 s38, s36, s12
	s_addc_u32 s39, s37, s13
	global_load_lds_dwordx4 v178, s[38:39]
	v_mfma_f32_16x16x32_bf16 v[52:55], v[158:161], v[202:205], v[52:55]
	v_mfma_f32_16x16x32_bf16 v[48:51], v[158:161], v[206:209], v[48:51]
	s_add_u32 m0, s45, 0x2000
	s_add_u32 s38, s36, s14
	s_addc_u32 s39, s37, s15
	global_load_lds_dwordx4 v178, s[38:39]
	v_mfma_f32_16x16x32_bf16 v[44:47], v[162:165], v[194:197], v[44:47]
	v_mfma_f32_16x16x32_bf16 v[32:35], v[162:165], v[198:201], v[32:35]
	s_add_u32 m0, s45, 0x4000
	s_add_u32 s38, s36, s16
	s_addc_u32 s39, s37, s17
	global_load_lds_dwordx4 v178, s[38:39]
	v_mfma_f32_16x16x32_bf16 v[28:31], v[162:165], v[202:205], v[28:31]
	v_mfma_f32_16x16x32_bf16 v[24:27], v[162:165], v[206:209], v[24:27]
	s_add_u32 m0, s45, 0x6000
	s_add_u32 s38, s36, s18
	s_addc_u32 s39, s37, s19
	global_load_lds_dwordx4 v178, s[38:39]
	v_mfma_f32_16x16x32_bf16 v[20:23], v[166:169], v[194:197], v[20:23]
	v_mfma_f32_16x16x32_bf16 v[16:19], v[166:169], v[198:201], v[16:19]
	s_add_u32 m0, s45, 0x8000
	s_add_u32 s38, s36, s22
	s_addc_u32 s39, s37, s23
	global_load_lds_dwordx4 v179, s[38:39]
	v_mfma_f32_16x16x32_bf16 v[12:15], v[166:169], v[202:205], v[12:15]
	v_mfma_f32_16x16x32_bf16 v[8:11], v[166:169], v[206:209], v[8:11]
	s_add_u32 m0, s45, 0xa000
	s_add_u32 s38, s36, s24
	s_addc_u32 s39, s37, s25
	global_load_lds_dwordx4 v179, s[38:39]
	v_mfma_f32_16x16x32_bf16 v[4:7], v[170:173], v[194:197], v[4:7]
	v_mfma_f32_16x16x32_bf16 v[0:3], v[170:173], v[198:201], v[0:3]
	s_add_u32 m0, s45, 0xc000
	s_add_u32 s38, s36, s26
	s_addc_u32 s39, s37, s27
	global_load_lds_dwordx4 v179, s[38:39]
	v_mfma_f32_16x16x32_bf16 v[40:43], v[170:173], v[202:205], v[40:43]
	v_mfma_f32_16x16x32_bf16 v[36:39], v[170:173], v[206:209], v[36:39]
	s_add_u32 m0, s45, 0xe000
	s_add_u32 s38, s36, s28
	s_addc_u32 s39, s37, s29
	global_load_lds_dwordx4 v179, s[38:39]
.Lg11_entry:
	ds_read_b128 v[158:161], v141 offset:8192
	ds_read_b128 v[162:165], v141 offset:10240
	ds_read_b128 v[166:169], v141 offset:12288
	ds_read_b128 v[170:173], v141 offset:14336
	s_waitcnt lgkmcnt(4)
	v_mfma_f32_16x16x32_bf16 v[124:127], v[142:145], v[174:177], v[124:127]
	v_mfma_f32_16x16x32_bf16 v[120:123], v[142:145], v[182:185], v[120:123]
	v_mfma_f32_16x16x32_bf16 v[116:119], v[142:145], v[186:189], v[116:119]
	v_mfma_f32_16x16x32_bf16 v[112:115], v[142:145], v[190:193], v[112:115]
	v_mfma_f32_16x16x32_bf16 v[108:111], v[146:149], v[174:177], v[108:111]
	v_mfma_f32_16x16x32_bf16 v[104:107], v[146:149], v[182:185], v[104:107]
	v_mfma_f32_16x16x32_bf16 v[100:103], v[146:149], v[186:189], v[100:103]
	v_mfma_f32_16x16x32_bf16 v[96:99], v[146:149], v[190:193], v[96:99]
	v_mfma_f32_16x16x32_bf16 v[92:95], v[150:153], v[174:177], v[92:95]
	v_mfma_f32_16x16x32_bf16 v[88:91], v[150:153], v[182:185], v[88:91]
	v_mfma_f32_16x16x32_bf16 v[84:87], v[150:153], v[186:189], v[84:87]
	v_mfma_f32_16x16x32_bf16 v[80:83], v[150:153], v[190:193], v[80:83]
	v_mfma_f32_16x16x32_bf16 v[76:79], v[154:157], v[174:177], v[76:79]
	v_mfma_f32_16x16x32_bf16 v[72:75], v[154:157], v[182:185], v[72:75]
	v_mfma_f32_16x16x32_bf16 v[68:71], v[154:157], v[186:189], v[68:71]
	v_mfma_f32_16x16x32_bf16 v[64:67], v[154:157], v[190:193], v[64:67]
	ds_read_b128 v[142:145], v180
	ds_read_b128 v[146:149], v180 offset:2048
	ds_read_b128 v[150:153], v180 offset:4096
	ds_read_b128 v[154:157], v180 offset:6144
	ds_read_b128 v[194:197], v211 offset:32768
	ds_read_b128 v[198:201], v211 offset:34816
	ds_read_b128 v[202:205], v211 offset:36864
	ds_read_b128 v[206:209], v211 offset:38912
	s_waitcnt lgkmcnt(8)
	v_mfma_f32_16x16x32_bf16 v[60:63], v[158:161], v[174:177], v[60:63]
	v_mfma_f32_16x16x32_bf16 v[56:59], v[158:161], v[182:185], v[56:59]
	v_mfma_f32_16x16x32_bf16 v[52:55], v[158:161], v[186:189], v[52:55]
	v_mfma_f32_16x16x32_bf16 v[48:51], v[158:161], v[190:193], v[48:51]
	v_mfma_f32_16x16x32_bf16 v[44:47], v[162:165], v[174:177], v[44:47]
	v_mfma_f32_16x16x32_bf16 v[32:35], v[162:165], v[182:185], v[32:35]
	v_mfma_f32_16x16x32_bf16 v[28:31], v[162:165], v[186:189], v[28:31]
	v_mfma_f32_16x16x32_bf16 v[24:27], v[162:165], v[190:193], v[24:27]
	v_mfma_f32_16x16x32_bf16 v[20:23], v[166:169], v[174:177], v[20:23]
	v_mfma_f32_16x16x32_bf16 v[16:19], v[166:169], v[182:185], v[16:19]
	v_mfma_f32_16x16x32_bf16 v[12:15], v[166:169], v[186:189], v[12:15]
	v_mfma_f32_16x16x32_bf16 v[8:11], v[166:169], v[190:193], v[8:11]
	v_mfma_f32_16x16x32_bf16 v[4:7], v[170:173], v[174:177], v[4:7]
	v_mfma_f32_16x16x32_bf16 v[0:3], v[170:173], v[182:185], v[0:3]
	v_mfma_f32_16x16x32_bf16 v[40:43], v[170:173], v[186:189], v[40:43]
	v_mfma_f32_16x16x32_bf16 v[36:39], v[170:173], v[190:193], v[36:39]
	ds_read_b128 v[158:161], v180 offset:8192
	ds_read_b128 v[162:165], v180 offset:10240
	ds_read_b128 v[166:169], v180 offset:12288
	ds_read_b128 v[170:173], v180 offset:14336
	s_waitcnt lgkmcnt(4)
	v_mfma_f32_16x16x32_bf16 v[124:127], v[142:145], v[194:197], v[124:127]
	v_mfma_f32_16x16x32_bf16 v[120:123], v[142:145], v[198:201], v[120:123]
	v_mfma_f32_16x16x32_bf16 v[116:119], v[142:145], v[202:205], v[116:119]
	v_mfma_f32_16x16x32_bf16 v[112:115], v[142:145], v[206:209], v[112:115]
	v_mfma_f32_16x16x32_bf16 v[108:111], v[146:149], v[194:197], v[108:111]
	v_mfma_f32_16x16x32_bf16 v[104:107], v[146:149], v[198:201], v[104:107]
	v_mfma_f32_16x16x32_bf16 v[100:103], v[146:149], v[202:205], v[100:103]
	v_mfma_f32_16x16x32_bf16 v[96:99], v[146:149], v[206:209], v[96:99]
	v_mfma_f32_16x16x32_bf16 v[92:95], v[150:153], v[194:197], v[92:95]
	v_mfma_f32_16x16x32_bf16 v[88:91], v[150:153], v[198:201], v[88:91]
	v_mfma_f32_16x16x32_bf16 v[84:87], v[150:153], v[202:205], v[84:87]
	v_mfma_f32_16x16x32_bf16 v[80:83], v[150:153], v[206:209], v[80:83]
	v_mfma_f32_16x16x32_bf16 v[76:79], v[154:157], v[194:197], v[76:79]
	v_mfma_f32_16x16x32_bf16 v[72:75], v[154:157], v[198:201], v[72:75]
	v_mfma_f32_16x16x32_bf16 v[68:71], v[154:157], v[202:205], v[68:71]
	v_mfma_f32_16x16x32_bf16 v[64:67], v[154:157], v[206:209], v[64:67]
	s_add_u32 s36, s36, 0x80
	s_addc_u32 s37, s37, 0
	s_add_i32 s31, s31, 1
	s_cmp_lt_u32 s31, 31
	s_cbranch_scc0 .Lg11_last
	s_waitcnt lgkmcnt(0)
	s_waitcnt vmcnt(0)
	s_barrier
	s_xor_b32 s45, s45, 0x10000
	ds_read_b128 v[142:145], v212
	ds_read_b128 v[146:149], v212 offset:2048
	ds_read_b128 v[150:153], v212 offset:4096
	ds_read_b128 v[154:157], v212 offset:6144
	ds_read_b128 v[174:177], v214 offset:32768
	ds_read_b128 v[182:185], v214 offset:34816
	ds_read_b128 v[186:189], v214 offset:36864
	ds_read_b128 v[190:193], v214 offset:38912
	v_mfma_f32_16x16x32_bf16 v[60:63], v[158:161], v[194:197], v[60:63]
	v_mfma_f32_16x16x32_bf16 v[56:59], v[158:161], v[198:201], v[56:59]
	s_mov_b32 m0, s45
	s_add_u32 s38, s36, s12
	s_addc_u32 s39, s37, s13
	global_load_lds_dwordx4 v178, s[38:39]
	v_mfma_f32_16x16x32_bf16 v[52:55], v[158:161], v[202:205], v[52:55]
	v_mfma_f32_16x16x32_bf16 v[48:51], v[158:161], v[206:209], v[48:51]
	s_add_u32 m0, s45, 0x2000
	s_add_u32 s38, s36, s14
	s_addc_u32 s39, s37, s15
	global_load_lds_dwordx4 v178, s[38:39]
	v_mfma_f32_16x16x32_bf16 v[44:47], v[162:165], v[194:197], v[44:47]
	v_mfma_f32_16x16x32_bf16 v[32:35], v[162:165], v[198:201], v[32:35]
	s_add_u32 m0, s45, 0x4000
	s_add_u32 s38, s36, s16
	s_addc_u32 s39, s37, s17
	global_load_lds_dwordx4 v178, s[38:39]
	v_mfma_f32_16x16x32_bf16 v[28:31], v[162:165], v[202:205], v[28:31]
	v_mfma_f32_16x16x32_bf16 v[24:27], v[162:165], v[206:209], v[24:27]
	s_add_u32 m0, s45, 0x6000
	s_add_u32 s38, s36, s18
	s_addc_u32 s39, s37, s19
	global_load_lds_dwordx4 v178, s[38:39]
	v_mfma_f32_16x16x32_bf16 v[20:23], v[166:169], v[194:197], v[20:23]
	v_mfma_f32_16x16x32_bf16 v[16:19], v[166:169], v[198:201], v[16:19]
	s_add_u32 m0, s45, 0x8000
	s_add_u32 s38, s36, s22
	s_addc_u32 s39, s37, s23
	global_load_lds_dwordx4 v179, s[38:39]
	v_mfma_f32_16x16x32_bf16 v[12:15], v[166:169], v[202:205], v[12:15]
	v_mfma_f32_16x16x32_bf16 v[8:11], v[166:169], v[206:209], v[8:11]
	s_add_u32 m0, s45, 0xa000
	s_add_u32 s38, s36, s24
	s_addc_u32 s39, s37, s25
	global_load_lds_dwordx4 v179, s[38:39]
	v_mfma_f32_16x16x32_bf16 v[4:7], v[170:173], v[194:197], v[4:7]
	v_mfma_f32_16x16x32_bf16 v[0:3], v[170:173], v[198:201], v[0:3]
	s_add_u32 m0, s45, 0xc000
	s_add_u32 s38, s36, s26
	s_addc_u32 s39, s37, s27
	global_load_lds_dwordx4 v179, s[38:39]
	v_mfma_f32_16x16x32_bf16 v[40:43], v[170:173], v[202:205], v[40:43]
	v_mfma_f32_16x16x32_bf16 v[36:39], v[170:173], v[206:209], v[36:39]
	s_add_u32 m0, s45, 0xe000
	s_add_u32 s38, s36, s28
	s_addc_u32 s39, s37, s29
	global_load_lds_dwordx4 v179, s[38:39]
	ds_read_b128 v[158:161], v212 offset:8192
	ds_read_b128 v[162:165], v212 offset:10240
	ds_read_b128 v[166:169], v212 offset:12288
	ds_read_b128 v[170:173], v212 offset:14336
	s_waitcnt lgkmcnt(4)
	v_mfma_f32_16x16x32_bf16 v[124:127], v[142:145], v[174:177], v[124:127]
	v_mfma_f32_16x16x32_bf16 v[120:123], v[142:145], v[182:185], v[120:123]
	v_mfma_f32_16x16x32_bf16 v[116:119], v[142:145], v[186:189], v[116:119]
	v_mfma_f32_16x16x32_bf16 v[112:115], v[142:145], v[190:193], v[112:115]
	v_mfma_f32_16x16x32_bf16 v[108:111], v[146:149], v[174:177], v[108:111]
	v_mfma_f32_16x16x32_bf16 v[104:107], v[146:149], v[182:185], v[104:107]
	v_mfma_f32_16x16x32_bf16 v[100:103], v[146:149], v[186:189], v[100:103]
	v_mfma_f32_16x16x32_bf16 v[96:99], v[146:149], v[190:193], v[96:99]
	v_mfma_f32_16x16x32_bf16 v[92:95], v[150:153], v[174:177], v[92:95]
	v_mfma_f32_16x16x32_bf16 v[88:91], v[150:153], v[182:185], v[88:91]
	v_mfma_f32_16x16x32_bf16 v[84:87], v[150:153], v[186:189], v[84:87]
	v_mfma_f32_16x16x32_bf16 v[80:83], v[150:153], v[190:193], v[80:83]
	v_mfma_f32_16x16x32_bf16 v[76:79], v[154:157], v[174:177], v[76:79]
	v_mfma_f32_16x16x32_bf16 v[72:75], v[154:157], v[182:185], v[72:75]
	v_mfma_f32_16x16x32_bf16 v[68:71], v[154:157], v[186:189], v[68:71]
	v_mfma_f32_16x16x32_bf16 v[64:67], v[154:157], v[190:193], v[64:67]
	ds_read_b128 v[142:145], v213
	ds_read_b128 v[146:149], v213 offset:2048
	ds_read_b128 v[150:153], v213 offset:4096
	ds_read_b128 v[154:157], v213 offset:6144
	ds_read_b128 v[194:197], v215 offset:32768
	ds_read_b128 v[198:201], v215 offset:34816
	ds_read_b128 v[202:205], v215 offset:36864
	ds_read_b128 v[206:209], v215 offset:38912
	s_waitcnt lgkmcnt(8)
	v_mfma_f32_16x16x32_bf16 v[60:63], v[158:161], v[174:177], v[60:63]
	v_mfma_f32_16x16x32_bf16 v[56:59], v[158:161], v[182:185], v[56:59]
	v_mfma_f32_16x16x32_bf16 v[52:55], v[158:161], v[186:189], v[52:55]
	v_mfma_f32_16x16x32_bf16 v[48:51], v[158:161], v[190:193], v[48:51]
	v_mfma_f32_16x16x32_bf16 v[44:47], v[162:165], v[174:177], v[44:47]
	v_mfma_f32_16x16x32_bf16 v[32:35], v[162:165], v[182:185], v[32:35]
	v_mfma_f32_16x16x32_bf16 v[28:31], v[162:165], v[186:189], v[28:31]
	v_mfma_f32_16x16x32_bf16 v[24:27], v[162:165], v[190:193], v[24:27]
	v_mfma_f32_16x16x32_bf16 v[20:23], v[166:169], v[174:177], v[20:23]
	v_mfma_f32_16x16x32_bf16 v[16:19], v[166:169], v[182:185], v[16:19]
	v_mfma_f32_16x16x32_bf16 v[12:15], v[166:169], v[186:189], v[12:15]
	v_mfma_f32_16x16x32_bf16 v[8:11], v[166:169], v[190:193], v[8:11]
	v_mfma_f32_16x16x32_bf16 v[4:7], v[170:173], v[174:177], v[4:7]
	v_mfma_f32_16x16x32_bf16 v[0:3], v[170:173], v[182:185], v[0:3]
	v_mfma_f32_16x16x32_bf16 v[40:43], v[170:173], v[186:189], v[40:43]
	v_mfma_f32_16x16x32_bf16 v[36:39], v[170:173], v[190:193], v[36:39]
	ds_read_b128 v[158:161], v213 offset:8192
	ds_read_b128 v[162:165], v213 offset:10240
	ds_read_b128 v[166:169], v213 offset:12288
	ds_read_b128 v[170:173], v213 offset:14336
	s_waitcnt lgkmcnt(4)
	v_mfma_f32_16x16x32_bf16 v[124:127], v[142:145], v[194:197], v[124:127]
	v_mfma_f32_16x16x32_bf16 v[120:123], v[142:145], v[198:201], v[120:123]
	v_mfma_f32_16x16x32_bf16 v[116:119], v[142:145], v[202:205], v[116:119]
	v_mfma_f32_16x16x32_bf16 v[112:115], v[142:145], v[206:209], v[112:115]
	v_mfma_f32_16x16x32_bf16 v[108:111], v[146:149], v[194:197], v[108:111]
	v_mfma_f32_16x16x32_bf16 v[104:107], v[146:149], v[198:201], v[104:107]
	v_mfma_f32_16x16x32_bf16 v[100:103], v[146:149], v[202:205], v[100:103]
	v_mfma_f32_16x16x32_bf16 v[96:99], v[146:149], v[206:209], v[96:99]
	v_mfma_f32_16x16x32_bf16 v[92:95], v[150:153], v[194:197], v[92:95]
	v_mfma_f32_16x16x32_bf16 v[88:91], v[150:153], v[198:201], v[88:91]
	v_mfma_f32_16x16x32_bf16 v[84:87], v[150:153], v[202:205], v[84:87]
	v_mfma_f32_16x16x32_bf16 v[80:83], v[150:153], v[206:209], v[80:83]
	v_mfma_f32_16x16x32_bf16 v[76:79], v[154:157], v[194:197], v[76:79]
	v_mfma_f32_16x16x32_bf16 v[72:75], v[154:157], v[198:201], v[72:75]
	v_mfma_f32_16x16x32_bf16 v[68:71], v[154:157], v[202:205], v[68:71]
	v_mfma_f32_16x16x32_bf16 v[64:67], v[154:157], v[206:209], v[64:67]
	s_add_u32 s36, s36, 0x80
	s_addc_u32 s37, s37, 0
	s_add_i32 s31, s31, 1
	s_branch .Lg11_top
.Lg11_last:
	s_waitcnt lgkmcnt(0)
	s_waitcnt vmcnt(0)
	s_barrier
	s_xor_b32 s45, s45, 0x10000
	ds_read_b128 v[142:145], v212
	ds_read_b128 v[146:149], v212 offset:2048
	ds_read_b128 v[150:153], v212 offset:4096
	ds_read_b128 v[154:157], v212 offset:6144
	ds_read_b128 v[174:177], v214 offset:32768
	ds_read_b128 v[182:185], v214 offset:34816
	ds_read_b128 v[186:189], v214 offset:36864
	ds_read_b128 v[190:193], v214 offset:38912
	v_mfma_f32_16x16x32_bf16 v[60:63], v[158:161], v[194:197], v[60:63]
	v_mfma_f32_16x16x32_bf16 v[56:59], v[158:161], v[198:201], v[56:59]
	v_mfma_f32_16x16x32_bf16 v[52:55], v[158:161], v[202:205], v[52:55]
	v_mfma_f32_16x16x32_bf16 v[48:51], v[158:161], v[206:209], v[48:51]
	v_mfma_f32_16x16x32_bf16 v[44:47], v[162:165], v[194:197], v[44:47]
	v_mfma_f32_16x16x32_bf16 v[32:35], v[162:165], v[198:201], v[32:35]
	v_mfma_f32_16x16x32_bf16 v[28:31], v[162:165], v[202:205], v[28:31]
	v_mfma_f32_16x16x32_bf16 v[24:27], v[162:165], v[206:209], v[24:27]
	v_mfma_f32_16x16x32_bf16 v[20:23], v[166:169], v[194:197], v[20:23]
	v_mfma_f32_16x16x32_bf16 v[16:19], v[166:169], v[198:201], v[16:19]
	v_mfma_f32_16x16x32_bf16 v[12:15], v[166:169], v[202:205], v[12:15]
	v_mfma_f32_16x16x32_bf16 v[8:11], v[166:169], v[206:209], v[8:11]
	v_mfma_f32_16x16x32_bf16 v[4:7], v[170:173], v[194:197], v[4:7]
	v_mfma_f32_16x16x32_bf16 v[0:3], v[170:173], v[198:201], v[0:3]
	v_mfma_f32_16x16x32_bf16 v[40:43], v[170:173], v[202:205], v[40:43]
	v_mfma_f32_16x16x32_bf16 v[36:39], v[170:173], v[206:209], v[36:39]
	ds_read_b128 v[158:161], v212 offset:8192
	ds_read_b128 v[162:165], v212 offset:10240
	ds_read_b128 v[166:169], v212 offset:12288
	ds_read_b128 v[170:173], v212 offset:14336
	s_waitcnt lgkmcnt(4)
	v_mfma_f32_16x16x32_bf16 v[124:127], v[142:145], v[174:177], v[124:127]
	v_mfma_f32_16x16x32_bf16 v[120:123], v[142:145], v[182:185], v[120:123]
	v_mfma_f32_16x16x32_bf16 v[116:119], v[142:145], v[186:189], v[116:119]
	v_mfma_f32_16x16x32_bf16 v[112:115], v[142:145], v[190:193], v[112:115]
	v_mfma_f32_16x16x32_bf16 v[108:111], v[146:149], v[174:177], v[108:111]
	v_mfma_f32_16x16x32_bf16 v[104:107], v[146:149], v[182:185], v[104:107]
	v_mfma_f32_16x16x32_bf16 v[100:103], v[146:149], v[186:189], v[100:103]
	v_mfma_f32_16x16x32_bf16 v[96:99], v[146:149], v[190:193], v[96:99]
	v_mfma_f32_16x16x32_bf16 v[92:95], v[150:153], v[174:177], v[92:95]
	v_mfma_f32_16x16x32_bf16 v[88:91], v[150:153], v[182:185], v[88:91]
	v_mfma_f32_16x16x32_bf16 v[84:87], v[150:153], v[186:189], v[84:87]
	v_mfma_f32_16x16x32_bf16 v[80:83], v[150:153], v[190:193], v[80:83]
	v_mfma_f32_16x16x32_bf16 v[76:79], v[154:157], v[174:177], v[76:79]
	v_mfma_f32_16x16x32_bf16 v[72:75], v[154:157], v[182:185], v[72:75]
	v_mfma_f32_16x16x32_bf16 v[68:71], v[154:157], v[186:189], v[68:71]
	v_mfma_f32_16x16x32_bf16 v[64:67], v[154:157], v[190:193], v[64:67]
	ds_read_b128 v[142:145], v213
	ds_read_b128 v[146:149], v213 offset:2048
	ds_read_b128 v[150:153], v213 offset:4096
	ds_read_b128 v[154:157], v213 offset:6144
	ds_read_b128 v[194:197], v215 offset:32768
	ds_read_b128 v[198:201], v215 offset:34816
	ds_read_b128 v[202:205], v215 offset:36864
	ds_read_b128 v[206:209], v215 offset:38912
	s_waitcnt lgkmcnt(8)
	v_mfma_f32_16x16x32_bf16 v[60:63], v[158:161], v[174:177], v[60:63]
	v_mfma_f32_16x16x32_bf16 v[56:59], v[158:161], v[182:185], v[56:59]
	v_mfma_f32_16x16x32_bf16 v[52:55], v[158:161], v[186:189], v[52:55]
	v_mfma_f32_16x16x32_bf16 v[48:51], v[158:161], v[190:193], v[48:51]
	v_mfma_f32_16x16x32_bf16 v[44:47], v[162:165], v[174:177], v[44:47]
	v_mfma_f32_16x16x32_bf16 v[32:35], v[162:165], v[182:185], v[32:35]
	v_mfma_f32_16x16x32_bf16 v[28:31], v[162:165], v[186:189], v[28:31]
	v_mfma_f32_16x16x32_bf16 v[24:27], v[162:165], v[190:193], v[24:27]
	v_mfma_f32_16x16x32_bf16 v[20:23], v[166:169], v[174:177], v[20:23]
	v_mfma_f32_16x16x32_bf16 v[16:19], v[166:169], v[182:185], v[16:19]
	v_mfma_f32_16x16x32_bf16 v[12:15], v[166:169], v[186:189], v[12:15]
	v_mfma_f32_16x16x32_bf16 v[8:11], v[166:169], v[190:193], v[8:11]
	v_mfma_f32_16x16x32_bf16 v[4:7], v[170:173], v[174:177], v[4:7]
	v_mfma_f32_16x16x32_bf16 v[0:3], v[170:173], v[182:185], v[0:3]
	v_mfma_f32_16x16x32_bf16 v[40:43], v[170:173], v[186:189], v[40:43]
	v_mfma_f32_16x16x32_bf16 v[36:39], v[170:173], v[190:193], v[36:39]
	ds_read_b128 v[158:161], v213 offset:8192
	ds_read_b128 v[162:165], v213 offset:10240
	ds_read_b128 v[166:169], v213 offset:12288
	ds_read_b128 v[170:173], v213 offset:14336
	s_waitcnt lgkmcnt(4)
	v_mfma_f32_16x16x32_bf16 v[124:127], v[142:145], v[194:197], v[124:127]
	v_mfma_f32_16x16x32_bf16 v[120:123], v[142:145], v[198:201], v[120:123]
	v_mfma_f32_16x16x32_bf16 v[116:119], v[142:145], v[202:205], v[116:119]
	v_mfma_f32_16x16x32_bf16 v[112:115], v[142:145], v[206:209], v[112:115]
	v_mfma_f32_16x16x32_bf16 v[108:111], v[146:149], v[194:197], v[108:111]
	v_mfma_f32_16x16x32_bf16 v[104:107], v[146:149], v[198:201], v[104:107]
	v_mfma_f32_16x16x32_bf16 v[100:103], v[146:149], v[202:205], v[100:103]
	v_mfma_f32_16x16x32_bf16 v[96:99], v[146:149], v[206:209], v[96:99]
	v_mfma_f32_16x16x32_bf16 v[92:95], v[150:153], v[194:197], v[92:95]
	v_mfma_f32_16x16x32_bf16 v[88:91], v[150:153], v[198:201], v[88:91]
	v_mfma_f32_16x16x32_bf16 v[84:87], v[150:153], v[202:205], v[84:87]
	v_mfma_f32_16x16x32_bf16 v[80:83], v[150:153], v[206:209], v[80:83]
	v_mfma_f32_16x16x32_bf16 v[76:79], v[154:157], v[194:197], v[76:79]
	v_mfma_f32_16x16x32_bf16 v[72:75], v[154:157], v[198:201], v[72:75]
	v_mfma_f32_16x16x32_bf16 v[68:71], v[154:157], v[202:205], v[68:71]
	v_mfma_f32_16x16x32_bf16 v[64:67], v[154:157], v[206:209], v[64:67]
	s_add_u32 s36, s36, 0x80
	s_addc_u32 s37, s37, 0
	s_add_i32 s31, s31, 1
	s_waitcnt lgkmcnt(0)
	s_waitcnt vmcnt(0)
	s_barrier
	v_mfma_f32_16x16x32_bf16 v[60:63], v[158:161], v[194:197], v[60:63]
	v_mfma_f32_16x16x32_bf16 v[56:59], v[158:161], v[198:201], v[56:59]
	v_mfma_f32_16x16x32_bf16 v[52:55], v[158:161], v[202:205], v[52:55]
	v_mfma_f32_16x16x32_bf16 v[48:51], v[158:161], v[206:209], v[48:51]
	v_mfma_f32_16x16x32_bf16 v[44:47], v[162:165], v[194:197], v[44:47]
	v_mfma_f32_16x16x32_bf16 v[32:35], v[162:165], v[198:201], v[32:35]
	v_mfma_f32_16x16x32_bf16 v[28:31], v[162:165], v[202:205], v[28:31]
	v_mfma_f32_16x16x32_bf16 v[24:27], v[162:165], v[206:209], v[24:27]
	v_mfma_f32_16x16x32_bf16 v[20:23], v[166:169], v[194:197], v[20:23]
	v_mfma_f32_16x16x32_bf16 v[16:19], v[166:169], v[198:201], v[16:19]
	v_mfma_f32_16x16x32_bf16 v[12:15], v[166:169], v[202:205], v[12:15]
	v_mfma_f32_16x16x32_bf16 v[8:11], v[166:169], v[206:209], v[8:11]
	v_mfma_f32_16x16x32_bf16 v[4:7], v[170:173], v[194:197], v[4:7]
	v_mfma_f32_16x16x32_bf16 v[0:3], v[170:173], v[198:201], v[0:3]
	v_mfma_f32_16x16x32_bf16 v[40:43], v[170:173], v[202:205], v[40:43]
	v_mfma_f32_16x16x32_bf16 v[36:39], v[170:173], v[206:209], v[36:39]
	s_nop 7
	s_nop 7
	s_sub_u32 s36, s36, s34
	s_subb_u32 s37, s37, s35
	s_mov_b32 s45, 0x100000
	s_mov_b32 s46, 0x100000
	s_mov_b64 s[38:39], 0
	s_mov_b64 vcc, exec
	s_branch .LBB0_1635
